# LDS-DMA (global_load_lds_dwordx4, source-side XOR swizzle) replaces register staging + ds_write in the three unrolled bf16 GEMM K-loops (PH2/PH6/PH8); scan/prep edits as before
# speedup vs baseline: 1.0384x; 1.0384x over previous
.LBB0_232:
	s_mul_hi_i32 s2, s8, 0x66666667
	s_lshr_b32 s3, s2, 31
	s_ashr_i32 s2, s2, 3
	s_add_i32 s34, s2, s3
	s_ashr_i32 s35, s34, 31
	v_readlane_b32 s36, v210, 50
	v_mov_b32_e32 v36, v133
	s_lshl_b64 s[2:3], s[34:35], 18
	v_readlane_b32 s38, v210, 52
	v_readlane_b32 s39, v210, 53
	v_ashrrev_i32_e32 v34, 3, v36
	s_add_u32 s2, s38, s2
	v_ashrrev_i32_e32 v35, 31, v34
	s_addc_u32 s3, s39, s3
	v_lshlrev_b64 v[2:3], 11, v[34:35]
	s_waitcnt vmcnt(0)
	v_lshlrev_b32_e32 v0, 4, v36
	v_lshl_add_u64 v[2:3], s[2:3], 0, v[2:3]
	v_and_b32_e32 v0, 0x70, v0
	s_mul_i32 s2, s34, 0xa00
	v_lshl_add_u64 v[66:67], v[2:3], 0, v[0:1]
	v_subrev_u32_e32 v2, s2, v34
	v_add_u32_e32 v2, s7, v2
	v_ashrrev_i32_e32 v3, 31, v2
	v_lshlrev_b64 v[2:3], 11, v[2:3]
	v_lshl_add_u64 v[2:3], s[0:1], 0, v[2:3]
	v_add_co_u32_e32 v70, vcc, s56, v66
	v_lshl_add_u64 v[68:69], v[2:3], 0, v[0:1]
	s_nop 0
	v_addc_co_u32_e32 v71, vcc, 0, v67, vcc
	v_add_co_u32_e32 v72, vcc, s56, v68
	v_addc_co_u32_e32 v73, vcc, 0, v69, vcc
	v_add_co_u32_e32 v74, vcc, s57, v66
	s_nop 0
	v_addc_co_u32_e32 v75, vcc, 0, v67, vcc
	v_add_co_u32_e32 v76, vcc, s57, v68
	s_nop 0
	v_addc_co_u32_e32 v77, vcc, 0, v69, vcc
	v_add_co_u32_e32 v78, vcc, s58, v66
	s_nop 0
	v_addc_co_u32_e32 v79, vcc, 0, v67, vcc
	v_add_co_u32_e32 v80, vcc, s58, v68
	v_lshlrev_b32_e32 v0, 7, v34
	s_nop 0
	v_addc_co_u32_e32 v81, vcc, 0, v69, vcc
	v_lshrrev_b32_e32 v216, 4, v133
	v_xor_b32_e32 v216, v216, v133
	v_and_b32_e32 v216, 7, v216
	v_lshlrev_b32_e32 v216, 4, v216
	v_mov_b32_e32 v217, 0x70
	v_lshrrev_b32_e32 v218, 6, v133
	v_lshlrev_b32_e32 v218, 10, v218
	s_nop 0
	v_readfirstlane_b32 s32, v218
	v_bfi_b32 v66, v217, v216, v66
	v_bfi_b32 v70, v217, v216, v70
	v_bfi_b32 v74, v217, v216, v74
	v_bfi_b32 v78, v217, v216, v78
	v_bfi_b32 v68, v217, v216, v68
	v_bfi_b32 v72, v217, v216, v72
	v_bfi_b32 v76, v217, v216, v76
	v_bfi_b32 v80, v217, v216, v80
	s_add_u32 m0, s32, 0x0
	s_nop 0
	global_load_lds_dwordx4 v[66:67], off
	s_add_u32 m0, s32, 0x1000
	s_nop 0
	global_load_lds_dwordx4 v[70:71], off
	s_add_u32 m0, s32, 0x2000
	s_nop 0
	global_load_lds_dwordx4 v[74:75], off
	s_add_u32 m0, s32, 0x3000
	s_nop 0
	global_load_lds_dwordx4 v[78:79], off
	s_add_u32 m0, s32, 0x8000
	s_nop 0
	global_load_lds_dwordx4 v[68:69], off
	s_add_u32 m0, s32, 0x9000
	s_nop 0
	global_load_lds_dwordx4 v[72:73], off
	s_add_u32 m0, s32, 0xa000
	s_nop 0
	global_load_lds_dwordx4 v[76:77], off
	s_add_u32 m0, s32, 0xb000
	s_nop 0
	global_load_lds_dwordx4 v[80:81], off
	v_lshl_add_u64 v[66:67], v[66:67], 0, 64
	v_lshl_add_u64 v[66:67], v[66:67], 0, 64
	v_lshl_add_u64 v[70:71], v[70:71], 0, 64
	v_lshl_add_u64 v[70:71], v[70:71], 0, 64
	v_lshl_add_u64 v[74:75], v[74:75], 0, 64
	v_lshl_add_u64 v[74:75], v[74:75], 0, 64
	v_lshl_add_u64 v[78:79], v[78:79], 0, 64
	v_lshl_add_u64 v[78:79], v[78:79], 0, 64
	v_lshl_add_u64 v[68:69], v[68:69], 0, 64
	v_lshl_add_u64 v[68:69], v[68:69], 0, 64
	v_lshl_add_u64 v[72:73], v[72:73], 0, 64
	v_lshl_add_u64 v[72:73], v[72:73], 0, 64
	v_lshl_add_u64 v[76:77], v[76:77], 0, 64
	v_lshl_add_u64 v[76:77], v[76:77], 0, 64
	v_lshl_add_u64 v[80:81], v[80:81], 0, 64
	v_lshl_add_u64 v[80:81], v[80:81], 0, 64
	v_lshrrev_b32_e32 v34, 1, v34
	v_xor_b32_e32 v34, v34, v36
	v_lshlrev_b32_e32 v34, 4, v34
	v_and_or_b32 v0, v34, s59, v0
	v_and_b32_e32 v84, 31, v36
	v_bfe_u32 v82, v36, 5, 1
	v_ashrrev_i32_e32 v83, 7, v36
	v_bfe_u32 v85, v36, 6, 1
	v_readlane_b32 s40, v210, 54
	v_readlane_b32 s41, v210, 55
	v_readlane_b32 s37, v210, 51
	v_readlane_b32 s42, v210, 56
	v_readlane_b32 s43, v210, 57
	v_readlane_b32 s44, v210, 58
	v_readlane_b32 s45, v210, 59
	v_readlane_b32 s46, v210, 60
	v_readlane_b32 s47, v210, 61
	v_readlane_b32 s48, v210, 62
	v_readlane_b32 s49, v210, 63
	v_readlane_b32 s50, v209, 0
	v_readlane_b32 s51, v209, 1
	s_waitcnt vmcnt(0)
	s_waitcnt lgkmcnt(0)
	s_barrier
	s_add_u32 m0, s32, 0x4000
	s_nop 0
	global_load_lds_dwordx4 v[66:67], off
	s_add_u32 m0, s32, 0x5000
	s_nop 0
	global_load_lds_dwordx4 v[70:71], off
	s_add_u32 m0, s32, 0x6000
	s_nop 0
	global_load_lds_dwordx4 v[74:75], off
	s_add_u32 m0, s32, 0x7000
	s_nop 0
	global_load_lds_dwordx4 v[78:79], off
	s_add_u32 m0, s32, 0xc000
	s_nop 0
	global_load_lds_dwordx4 v[68:69], off
	s_add_u32 m0, s32, 0xd000
	s_nop 0
	global_load_lds_dwordx4 v[72:73], off
	s_add_u32 m0, s32, 0xe000
	s_nop 0
	global_load_lds_dwordx4 v[76:77], off
	s_add_u32 m0, s32, 0xf000
	s_nop 0
	global_load_lds_dwordx4 v[80:81], off
	v_lshl_add_u64 v[66:67], v[66:67], 0, 64
	v_lshl_add_u64 v[66:67], v[66:67], 0, 64
	v_lshl_add_u64 v[70:71], v[70:71], 0, 64
	v_lshl_add_u64 v[70:71], v[70:71], 0, 64
	v_lshl_add_u64 v[74:75], v[74:75], 0, 64
	v_lshl_add_u64 v[74:75], v[74:75], 0, 64
	v_lshl_add_u64 v[78:79], v[78:79], 0, 64
	v_lshl_add_u64 v[78:79], v[78:79], 0, 64
	v_lshl_add_u64 v[68:69], v[68:69], 0, 64
	v_lshl_add_u64 v[68:69], v[68:69], 0, 64
	v_lshl_add_u64 v[72:73], v[72:73], 0, 64
	v_lshl_add_u64 v[72:73], v[72:73], 0, 64
	v_lshl_add_u64 v[76:77], v[76:77], 0, 64
	v_lshl_add_u64 v[76:77], v[76:77], 0, 64
	v_lshl_add_u64 v[80:81], v[80:81], 0, 64
	v_lshl_add_u64 v[80:81], v[80:81], 0, 64
	v_lshrrev_b32_e32 v4, 1, v36
	v_lshlrev_b32_e32 v2, 7, v84
	v_bitop3_b32 v4, v4, v82, 7 bitop3:0x6c
	v_lshl_or_b32 v3, v83, 13, v2
	v_bfe_u32 v5, v36, 1, 3
	v_lshlrev_b32_e32 v4, 4, v4
	v_lshl_or_b32 v2, v85, 13, v2
	v_or_b32_e32 v91, v3, v4
	v_or_b32_e32 v92, v2, v4
	v_bitop3_b32 v4, v82, v5, 2 bitop3:0x36
	v_lshlrev_b32_e32 v4, 4, v4
	v_or_b32_e32 v93, v3, v4
	v_or_b32_e32 v90, v2, v4
	v_bitop3_b32 v4, v82, v5, 4 bitop3:0x36
	v_lshlrev_b32_e32 v4, 4, v4
	v_or_b32_e32 v89, v3, v4
	v_or_b32_e32 v88, v2, v4
	v_bitop3_b32 v4, v82, v5, 6 bitop3:0x36
	v_lshlrev_b32_e32 v4, 4, v4
	v_or_b32_e32 v87, v3, v4
	v_or_b32_e32 v86, v2, v4
	ds_read_b128 v[2:5], v91
	ds_read_b128 v[6:9], v92 offset:32768
	ds_read_b128 v[10:13], v91 offset:4096
	ds_read_b128 v[14:17], v92 offset:36864
	ds_read_b128 v[162:165], v93
	ds_read_b128 v[166:169], v90 offset:32768
	ds_read_b128 v[182:185], v93 offset:4096
	ds_read_b128 v[186:189], v90 offset:36864
	s_waitcnt lgkmcnt(6)
	v_mfma_f32_32x32x16_bf16 v[50:65], v[2:5], v[6:9], 0
	s_waitcnt lgkmcnt(4)
	v_mfma_f32_32x32x16_bf16 v[34:49], v[2:5], v[14:17], 0
	v_mfma_f32_32x32x16_bf16 v[18:33], v[10:13], v[6:9], 0
	v_mfma_f32_32x32x16_bf16 v[2:17], v[10:13], v[14:17], 0
	ds_read_b128 v[190:193], v89
	ds_read_b128 v[194:197], v89 offset:4096
	ds_read_b128 v[198:201], v88 offset:32768
	ds_read_b128 v[202:205], v88 offset:36864
	s_waitcnt lgkmcnt(6)
	v_mfma_f32_32x32x16_bf16 v[50:65], v[162:165], v[166:169], v[50:65]
	s_waitcnt lgkmcnt(4)
	v_mfma_f32_32x32x16_bf16 v[34:49], v[162:165], v[186:189], v[34:49]
	v_mfma_f32_32x32x16_bf16 v[18:33], v[182:185], v[166:169], v[18:33]
	v_mfma_f32_32x32x16_bf16 v[2:17], v[182:185], v[186:189], v[2:17]
	ds_read_b128 v[162:165], v87
	ds_read_b128 v[166:169], v87 offset:4096
	ds_read_b128 v[182:185], v86 offset:32768
	ds_read_b128 v[186:189], v86 offset:36864
	s_waitcnt vmcnt(0)
	s_waitcnt lgkmcnt(0)
	s_barrier
	s_add_u32 m0, s32, 0x0
	s_nop 0
	global_load_lds_dwordx4 v[66:67], off
	s_add_u32 m0, s32, 0x1000
	s_nop 0
	global_load_lds_dwordx4 v[70:71], off
	s_add_u32 m0, s32, 0x2000
	s_nop 0
	global_load_lds_dwordx4 v[74:75], off
	s_add_u32 m0, s32, 0x3000
	s_nop 0
	global_load_lds_dwordx4 v[78:79], off
	s_add_u32 m0, s32, 0x8000
	s_nop 0
	global_load_lds_dwordx4 v[68:69], off
	s_add_u32 m0, s32, 0x9000
	s_nop 0
	global_load_lds_dwordx4 v[72:73], off
	s_add_u32 m0, s32, 0xa000
	s_nop 0
	global_load_lds_dwordx4 v[76:77], off
	s_add_u32 m0, s32, 0xb000
	s_nop 0
	global_load_lds_dwordx4 v[80:81], off
	v_lshl_add_u64 v[66:67], v[66:67], 0, 64
	v_lshl_add_u64 v[66:67], v[66:67], 0, 64
	v_lshl_add_u64 v[70:71], v[70:71], 0, 64
	v_lshl_add_u64 v[70:71], v[70:71], 0, 64
	v_lshl_add_u64 v[74:75], v[74:75], 0, 64
	v_lshl_add_u64 v[74:75], v[74:75], 0, 64
	v_lshl_add_u64 v[78:79], v[78:79], 0, 64
	v_lshl_add_u64 v[78:79], v[78:79], 0, 64
	v_lshl_add_u64 v[68:69], v[68:69], 0, 64
	v_lshl_add_u64 v[68:69], v[68:69], 0, 64
	v_lshl_add_u64 v[72:73], v[72:73], 0, 64
	v_lshl_add_u64 v[72:73], v[72:73], 0, 64
	v_lshl_add_u64 v[76:77], v[76:77], 0, 64
	v_lshl_add_u64 v[76:77], v[76:77], 0, 64
	v_lshl_add_u64 v[80:81], v[80:81], 0, 64
	v_lshl_add_u64 v[80:81], v[80:81], 0, 64
	v_mfma_f32_32x32x16_bf16 v[50:65], v[190:193], v[198:201], v[50:65]
	v_mfma_f32_32x32x16_bf16 v[34:49], v[190:193], v[202:205], v[34:49]
	v_mfma_f32_32x32x16_bf16 v[18:33], v[194:197], v[198:201], v[18:33]
	v_mfma_f32_32x32x16_bf16 v[2:17], v[194:197], v[202:205], v[2:17]
	v_mfma_f32_32x32x16_bf16 v[50:65], v[162:165], v[182:185], v[50:65]
	v_mfma_f32_32x32x16_bf16 v[34:49], v[162:165], v[186:189], v[34:49]
	v_mfma_f32_32x32x16_bf16 v[18:33], v[166:169], v[182:185], v[18:33]
	v_mfma_f32_32x32x16_bf16 v[2:17], v[166:169], v[186:189], v[2:17]
	ds_read_b128 v[162:165], v91 offset:16384
	ds_read_b128 v[166:169], v92 offset:49152
	ds_read_b128 v[182:185], v91 offset:20480
	ds_read_b128 v[186:189], v92 offset:53248
	ds_read_b128 v[190:193], v93 offset:16384
	ds_read_b128 v[194:197], v90 offset:49152
	ds_read_b128 v[198:201], v93 offset:20480
	ds_read_b128 v[202:205], v90 offset:53248
	s_waitcnt lgkmcnt(6)
	v_mfma_f32_32x32x16_bf16 v[50:65], v[162:165], v[166:169], v[50:65]
	s_waitcnt lgkmcnt(4)
	v_mfma_f32_32x32x16_bf16 v[34:49], v[162:165], v[186:189], v[34:49]
	v_mfma_f32_32x32x16_bf16 v[18:33], v[182:185], v[166:169], v[18:33]
	v_mfma_f32_32x32x16_bf16 v[2:17], v[182:185], v[186:189], v[2:17]
	ds_read_b128 v[162:165], v89 offset:16384
	ds_read_b128 v[166:169], v89 offset:20480
	ds_read_b128 v[182:185], v88 offset:49152
	ds_read_b128 v[186:189], v88 offset:53248
	s_waitcnt lgkmcnt(6)
	v_mfma_f32_32x32x16_bf16 v[50:65], v[190:193], v[194:197], v[50:65]
	s_waitcnt lgkmcnt(4)
	v_mfma_f32_32x32x16_bf16 v[34:49], v[190:193], v[202:205], v[34:49]
	v_mfma_f32_32x32x16_bf16 v[18:33], v[198:201], v[194:197], v[18:33]
	v_mfma_f32_32x32x16_bf16 v[2:17], v[198:201], v[202:205], v[2:17]
	ds_read_b128 v[190:193], v87 offset:16384
	ds_read_b128 v[194:197], v87 offset:20480
	ds_read_b128 v[198:201], v86 offset:49152
	ds_read_b128 v[202:205], v86 offset:53248
	s_waitcnt vmcnt(0)
	s_waitcnt lgkmcnt(0)
	s_barrier
	s_add_u32 m0, s32, 0x4000
	s_nop 0
	global_load_lds_dwordx4 v[66:67], off
	s_add_u32 m0, s32, 0x5000
	s_nop 0
	global_load_lds_dwordx4 v[70:71], off
	s_add_u32 m0, s32, 0x6000
	s_nop 0
	global_load_lds_dwordx4 v[74:75], off
	s_add_u32 m0, s32, 0x7000
	s_nop 0
	global_load_lds_dwordx4 v[78:79], off
	s_add_u32 m0, s32, 0xc000
	s_nop 0
	global_load_lds_dwordx4 v[68:69], off
	s_add_u32 m0, s32, 0xd000
	s_nop 0
	global_load_lds_dwordx4 v[72:73], off
	s_add_u32 m0, s32, 0xe000
	s_nop 0
	global_load_lds_dwordx4 v[76:77], off
	s_add_u32 m0, s32, 0xf000
	s_nop 0
	global_load_lds_dwordx4 v[80:81], off
	v_lshl_add_u64 v[66:67], v[66:67], 0, 64
	v_lshl_add_u64 v[66:67], v[66:67], 0, 64
	v_lshl_add_u64 v[70:71], v[70:71], 0, 64
	v_lshl_add_u64 v[70:71], v[70:71], 0, 64
	v_lshl_add_u64 v[74:75], v[74:75], 0, 64
	v_lshl_add_u64 v[74:75], v[74:75], 0, 64
	v_lshl_add_u64 v[78:79], v[78:79], 0, 64
	v_lshl_add_u64 v[78:79], v[78:79], 0, 64
	v_lshl_add_u64 v[68:69], v[68:69], 0, 64
	v_lshl_add_u64 v[68:69], v[68:69], 0, 64
	v_lshl_add_u64 v[72:73], v[72:73], 0, 64
	v_lshl_add_u64 v[72:73], v[72:73], 0, 64
	v_lshl_add_u64 v[76:77], v[76:77], 0, 64
	v_lshl_add_u64 v[76:77], v[76:77], 0, 64
	v_lshl_add_u64 v[80:81], v[80:81], 0, 64
	v_lshl_add_u64 v[80:81], v[80:81], 0, 64
	v_mfma_f32_32x32x16_bf16 v[50:65], v[162:165], v[182:185], v[50:65]
	v_mfma_f32_32x32x16_bf16 v[34:49], v[162:165], v[186:189], v[34:49]
	v_mfma_f32_32x32x16_bf16 v[18:33], v[166:169], v[182:185], v[18:33]
	v_mfma_f32_32x32x16_bf16 v[2:17], v[166:169], v[186:189], v[2:17]
	v_mfma_f32_32x32x16_bf16 v[50:65], v[190:193], v[198:201], v[50:65]
	v_mfma_f32_32x32x16_bf16 v[34:49], v[190:193], v[202:205], v[34:49]
	v_mfma_f32_32x32x16_bf16 v[18:33], v[194:197], v[198:201], v[18:33]
	v_mfma_f32_32x32x16_bf16 v[2:17], v[194:197], v[202:205], v[2:17]
	ds_read_b128 v[162:165], v91
	ds_read_b128 v[166:169], v92 offset:32768
	ds_read_b128 v[182:185], v91 offset:4096
	ds_read_b128 v[186:189], v92 offset:36864
	ds_read_b128 v[190:193], v93
	ds_read_b128 v[194:197], v90 offset:32768
	ds_read_b128 v[198:201], v93 offset:4096
	ds_read_b128 v[202:205], v90 offset:36864
	s_waitcnt lgkmcnt(6)
	v_mfma_f32_32x32x16_bf16 v[50:65], v[162:165], v[166:169], v[50:65]
	s_waitcnt lgkmcnt(4)
	v_mfma_f32_32x32x16_bf16 v[34:49], v[162:165], v[186:189], v[34:49]
	v_mfma_f32_32x32x16_bf16 v[18:33], v[182:185], v[166:169], v[18:33]
	v_mfma_f32_32x32x16_bf16 v[2:17], v[182:185], v[186:189], v[2:17]
	ds_read_b128 v[162:165], v89
	ds_read_b128 v[166:169], v89 offset:4096
	ds_read_b128 v[182:185], v88 offset:32768
	ds_read_b128 v[186:189], v88 offset:36864
	s_waitcnt lgkmcnt(6)
	v_mfma_f32_32x32x16_bf16 v[50:65], v[190:193], v[194:197], v[50:65]
	s_waitcnt lgkmcnt(4)
	v_mfma_f32_32x32x16_bf16 v[34:49], v[190:193], v[202:205], v[34:49]
	v_mfma_f32_32x32x16_bf16 v[18:33], v[198:201], v[194:197], v[18:33]
	v_mfma_f32_32x32x16_bf16 v[2:17], v[198:201], v[202:205], v[2:17]
	ds_read_b128 v[190:193], v87
	ds_read_b128 v[194:197], v87 offset:4096
	ds_read_b128 v[198:201], v86 offset:32768
	ds_read_b128 v[202:205], v86 offset:36864
	s_waitcnt vmcnt(0)
	s_waitcnt lgkmcnt(0)
	s_barrier
	s_add_u32 m0, s32, 0x0
	s_nop 0
	global_load_lds_dwordx4 v[66:67], off
	s_add_u32 m0, s32, 0x1000
	s_nop 0
	global_load_lds_dwordx4 v[70:71], off
	s_add_u32 m0, s32, 0x2000
	s_nop 0
	global_load_lds_dwordx4 v[74:75], off
	s_add_u32 m0, s32, 0x3000
	s_nop 0
	global_load_lds_dwordx4 v[78:79], off
	s_add_u32 m0, s32, 0x8000
	s_nop 0
	global_load_lds_dwordx4 v[68:69], off
	s_add_u32 m0, s32, 0x9000
	s_nop 0
	global_load_lds_dwordx4 v[72:73], off
	s_add_u32 m0, s32, 0xa000
	s_nop 0
	global_load_lds_dwordx4 v[76:77], off
	s_add_u32 m0, s32, 0xb000
	s_nop 0
	global_load_lds_dwordx4 v[80:81], off
	v_lshl_add_u64 v[66:67], v[66:67], 0, 64
	v_lshl_add_u64 v[66:67], v[66:67], 0, 64
	v_lshl_add_u64 v[70:71], v[70:71], 0, 64
	v_lshl_add_u64 v[70:71], v[70:71], 0, 64
	v_lshl_add_u64 v[74:75], v[74:75], 0, 64
	v_lshl_add_u64 v[74:75], v[74:75], 0, 64
	v_lshl_add_u64 v[78:79], v[78:79], 0, 64
	v_lshl_add_u64 v[78:79], v[78:79], 0, 64
	v_lshl_add_u64 v[68:69], v[68:69], 0, 64
	v_lshl_add_u64 v[68:69], v[68:69], 0, 64
	v_lshl_add_u64 v[72:73], v[72:73], 0, 64
	v_lshl_add_u64 v[72:73], v[72:73], 0, 64
	v_lshl_add_u64 v[76:77], v[76:77], 0, 64
	v_lshl_add_u64 v[76:77], v[76:77], 0, 64
	v_lshl_add_u64 v[80:81], v[80:81], 0, 64
	v_lshl_add_u64 v[80:81], v[80:81], 0, 64
	v_mfma_f32_32x32x16_bf16 v[50:65], v[162:165], v[182:185], v[50:65]
	v_mfma_f32_32x32x16_bf16 v[34:49], v[162:165], v[186:189], v[34:49]
	v_mfma_f32_32x32x16_bf16 v[18:33], v[166:169], v[182:185], v[18:33]
	v_mfma_f32_32x32x16_bf16 v[2:17], v[166:169], v[186:189], v[2:17]
	v_mfma_f32_32x32x16_bf16 v[50:65], v[190:193], v[198:201], v[50:65]
	v_mfma_f32_32x32x16_bf16 v[34:49], v[190:193], v[202:205], v[34:49]
	v_mfma_f32_32x32x16_bf16 v[18:33], v[194:197], v[198:201], v[18:33]
	v_mfma_f32_32x32x16_bf16 v[2:17], v[194:197], v[202:205], v[2:17]
	ds_read_b128 v[162:165], v91 offset:16384
	ds_read_b128 v[166:169], v92 offset:49152
	ds_read_b128 v[182:185], v91 offset:20480
	ds_read_b128 v[186:189], v92 offset:53248
	ds_read_b128 v[190:193], v93 offset:16384
	ds_read_b128 v[194:197], v90 offset:49152
	ds_read_b128 v[198:201], v93 offset:20480
	ds_read_b128 v[202:205], v90 offset:53248
	s_waitcnt lgkmcnt(6)
	v_mfma_f32_32x32x16_bf16 v[50:65], v[162:165], v[166:169], v[50:65]
	s_waitcnt lgkmcnt(4)
	v_mfma_f32_32x32x16_bf16 v[34:49], v[162:165], v[186:189], v[34:49]
	v_mfma_f32_32x32x16_bf16 v[18:33], v[182:185], v[166:169], v[18:33]
	v_mfma_f32_32x32x16_bf16 v[2:17], v[182:185], v[186:189], v[2:17]
	ds_read_b128 v[162:165], v89 offset:16384
	ds_read_b128 v[166:169], v89 offset:20480
	ds_read_b128 v[182:185], v88 offset:49152
	ds_read_b128 v[186:189], v88 offset:53248
	s_waitcnt lgkmcnt(6)
	v_mfma_f32_32x32x16_bf16 v[50:65], v[190:193], v[194:197], v[50:65]
	s_waitcnt lgkmcnt(4)
	v_mfma_f32_32x32x16_bf16 v[34:49], v[190:193], v[202:205], v[34:49]
	v_mfma_f32_32x32x16_bf16 v[18:33], v[198:201], v[194:197], v[18:33]
	v_mfma_f32_32x32x16_bf16 v[2:17], v[198:201], v[202:205], v[2:17]
	ds_read_b128 v[190:193], v87 offset:16384
	ds_read_b128 v[194:197], v87 offset:20480
	ds_read_b128 v[198:201], v86 offset:49152
	ds_read_b128 v[202:205], v86 offset:53248
	s_waitcnt vmcnt(0)
	s_waitcnt lgkmcnt(0)
	s_barrier
	s_add_u32 m0, s32, 0x4000
	s_nop 0
	global_load_lds_dwordx4 v[66:67], off
	s_add_u32 m0, s32, 0x5000
	s_nop 0
	global_load_lds_dwordx4 v[70:71], off
	s_add_u32 m0, s32, 0x6000
	s_nop 0
	global_load_lds_dwordx4 v[74:75], off
	s_add_u32 m0, s32, 0x7000
	s_nop 0
	global_load_lds_dwordx4 v[78:79], off
	s_add_u32 m0, s32, 0xc000
	s_nop 0
	global_load_lds_dwordx4 v[68:69], off
	s_add_u32 m0, s32, 0xd000
	s_nop 0
	global_load_lds_dwordx4 v[72:73], off
	s_add_u32 m0, s32, 0xe000
	s_nop 0
	global_load_lds_dwordx4 v[76:77], off
	s_add_u32 m0, s32, 0xf000
	s_nop 0
	global_load_lds_dwordx4 v[80:81], off
	v_lshl_add_u64 v[66:67], v[66:67], 0, 64
	v_lshl_add_u64 v[66:67], v[66:67], 0, 64
	v_lshl_add_u64 v[70:71], v[70:71], 0, 64
	v_lshl_add_u64 v[70:71], v[70:71], 0, 64
	v_lshl_add_u64 v[74:75], v[74:75], 0, 64
	v_lshl_add_u64 v[74:75], v[74:75], 0, 64
	v_lshl_add_u64 v[78:79], v[78:79], 0, 64
	v_lshl_add_u64 v[78:79], v[78:79], 0, 64
	v_lshl_add_u64 v[68:69], v[68:69], 0, 64
	v_lshl_add_u64 v[68:69], v[68:69], 0, 64
	v_lshl_add_u64 v[72:73], v[72:73], 0, 64
	v_lshl_add_u64 v[72:73], v[72:73], 0, 64
	v_lshl_add_u64 v[76:77], v[76:77], 0, 64
	v_lshl_add_u64 v[76:77], v[76:77], 0, 64
	v_lshl_add_u64 v[80:81], v[80:81], 0, 64
	v_lshl_add_u64 v[80:81], v[80:81], 0, 64
	v_mfma_f32_32x32x16_bf16 v[50:65], v[162:165], v[182:185], v[50:65]
	v_mfma_f32_32x32x16_bf16 v[34:49], v[162:165], v[186:189], v[34:49]
	v_mfma_f32_32x32x16_bf16 v[18:33], v[166:169], v[182:185], v[18:33]
	v_mfma_f32_32x32x16_bf16 v[2:17], v[166:169], v[186:189], v[2:17]
	v_mfma_f32_32x32x16_bf16 v[50:65], v[190:193], v[198:201], v[50:65]
	v_mfma_f32_32x32x16_bf16 v[34:49], v[190:193], v[202:205], v[34:49]
	v_mfma_f32_32x32x16_bf16 v[18:33], v[194:197], v[198:201], v[18:33]
	v_mfma_f32_32x32x16_bf16 v[2:17], v[194:197], v[202:205], v[2:17]
	ds_read_b128 v[162:165], v91
	ds_read_b128 v[166:169], v92 offset:32768
	ds_read_b128 v[182:185], v91 offset:4096
	ds_read_b128 v[186:189], v92 offset:36864
	ds_read_b128 v[190:193], v93
	ds_read_b128 v[194:197], v90 offset:32768
	ds_read_b128 v[198:201], v93 offset:4096
	ds_read_b128 v[202:205], v90 offset:36864
	s_waitcnt lgkmcnt(6)
	v_mfma_f32_32x32x16_bf16 v[50:65], v[162:165], v[166:169], v[50:65]
	s_waitcnt lgkmcnt(4)
	v_mfma_f32_32x32x16_bf16 v[34:49], v[162:165], v[186:189], v[34:49]
	v_mfma_f32_32x32x16_bf16 v[18:33], v[182:185], v[166:169], v[18:33]
	v_mfma_f32_32x32x16_bf16 v[2:17], v[182:185], v[186:189], v[2:17]
	ds_read_b128 v[162:165], v89
	ds_read_b128 v[166:169], v89 offset:4096
	ds_read_b128 v[182:185], v88 offset:32768
	ds_read_b128 v[186:189], v88 offset:36864
	s_waitcnt lgkmcnt(6)
	v_mfma_f32_32x32x16_bf16 v[50:65], v[190:193], v[194:197], v[50:65]
	s_waitcnt lgkmcnt(4)
	v_mfma_f32_32x32x16_bf16 v[34:49], v[190:193], v[202:205], v[34:49]
	v_mfma_f32_32x32x16_bf16 v[18:33], v[198:201], v[194:197], v[18:33]
	v_mfma_f32_32x32x16_bf16 v[2:17], v[198:201], v[202:205], v[2:17]
	ds_read_b128 v[190:193], v87
	ds_read_b128 v[194:197], v87 offset:4096
	ds_read_b128 v[198:201], v86 offset:32768
	ds_read_b128 v[202:205], v86 offset:36864
	s_waitcnt vmcnt(0)
	s_waitcnt lgkmcnt(0)
	s_barrier
	s_add_u32 m0, s32, 0x0
	s_nop 0
	global_load_lds_dwordx4 v[66:67], off
	s_add_u32 m0, s32, 0x1000
	s_nop 0
	global_load_lds_dwordx4 v[70:71], off
	s_add_u32 m0, s32, 0x2000
	s_nop 0
	global_load_lds_dwordx4 v[74:75], off
	s_add_u32 m0, s32, 0x3000
	s_nop 0
	global_load_lds_dwordx4 v[78:79], off
	s_add_u32 m0, s32, 0x8000
	s_nop 0
	global_load_lds_dwordx4 v[68:69], off
	s_add_u32 m0, s32, 0x9000
	s_nop 0
	global_load_lds_dwordx4 v[72:73], off
	s_add_u32 m0, s32, 0xa000
	s_nop 0
	global_load_lds_dwordx4 v[76:77], off
	s_add_u32 m0, s32, 0xb000
	s_nop 0
	global_load_lds_dwordx4 v[80:81], off
	v_lshl_add_u64 v[66:67], v[66:67], 0, 64
	v_lshl_add_u64 v[66:67], v[66:67], 0, 64
	v_lshl_add_u64 v[70:71], v[70:71], 0, 64
	v_lshl_add_u64 v[70:71], v[70:71], 0, 64
	v_lshl_add_u64 v[74:75], v[74:75], 0, 64
	v_lshl_add_u64 v[74:75], v[74:75], 0, 64
	v_lshl_add_u64 v[78:79], v[78:79], 0, 64
	v_lshl_add_u64 v[78:79], v[78:79], 0, 64
	v_lshl_add_u64 v[68:69], v[68:69], 0, 64
	v_lshl_add_u64 v[68:69], v[68:69], 0, 64
	v_lshl_add_u64 v[72:73], v[72:73], 0, 64
	v_lshl_add_u64 v[72:73], v[72:73], 0, 64
	v_lshl_add_u64 v[76:77], v[76:77], 0, 64
	v_lshl_add_u64 v[76:77], v[76:77], 0, 64
	v_lshl_add_u64 v[80:81], v[80:81], 0, 64
	v_lshl_add_u64 v[80:81], v[80:81], 0, 64
	v_mfma_f32_32x32x16_bf16 v[50:65], v[162:165], v[182:185], v[50:65]
	v_mfma_f32_32x32x16_bf16 v[34:49], v[162:165], v[186:189], v[34:49]
	v_mfma_f32_32x32x16_bf16 v[18:33], v[166:169], v[182:185], v[18:33]
	v_mfma_f32_32x32x16_bf16 v[2:17], v[166:169], v[186:189], v[2:17]
	v_mfma_f32_32x32x16_bf16 v[50:65], v[190:193], v[198:201], v[50:65]
	v_mfma_f32_32x32x16_bf16 v[34:49], v[190:193], v[202:205], v[34:49]
	v_mfma_f32_32x32x16_bf16 v[18:33], v[194:197], v[198:201], v[18:33]
	v_mfma_f32_32x32x16_bf16 v[2:17], v[194:197], v[202:205], v[2:17]
	ds_read_b128 v[162:165], v91 offset:16384
	ds_read_b128 v[166:169], v92 offset:49152
	ds_read_b128 v[182:185], v91 offset:20480
	ds_read_b128 v[186:189], v92 offset:53248
	ds_read_b128 v[190:193], v93 offset:16384
	ds_read_b128 v[194:197], v90 offset:49152
	ds_read_b128 v[198:201], v93 offset:20480
	ds_read_b128 v[202:205], v90 offset:53248
	s_waitcnt lgkmcnt(6)
	v_mfma_f32_32x32x16_bf16 v[50:65], v[162:165], v[166:169], v[50:65]
	s_waitcnt lgkmcnt(4)
	v_mfma_f32_32x32x16_bf16 v[34:49], v[162:165], v[186:189], v[34:49]
	v_mfma_f32_32x32x16_bf16 v[18:33], v[182:185], v[166:169], v[18:33]
	v_mfma_f32_32x32x16_bf16 v[2:17], v[182:185], v[186:189], v[2:17]
	ds_read_b128 v[162:165], v89 offset:16384
	ds_read_b128 v[166:169], v89 offset:20480
	ds_read_b128 v[182:185], v88 offset:49152
	ds_read_b128 v[186:189], v88 offset:53248
	s_waitcnt lgkmcnt(6)
	v_mfma_f32_32x32x16_bf16 v[50:65], v[190:193], v[194:197], v[50:65]
	s_waitcnt lgkmcnt(4)
	v_mfma_f32_32x32x16_bf16 v[34:49], v[190:193], v[202:205], v[34:49]
	v_mfma_f32_32x32x16_bf16 v[18:33], v[198:201], v[194:197], v[18:33]
	v_mfma_f32_32x32x16_bf16 v[2:17], v[198:201], v[202:205], v[2:17]
	ds_read_b128 v[190:193], v87 offset:16384
	ds_read_b128 v[194:197], v87 offset:20480
	ds_read_b128 v[198:201], v86 offset:49152
	ds_read_b128 v[202:205], v86 offset:53248
	s_waitcnt vmcnt(0)
	s_waitcnt lgkmcnt(0)
	s_barrier
	s_add_u32 m0, s32, 0x4000
	s_nop 0
	global_load_lds_dwordx4 v[66:67], off
	s_add_u32 m0, s32, 0x5000
	s_nop 0
	global_load_lds_dwordx4 v[70:71], off
	s_add_u32 m0, s32, 0x6000
	s_nop 0
	global_load_lds_dwordx4 v[74:75], off
	s_add_u32 m0, s32, 0x7000
	s_nop 0
	global_load_lds_dwordx4 v[78:79], off
	s_add_u32 m0, s32, 0xc000
	s_nop 0
	global_load_lds_dwordx4 v[68:69], off
	s_add_u32 m0, s32, 0xd000
	s_nop 0
	global_load_lds_dwordx4 v[72:73], off
	s_add_u32 m0, s32, 0xe000
	s_nop 0
	global_load_lds_dwordx4 v[76:77], off
	s_add_u32 m0, s32, 0xf000
	s_nop 0
	global_load_lds_dwordx4 v[80:81], off
	v_lshl_add_u64 v[66:67], v[66:67], 0, 64
	v_lshl_add_u64 v[66:67], v[66:67], 0, 64
	v_lshl_add_u64 v[70:71], v[70:71], 0, 64
	v_lshl_add_u64 v[70:71], v[70:71], 0, 64
	v_lshl_add_u64 v[74:75], v[74:75], 0, 64
	v_lshl_add_u64 v[74:75], v[74:75], 0, 64
	v_lshl_add_u64 v[78:79], v[78:79], 0, 64
	v_lshl_add_u64 v[78:79], v[78:79], 0, 64
	v_lshl_add_u64 v[68:69], v[68:69], 0, 64
	v_lshl_add_u64 v[68:69], v[68:69], 0, 64
	v_lshl_add_u64 v[72:73], v[72:73], 0, 64
	v_lshl_add_u64 v[72:73], v[72:73], 0, 64
	v_lshl_add_u64 v[76:77], v[76:77], 0, 64
	v_lshl_add_u64 v[76:77], v[76:77], 0, 64
	v_lshl_add_u64 v[80:81], v[80:81], 0, 64
	v_lshl_add_u64 v[80:81], v[80:81], 0, 64
	v_mfma_f32_32x32x16_bf16 v[50:65], v[162:165], v[182:185], v[50:65]
	v_mfma_f32_32x32x16_bf16 v[34:49], v[162:165], v[186:189], v[34:49]
	v_mfma_f32_32x32x16_bf16 v[18:33], v[166:169], v[182:185], v[18:33]
	v_mfma_f32_32x32x16_bf16 v[2:17], v[166:169], v[186:189], v[2:17]
	v_mfma_f32_32x32x16_bf16 v[50:65], v[190:193], v[198:201], v[50:65]
	v_mfma_f32_32x32x16_bf16 v[34:49], v[190:193], v[202:205], v[34:49]
	v_mfma_f32_32x32x16_bf16 v[18:33], v[194:197], v[198:201], v[18:33]
	v_mfma_f32_32x32x16_bf16 v[2:17], v[194:197], v[202:205], v[2:17]
	ds_read_b128 v[162:165], v91
	ds_read_b128 v[166:169], v92 offset:32768
	ds_read_b128 v[182:185], v91 offset:4096
	ds_read_b128 v[186:189], v92 offset:36864
	ds_read_b128 v[190:193], v93
	ds_read_b128 v[194:197], v90 offset:32768
	ds_read_b128 v[198:201], v93 offset:4096
	ds_read_b128 v[202:205], v90 offset:36864
	s_waitcnt lgkmcnt(6)
	v_mfma_f32_32x32x16_bf16 v[50:65], v[162:165], v[166:169], v[50:65]
	s_waitcnt lgkmcnt(4)
	v_mfma_f32_32x32x16_bf16 v[34:49], v[162:165], v[186:189], v[34:49]
	v_mfma_f32_32x32x16_bf16 v[18:33], v[182:185], v[166:169], v[18:33]
	v_mfma_f32_32x32x16_bf16 v[2:17], v[182:185], v[186:189], v[2:17]
	ds_read_b128 v[162:165], v89
	ds_read_b128 v[166:169], v89 offset:4096
	ds_read_b128 v[182:185], v88 offset:32768
	ds_read_b128 v[186:189], v88 offset:36864
	s_waitcnt lgkmcnt(6)
	v_mfma_f32_32x32x16_bf16 v[50:65], v[190:193], v[194:197], v[50:65]
	s_waitcnt lgkmcnt(4)
	v_mfma_f32_32x32x16_bf16 v[34:49], v[190:193], v[202:205], v[34:49]
	v_mfma_f32_32x32x16_bf16 v[18:33], v[198:201], v[194:197], v[18:33]
	v_mfma_f32_32x32x16_bf16 v[2:17], v[198:201], v[202:205], v[2:17]
	ds_read_b128 v[190:193], v87
	ds_read_b128 v[194:197], v87 offset:4096
	ds_read_b128 v[198:201], v86 offset:32768
	ds_read_b128 v[202:205], v86 offset:36864
	s_waitcnt vmcnt(0)
	s_waitcnt lgkmcnt(0)
	s_barrier
	s_add_u32 m0, s32, 0x0
	s_nop 0
	global_load_lds_dwordx4 v[66:67], off
	s_add_u32 m0, s32, 0x1000
	s_nop 0
	global_load_lds_dwordx4 v[70:71], off
	s_add_u32 m0, s32, 0x2000
	s_nop 0
	global_load_lds_dwordx4 v[74:75], off
	s_add_u32 m0, s32, 0x3000
	s_nop 0
	global_load_lds_dwordx4 v[78:79], off
	s_add_u32 m0, s32, 0x8000
	s_nop 0
	global_load_lds_dwordx4 v[68:69], off
	s_add_u32 m0, s32, 0x9000
	s_nop 0
	global_load_lds_dwordx4 v[72:73], off
	s_add_u32 m0, s32, 0xa000
	s_nop 0
	global_load_lds_dwordx4 v[76:77], off
	s_add_u32 m0, s32, 0xb000
	s_nop 0
	global_load_lds_dwordx4 v[80:81], off
	v_lshl_add_u64 v[66:67], v[66:67], 0, 64
	v_lshl_add_u64 v[66:67], v[66:67], 0, 64
	v_lshl_add_u64 v[70:71], v[70:71], 0, 64
	v_lshl_add_u64 v[70:71], v[70:71], 0, 64
	v_lshl_add_u64 v[74:75], v[74:75], 0, 64
	v_lshl_add_u64 v[74:75], v[74:75], 0, 64
	v_lshl_add_u64 v[78:79], v[78:79], 0, 64
	v_lshl_add_u64 v[78:79], v[78:79], 0, 64
	v_lshl_add_u64 v[68:69], v[68:69], 0, 64
	v_lshl_add_u64 v[68:69], v[68:69], 0, 64
	v_lshl_add_u64 v[72:73], v[72:73], 0, 64
	v_lshl_add_u64 v[72:73], v[72:73], 0, 64
	v_lshl_add_u64 v[76:77], v[76:77], 0, 64
	v_lshl_add_u64 v[76:77], v[76:77], 0, 64
	v_lshl_add_u64 v[80:81], v[80:81], 0, 64
	v_lshl_add_u64 v[80:81], v[80:81], 0, 64
	v_mfma_f32_32x32x16_bf16 v[50:65], v[162:165], v[182:185], v[50:65]
	v_mfma_f32_32x32x16_bf16 v[34:49], v[162:165], v[186:189], v[34:49]
	v_mfma_f32_32x32x16_bf16 v[18:33], v[166:169], v[182:185], v[18:33]
	v_mfma_f32_32x32x16_bf16 v[2:17], v[166:169], v[186:189], v[2:17]
	v_mfma_f32_32x32x16_bf16 v[50:65], v[190:193], v[198:201], v[50:65]
	v_mfma_f32_32x32x16_bf16 v[34:49], v[190:193], v[202:205], v[34:49]
	v_mfma_f32_32x32x16_bf16 v[18:33], v[194:197], v[198:201], v[18:33]
	v_mfma_f32_32x32x16_bf16 v[2:17], v[194:197], v[202:205], v[2:17]
	ds_read_b128 v[162:165], v91 offset:16384
	ds_read_b128 v[166:169], v92 offset:49152
	ds_read_b128 v[182:185], v91 offset:20480
	ds_read_b128 v[186:189], v92 offset:53248
	ds_read_b128 v[190:193], v93 offset:16384
	ds_read_b128 v[194:197], v90 offset:49152
	ds_read_b128 v[198:201], v93 offset:20480
	ds_read_b128 v[202:205], v90 offset:53248
	s_waitcnt lgkmcnt(6)
	v_mfma_f32_32x32x16_bf16 v[50:65], v[162:165], v[166:169], v[50:65]
	s_waitcnt lgkmcnt(4)
	v_mfma_f32_32x32x16_bf16 v[34:49], v[162:165], v[186:189], v[34:49]
	v_mfma_f32_32x32x16_bf16 v[18:33], v[182:185], v[166:169], v[18:33]
	v_mfma_f32_32x32x16_bf16 v[2:17], v[182:185], v[186:189], v[2:17]
	ds_read_b128 v[162:165], v89 offset:16384
	ds_read_b128 v[166:169], v89 offset:20480
	ds_read_b128 v[182:185], v88 offset:49152
	ds_read_b128 v[186:189], v88 offset:53248
	s_waitcnt lgkmcnt(6)
	v_mfma_f32_32x32x16_bf16 v[50:65], v[190:193], v[194:197], v[50:65]
	s_waitcnt lgkmcnt(4)
	v_mfma_f32_32x32x16_bf16 v[34:49], v[190:193], v[202:205], v[34:49]
	v_mfma_f32_32x32x16_bf16 v[18:33], v[198:201], v[194:197], v[18:33]
	v_mfma_f32_32x32x16_bf16 v[2:17], v[198:201], v[202:205], v[2:17]
	ds_read_b128 v[190:193], v87 offset:16384
	ds_read_b128 v[194:197], v87 offset:20480
	ds_read_b128 v[198:201], v86 offset:49152
	ds_read_b128 v[202:205], v86 offset:53248
	s_waitcnt vmcnt(0)
	s_waitcnt lgkmcnt(0)
	s_barrier
	s_add_u32 m0, s32, 0x4000
	s_nop 0
	global_load_lds_dwordx4 v[66:67], off
	s_add_u32 m0, s32, 0x5000
	s_nop 0
	global_load_lds_dwordx4 v[70:71], off
	s_add_u32 m0, s32, 0x6000
	s_nop 0
	global_load_lds_dwordx4 v[74:75], off
	s_add_u32 m0, s32, 0x7000
	s_nop 0
	global_load_lds_dwordx4 v[78:79], off
	s_add_u32 m0, s32, 0xc000
	s_nop 0
	global_load_lds_dwordx4 v[68:69], off
	s_add_u32 m0, s32, 0xd000
	s_nop 0
	global_load_lds_dwordx4 v[72:73], off
	s_add_u32 m0, s32, 0xe000
	s_nop 0
	global_load_lds_dwordx4 v[76:77], off
	s_add_u32 m0, s32, 0xf000
	s_nop 0
	global_load_lds_dwordx4 v[80:81], off
	v_lshl_add_u64 v[66:67], v[66:67], 0, 64
	v_lshl_add_u64 v[66:67], v[66:67], 0, 64
	v_lshl_add_u64 v[70:71], v[70:71], 0, 64
	v_lshl_add_u64 v[70:71], v[70:71], 0, 64
	v_lshl_add_u64 v[74:75], v[74:75], 0, 64
	v_lshl_add_u64 v[74:75], v[74:75], 0, 64
	v_lshl_add_u64 v[78:79], v[78:79], 0, 64
	v_lshl_add_u64 v[78:79], v[78:79], 0, 64
	v_lshl_add_u64 v[68:69], v[68:69], 0, 64
	v_lshl_add_u64 v[68:69], v[68:69], 0, 64
	v_lshl_add_u64 v[72:73], v[72:73], 0, 64
	v_lshl_add_u64 v[72:73], v[72:73], 0, 64
	v_lshl_add_u64 v[76:77], v[76:77], 0, 64
	v_lshl_add_u64 v[76:77], v[76:77], 0, 64
	v_lshl_add_u64 v[80:81], v[80:81], 0, 64
	v_lshl_add_u64 v[80:81], v[80:81], 0, 64
	v_mfma_f32_32x32x16_bf16 v[50:65], v[162:165], v[182:185], v[50:65]
	v_mfma_f32_32x32x16_bf16 v[34:49], v[162:165], v[186:189], v[34:49]
	v_mfma_f32_32x32x16_bf16 v[18:33], v[166:169], v[182:185], v[18:33]
	v_mfma_f32_32x32x16_bf16 v[2:17], v[166:169], v[186:189], v[2:17]
	v_mfma_f32_32x32x16_bf16 v[50:65], v[190:193], v[198:201], v[50:65]
	v_mfma_f32_32x32x16_bf16 v[34:49], v[190:193], v[202:205], v[34:49]
	v_mfma_f32_32x32x16_bf16 v[18:33], v[194:197], v[198:201], v[18:33]
	v_mfma_f32_32x32x16_bf16 v[2:17], v[194:197], v[202:205], v[2:17]
	ds_read_b128 v[162:165], v91
	ds_read_b128 v[166:169], v92 offset:32768
	ds_read_b128 v[182:185], v91 offset:4096
	ds_read_b128 v[186:189], v92 offset:36864
	ds_read_b128 v[190:193], v93
	ds_read_b128 v[194:197], v90 offset:32768
	ds_read_b128 v[198:201], v93 offset:4096
	ds_read_b128 v[202:205], v90 offset:36864
	s_waitcnt lgkmcnt(6)
	v_mfma_f32_32x32x16_bf16 v[50:65], v[162:165], v[166:169], v[50:65]
	s_waitcnt lgkmcnt(4)
	v_mfma_f32_32x32x16_bf16 v[34:49], v[162:165], v[186:189], v[34:49]
	v_mfma_f32_32x32x16_bf16 v[18:33], v[182:185], v[166:169], v[18:33]
	v_mfma_f32_32x32x16_bf16 v[2:17], v[182:185], v[186:189], v[2:17]
	ds_read_b128 v[162:165], v89
	ds_read_b128 v[166:169], v89 offset:4096
	ds_read_b128 v[182:185], v88 offset:32768
	ds_read_b128 v[186:189], v88 offset:36864
	s_waitcnt lgkmcnt(6)
	v_mfma_f32_32x32x16_bf16 v[50:65], v[190:193], v[194:197], v[50:65]
	s_waitcnt lgkmcnt(4)
	v_mfma_f32_32x32x16_bf16 v[34:49], v[190:193], v[202:205], v[34:49]
	v_mfma_f32_32x32x16_bf16 v[18:33], v[198:201], v[194:197], v[18:33]
	v_mfma_f32_32x32x16_bf16 v[2:17], v[198:201], v[202:205], v[2:17]
	ds_read_b128 v[190:193], v87
	ds_read_b128 v[194:197], v87 offset:4096
	ds_read_b128 v[198:201], v86 offset:32768
	ds_read_b128 v[202:205], v86 offset:36864
	s_waitcnt vmcnt(0)
	s_waitcnt lgkmcnt(0)
	s_barrier
	s_add_u32 m0, s32, 0x0
	s_nop 0
	global_load_lds_dwordx4 v[66:67], off
	s_add_u32 m0, s32, 0x1000
	s_nop 0
	global_load_lds_dwordx4 v[70:71], off
	s_add_u32 m0, s32, 0x2000
	s_nop 0
	global_load_lds_dwordx4 v[74:75], off
	s_add_u32 m0, s32, 0x3000
	s_nop 0
	global_load_lds_dwordx4 v[78:79], off
	s_add_u32 m0, s32, 0x8000
	s_nop 0
	global_load_lds_dwordx4 v[68:69], off
	s_add_u32 m0, s32, 0x9000
	s_nop 0
	global_load_lds_dwordx4 v[72:73], off
	s_add_u32 m0, s32, 0xa000
	s_nop 0
	global_load_lds_dwordx4 v[76:77], off
	s_add_u32 m0, s32, 0xb000
	s_nop 0
	global_load_lds_dwordx4 v[80:81], off
	v_lshl_add_u64 v[66:67], v[66:67], 0, 64
	v_lshl_add_u64 v[66:67], v[66:67], 0, 64
	v_lshl_add_u64 v[70:71], v[70:71], 0, 64
	v_lshl_add_u64 v[70:71], v[70:71], 0, 64
	v_lshl_add_u64 v[74:75], v[74:75], 0, 64
	v_lshl_add_u64 v[74:75], v[74:75], 0, 64
	v_lshl_add_u64 v[78:79], v[78:79], 0, 64
	v_lshl_add_u64 v[78:79], v[78:79], 0, 64
	v_lshl_add_u64 v[68:69], v[68:69], 0, 64
	v_lshl_add_u64 v[68:69], v[68:69], 0, 64
	v_lshl_add_u64 v[72:73], v[72:73], 0, 64
	v_lshl_add_u64 v[72:73], v[72:73], 0, 64
	v_lshl_add_u64 v[76:77], v[76:77], 0, 64
	v_lshl_add_u64 v[76:77], v[76:77], 0, 64
	v_lshl_add_u64 v[80:81], v[80:81], 0, 64
	v_lshl_add_u64 v[80:81], v[80:81], 0, 64
	v_mfma_f32_32x32x16_bf16 v[50:65], v[162:165], v[182:185], v[50:65]
	v_mfma_f32_32x32x16_bf16 v[34:49], v[162:165], v[186:189], v[34:49]
	v_mfma_f32_32x32x16_bf16 v[18:33], v[166:169], v[182:185], v[18:33]
	v_mfma_f32_32x32x16_bf16 v[2:17], v[166:169], v[186:189], v[2:17]
	v_mfma_f32_32x32x16_bf16 v[50:65], v[190:193], v[198:201], v[50:65]
	v_mfma_f32_32x32x16_bf16 v[34:49], v[190:193], v[202:205], v[34:49]
	v_mfma_f32_32x32x16_bf16 v[18:33], v[194:197], v[198:201], v[18:33]
	v_mfma_f32_32x32x16_bf16 v[2:17], v[194:197], v[202:205], v[2:17]
	ds_read_b128 v[162:165], v91 offset:16384
	ds_read_b128 v[166:169], v92 offset:49152
	ds_read_b128 v[182:185], v91 offset:20480
	ds_read_b128 v[186:189], v92 offset:53248
	ds_read_b128 v[190:193], v93 offset:16384
	ds_read_b128 v[194:197], v90 offset:49152
	ds_read_b128 v[198:201], v93 offset:20480
	ds_read_b128 v[202:205], v90 offset:53248
	s_waitcnt lgkmcnt(6)
	v_mfma_f32_32x32x16_bf16 v[50:65], v[162:165], v[166:169], v[50:65]
	s_waitcnt lgkmcnt(4)
	v_mfma_f32_32x32x16_bf16 v[34:49], v[162:165], v[186:189], v[34:49]
	v_mfma_f32_32x32x16_bf16 v[18:33], v[182:185], v[166:169], v[18:33]
	v_mfma_f32_32x32x16_bf16 v[2:17], v[182:185], v[186:189], v[2:17]
	ds_read_b128 v[162:165], v89 offset:16384
	ds_read_b128 v[166:169], v89 offset:20480
	ds_read_b128 v[182:185], v88 offset:49152
	ds_read_b128 v[186:189], v88 offset:53248
	s_waitcnt lgkmcnt(6)
	v_mfma_f32_32x32x16_bf16 v[50:65], v[190:193], v[194:197], v[50:65]
	s_waitcnt lgkmcnt(4)
	v_mfma_f32_32x32x16_bf16 v[34:49], v[190:193], v[202:205], v[34:49]
	v_mfma_f32_32x32x16_bf16 v[18:33], v[198:201], v[194:197], v[18:33]
	v_mfma_f32_32x32x16_bf16 v[2:17], v[198:201], v[202:205], v[2:17]
	ds_read_b128 v[190:193], v87 offset:16384
	ds_read_b128 v[194:197], v87 offset:20480
	ds_read_b128 v[198:201], v86 offset:49152
	ds_read_b128 v[202:205], v86 offset:53248
	s_waitcnt vmcnt(0)
	s_waitcnt lgkmcnt(0)
	s_barrier
	s_add_u32 m0, s32, 0x4000
	s_nop 0
	global_load_lds_dwordx4 v[66:67], off
	s_add_u32 m0, s32, 0x5000
	s_nop 0
	global_load_lds_dwordx4 v[70:71], off
	s_add_u32 m0, s32, 0x6000
	s_nop 0
	global_load_lds_dwordx4 v[74:75], off
	s_add_u32 m0, s32, 0x7000
	s_nop 0
	global_load_lds_dwordx4 v[78:79], off
	s_add_u32 m0, s32, 0xc000
	s_nop 0
	global_load_lds_dwordx4 v[68:69], off
	s_add_u32 m0, s32, 0xd000
	s_nop 0
	global_load_lds_dwordx4 v[72:73], off
	s_add_u32 m0, s32, 0xe000
	s_nop 0
	global_load_lds_dwordx4 v[76:77], off
	s_add_u32 m0, s32, 0xf000
	s_nop 0
	global_load_lds_dwordx4 v[80:81], off
	v_lshl_add_u64 v[66:67], v[66:67], 0, 64
	v_lshl_add_u64 v[66:67], v[66:67], 0, 64
	v_lshl_add_u64 v[70:71], v[70:71], 0, 64
	v_lshl_add_u64 v[70:71], v[70:71], 0, 64
	v_lshl_add_u64 v[74:75], v[74:75], 0, 64
	v_lshl_add_u64 v[74:75], v[74:75], 0, 64
	v_lshl_add_u64 v[78:79], v[78:79], 0, 64
	v_lshl_add_u64 v[78:79], v[78:79], 0, 64
	v_lshl_add_u64 v[68:69], v[68:69], 0, 64
	v_lshl_add_u64 v[68:69], v[68:69], 0, 64
	v_lshl_add_u64 v[72:73], v[72:73], 0, 64
	v_lshl_add_u64 v[72:73], v[72:73], 0, 64
	v_lshl_add_u64 v[76:77], v[76:77], 0, 64
	v_lshl_add_u64 v[76:77], v[76:77], 0, 64
	v_lshl_add_u64 v[80:81], v[80:81], 0, 64
	v_lshl_add_u64 v[80:81], v[80:81], 0, 64
	v_mfma_f32_32x32x16_bf16 v[50:65], v[162:165], v[182:185], v[50:65]
	v_mfma_f32_32x32x16_bf16 v[34:49], v[162:165], v[186:189], v[34:49]
	v_mfma_f32_32x32x16_bf16 v[18:33], v[166:169], v[182:185], v[18:33]
	v_mfma_f32_32x32x16_bf16 v[2:17], v[166:169], v[186:189], v[2:17]
	v_mfma_f32_32x32x16_bf16 v[50:65], v[190:193], v[198:201], v[50:65]
	v_mfma_f32_32x32x16_bf16 v[34:49], v[190:193], v[202:205], v[34:49]
	v_mfma_f32_32x32x16_bf16 v[18:33], v[194:197], v[198:201], v[18:33]
	v_mfma_f32_32x32x16_bf16 v[2:17], v[194:197], v[202:205], v[2:17]
	ds_read_b128 v[162:165], v91
	ds_read_b128 v[166:169], v92 offset:32768
	ds_read_b128 v[182:185], v91 offset:4096
	ds_read_b128 v[186:189], v92 offset:36864
	ds_read_b128 v[190:193], v93
	ds_read_b128 v[194:197], v90 offset:32768
	ds_read_b128 v[198:201], v93 offset:4096
	ds_read_b128 v[202:205], v90 offset:36864
	s_waitcnt lgkmcnt(6)
	v_mfma_f32_32x32x16_bf16 v[50:65], v[162:165], v[166:169], v[50:65]
	s_waitcnt lgkmcnt(4)
	v_mfma_f32_32x32x16_bf16 v[34:49], v[162:165], v[186:189], v[34:49]
	v_mfma_f32_32x32x16_bf16 v[18:33], v[182:185], v[166:169], v[18:33]
	v_mfma_f32_32x32x16_bf16 v[2:17], v[182:185], v[186:189], v[2:17]
	ds_read_b128 v[162:165], v89
	ds_read_b128 v[166:169], v89 offset:4096
	ds_read_b128 v[182:185], v88 offset:32768
	ds_read_b128 v[186:189], v88 offset:36864
	s_waitcnt lgkmcnt(6)
	v_mfma_f32_32x32x16_bf16 v[50:65], v[190:193], v[194:197], v[50:65]
	s_waitcnt lgkmcnt(4)
	v_mfma_f32_32x32x16_bf16 v[34:49], v[190:193], v[202:205], v[34:49]
	v_mfma_f32_32x32x16_bf16 v[18:33], v[198:201], v[194:197], v[18:33]
	v_mfma_f32_32x32x16_bf16 v[2:17], v[198:201], v[202:205], v[2:17]
	ds_read_b128 v[190:193], v87
	ds_read_b128 v[194:197], v87 offset:4096
	ds_read_b128 v[198:201], v86 offset:32768
	ds_read_b128 v[202:205], v86 offset:36864
	s_waitcnt vmcnt(0)
	s_waitcnt lgkmcnt(0)
	s_barrier
	s_add_u32 m0, s32, 0x0
	s_nop 0
	global_load_lds_dwordx4 v[66:67], off
	s_add_u32 m0, s32, 0x1000
	s_nop 0
	global_load_lds_dwordx4 v[70:71], off
	s_add_u32 m0, s32, 0x2000
	s_nop 0
	global_load_lds_dwordx4 v[74:75], off
	s_add_u32 m0, s32, 0x3000
	s_nop 0
	global_load_lds_dwordx4 v[78:79], off
	s_add_u32 m0, s32, 0x8000
	s_nop 0
	global_load_lds_dwordx4 v[68:69], off
	s_add_u32 m0, s32, 0x9000
	s_nop 0
	global_load_lds_dwordx4 v[72:73], off
	s_add_u32 m0, s32, 0xa000
	s_nop 0
	global_load_lds_dwordx4 v[76:77], off
	s_add_u32 m0, s32, 0xb000
	s_nop 0
	global_load_lds_dwordx4 v[80:81], off
	v_lshl_add_u64 v[66:67], v[66:67], 0, 64
	v_lshl_add_u64 v[66:67], v[66:67], 0, 64
	v_lshl_add_u64 v[70:71], v[70:71], 0, 64
	v_lshl_add_u64 v[70:71], v[70:71], 0, 64
	v_lshl_add_u64 v[74:75], v[74:75], 0, 64
	v_lshl_add_u64 v[74:75], v[74:75], 0, 64
	v_lshl_add_u64 v[78:79], v[78:79], 0, 64
	v_lshl_add_u64 v[78:79], v[78:79], 0, 64
	v_lshl_add_u64 v[68:69], v[68:69], 0, 64
	v_lshl_add_u64 v[68:69], v[68:69], 0, 64
	v_lshl_add_u64 v[72:73], v[72:73], 0, 64
	v_lshl_add_u64 v[72:73], v[72:73], 0, 64
	v_lshl_add_u64 v[76:77], v[76:77], 0, 64
	v_lshl_add_u64 v[76:77], v[76:77], 0, 64
	v_lshl_add_u64 v[80:81], v[80:81], 0, 64
	v_lshl_add_u64 v[80:81], v[80:81], 0, 64
	v_mfma_f32_32x32x16_bf16 v[50:65], v[162:165], v[182:185], v[50:65]
	v_mfma_f32_32x32x16_bf16 v[34:49], v[162:165], v[186:189], v[34:49]
	v_mfma_f32_32x32x16_bf16 v[18:33], v[166:169], v[182:185], v[18:33]
	v_mfma_f32_32x32x16_bf16 v[2:17], v[166:169], v[186:189], v[2:17]
	v_mfma_f32_32x32x16_bf16 v[50:65], v[190:193], v[198:201], v[50:65]
	v_mfma_f32_32x32x16_bf16 v[34:49], v[190:193], v[202:205], v[34:49]
	v_mfma_f32_32x32x16_bf16 v[18:33], v[194:197], v[198:201], v[18:33]
	v_mfma_f32_32x32x16_bf16 v[2:17], v[194:197], v[202:205], v[2:17]
	ds_read_b128 v[162:165], v91 offset:16384
	ds_read_b128 v[166:169], v92 offset:49152
	ds_read_b128 v[182:185], v91 offset:20480
	ds_read_b128 v[186:189], v92 offset:53248
	ds_read_b128 v[190:193], v93 offset:16384
	ds_read_b128 v[194:197], v90 offset:49152
	ds_read_b128 v[198:201], v93 offset:20480
	ds_read_b128 v[202:205], v90 offset:53248
	s_waitcnt lgkmcnt(6)
	v_mfma_f32_32x32x16_bf16 v[50:65], v[162:165], v[166:169], v[50:65]
	s_waitcnt lgkmcnt(4)
	v_mfma_f32_32x32x16_bf16 v[34:49], v[162:165], v[186:189], v[34:49]
	v_mfma_f32_32x32x16_bf16 v[18:33], v[182:185], v[166:169], v[18:33]
	v_mfma_f32_32x32x16_bf16 v[2:17], v[182:185], v[186:189], v[2:17]
	ds_read_b128 v[162:165], v89 offset:16384
	ds_read_b128 v[166:169], v89 offset:20480
	ds_read_b128 v[182:185], v88 offset:49152
	ds_read_b128 v[186:189], v88 offset:53248
	s_waitcnt lgkmcnt(6)
	v_mfma_f32_32x32x16_bf16 v[50:65], v[190:193], v[194:197], v[50:65]
	s_waitcnt lgkmcnt(4)
	v_mfma_f32_32x32x16_bf16 v[34:49], v[190:193], v[202:205], v[34:49]
	v_mfma_f32_32x32x16_bf16 v[18:33], v[198:201], v[194:197], v[18:33]
	v_mfma_f32_32x32x16_bf16 v[2:17], v[198:201], v[202:205], v[2:17]
	ds_read_b128 v[190:193], v87 offset:16384
	ds_read_b128 v[194:197], v87 offset:20480
	ds_read_b128 v[198:201], v86 offset:49152
	ds_read_b128 v[202:205], v86 offset:53248
	s_waitcnt vmcnt(0)
	s_waitcnt lgkmcnt(0)
	s_barrier
	s_add_u32 m0, s32, 0x4000
	s_nop 0
	global_load_lds_dwordx4 v[66:67], off
	s_add_u32 m0, s32, 0x5000
	s_nop 0
	global_load_lds_dwordx4 v[70:71], off
	s_add_u32 m0, s32, 0x6000
	s_nop 0
	global_load_lds_dwordx4 v[74:75], off
	s_add_u32 m0, s32, 0x7000
	s_nop 0
	global_load_lds_dwordx4 v[78:79], off
	s_add_u32 m0, s32, 0xc000
	s_nop 0
	global_load_lds_dwordx4 v[68:69], off
	s_add_u32 m0, s32, 0xd000
	s_nop 0
	global_load_lds_dwordx4 v[72:73], off
	s_add_u32 m0, s32, 0xe000
	s_nop 0
	global_load_lds_dwordx4 v[76:77], off
	s_add_u32 m0, s32, 0xf000
	s_nop 0
	global_load_lds_dwordx4 v[80:81], off
	v_lshl_add_u64 v[66:67], v[66:67], 0, 64
	v_lshl_add_u64 v[66:67], v[66:67], 0, 64
	v_lshl_add_u64 v[70:71], v[70:71], 0, 64
	v_lshl_add_u64 v[70:71], v[70:71], 0, 64
	v_lshl_add_u64 v[74:75], v[74:75], 0, 64
	v_lshl_add_u64 v[74:75], v[74:75], 0, 64
	v_lshl_add_u64 v[78:79], v[78:79], 0, 64
	v_lshl_add_u64 v[78:79], v[78:79], 0, 64
	v_lshl_add_u64 v[68:69], v[68:69], 0, 64
	v_lshl_add_u64 v[68:69], v[68:69], 0, 64
	v_lshl_add_u64 v[72:73], v[72:73], 0, 64
	v_lshl_add_u64 v[72:73], v[72:73], 0, 64
	v_lshl_add_u64 v[76:77], v[76:77], 0, 64
	v_lshl_add_u64 v[76:77], v[76:77], 0, 64
	v_lshl_add_u64 v[80:81], v[80:81], 0, 64
	v_lshl_add_u64 v[80:81], v[80:81], 0, 64
	v_mfma_f32_32x32x16_bf16 v[50:65], v[162:165], v[182:185], v[50:65]
	v_mfma_f32_32x32x16_bf16 v[34:49], v[162:165], v[186:189], v[34:49]
	v_mfma_f32_32x32x16_bf16 v[18:33], v[166:169], v[182:185], v[18:33]
	v_mfma_f32_32x32x16_bf16 v[2:17], v[166:169], v[186:189], v[2:17]
	v_mfma_f32_32x32x16_bf16 v[50:65], v[190:193], v[198:201], v[50:65]
	v_mfma_f32_32x32x16_bf16 v[34:49], v[190:193], v[202:205], v[34:49]
	v_mfma_f32_32x32x16_bf16 v[18:33], v[194:197], v[198:201], v[18:33]
	v_mfma_f32_32x32x16_bf16 v[2:17], v[194:197], v[202:205], v[2:17]
	ds_read_b128 v[162:165], v91
	ds_read_b128 v[166:169], v92 offset:32768
	ds_read_b128 v[182:185], v91 offset:4096
	ds_read_b128 v[186:189], v92 offset:36864
	ds_read_b128 v[190:193], v93
	ds_read_b128 v[194:197], v90 offset:32768
	ds_read_b128 v[198:201], v93 offset:4096
	ds_read_b128 v[202:205], v90 offset:36864
	s_waitcnt lgkmcnt(6)
	v_mfma_f32_32x32x16_bf16 v[50:65], v[162:165], v[166:169], v[50:65]
	s_waitcnt lgkmcnt(4)
	v_mfma_f32_32x32x16_bf16 v[34:49], v[162:165], v[186:189], v[34:49]
	v_mfma_f32_32x32x16_bf16 v[18:33], v[182:185], v[166:169], v[18:33]
	v_mfma_f32_32x32x16_bf16 v[2:17], v[182:185], v[186:189], v[2:17]
	ds_read_b128 v[162:165], v89
	ds_read_b128 v[166:169], v89 offset:4096
	ds_read_b128 v[182:185], v88 offset:32768
	ds_read_b128 v[186:189], v88 offset:36864
	s_waitcnt lgkmcnt(6)
	v_mfma_f32_32x32x16_bf16 v[50:65], v[190:193], v[194:197], v[50:65]
	s_waitcnt lgkmcnt(4)
	v_mfma_f32_32x32x16_bf16 v[34:49], v[190:193], v[202:205], v[34:49]
	v_mfma_f32_32x32x16_bf16 v[18:33], v[198:201], v[194:197], v[18:33]
	v_mfma_f32_32x32x16_bf16 v[2:17], v[198:201], v[202:205], v[2:17]
	ds_read_b128 v[190:193], v87
	ds_read_b128 v[194:197], v87 offset:4096
	ds_read_b128 v[198:201], v86 offset:32768
	ds_read_b128 v[202:205], v86 offset:36864
	s_waitcnt vmcnt(0)
	s_waitcnt lgkmcnt(0)
	s_barrier
	s_add_u32 m0, s32, 0x0
	s_nop 0
	global_load_lds_dwordx4 v[66:67], off
	s_add_u32 m0, s32, 0x1000
	s_nop 0
	global_load_lds_dwordx4 v[70:71], off
	s_add_u32 m0, s32, 0x2000
	s_nop 0
	global_load_lds_dwordx4 v[74:75], off
	s_add_u32 m0, s32, 0x3000
	s_nop 0
	global_load_lds_dwordx4 v[78:79], off
	s_add_u32 m0, s32, 0x8000
	s_nop 0
	global_load_lds_dwordx4 v[68:69], off
	s_add_u32 m0, s32, 0x9000
	s_nop 0
	global_load_lds_dwordx4 v[72:73], off
	s_add_u32 m0, s32, 0xa000
	s_nop 0
	global_load_lds_dwordx4 v[76:77], off
	s_add_u32 m0, s32, 0xb000
	s_nop 0
	global_load_lds_dwordx4 v[80:81], off
	v_lshl_add_u64 v[66:67], v[66:67], 0, 64
	v_lshl_add_u64 v[66:67], v[66:67], 0, 64
	v_lshl_add_u64 v[70:71], v[70:71], 0, 64
	v_lshl_add_u64 v[70:71], v[70:71], 0, 64
	v_lshl_add_u64 v[74:75], v[74:75], 0, 64
	v_lshl_add_u64 v[74:75], v[74:75], 0, 64
	v_lshl_add_u64 v[78:79], v[78:79], 0, 64
	v_lshl_add_u64 v[78:79], v[78:79], 0, 64
	v_lshl_add_u64 v[68:69], v[68:69], 0, 64
	v_lshl_add_u64 v[68:69], v[68:69], 0, 64
	v_lshl_add_u64 v[72:73], v[72:73], 0, 64
	v_lshl_add_u64 v[72:73], v[72:73], 0, 64
	v_lshl_add_u64 v[76:77], v[76:77], 0, 64
	v_lshl_add_u64 v[76:77], v[76:77], 0, 64
	v_lshl_add_u64 v[80:81], v[80:81], 0, 64
	v_lshl_add_u64 v[80:81], v[80:81], 0, 64
	s_nop 0
	s_nop 0
	s_nop 0
	s_nop 0
	s_nop 0
	s_nop 0
	s_nop 0
	v_mfma_f32_32x32x16_bf16 v[50:65], v[162:165], v[182:185], v[50:65]
	v_mfma_f32_32x32x16_bf16 v[34:49], v[162:165], v[186:189], v[34:49]
	v_mfma_f32_32x32x16_bf16 v[18:33], v[166:169], v[182:185], v[18:33]
	v_mfma_f32_32x32x16_bf16 v[2:17], v[166:169], v[186:189], v[2:17]
	ds_read_b128 v[110:113], v91 offset:16384
	ds_read_b128 v[114:117], v91 offset:20480
	ds_read_b128 v[118:121], v92 offset:49152
	ds_read_b128 v[122:125], v92 offset:53248
	ds_read_b128 v[162:165], v93 offset:16384
	ds_read_b128 v[166:169], v93 offset:20480
	ds_read_b128 v[182:185], v90 offset:49152
	ds_read_b128 v[186:189], v90 offset:53248
	v_mfma_f32_32x32x16_bf16 v[50:65], v[190:193], v[198:201], v[50:65]
	v_mfma_f32_32x32x16_bf16 v[34:49], v[190:193], v[202:205], v[34:49]
	v_mfma_f32_32x32x16_bf16 v[18:33], v[194:197], v[198:201], v[18:33]
	v_mfma_f32_32x32x16_bf16 v[2:17], v[194:197], v[202:205], v[2:17]
	s_waitcnt lgkmcnt(5)
	v_mfma_f32_32x32x16_bf16 v[50:65], v[110:113], v[118:121], v[50:65]
	s_waitcnt lgkmcnt(4)
	v_mfma_f32_32x32x16_bf16 v[34:49], v[110:113], v[122:125], v[34:49]
	v_mfma_f32_32x32x16_bf16 v[18:33], v[114:117], v[118:121], v[18:33]
	v_mfma_f32_32x32x16_bf16 v[2:17], v[114:117], v[122:125], v[2:17]
	ds_read_b128 v[110:113], v89 offset:16384
	ds_read_b128 v[114:117], v89 offset:20480
	ds_read_b128 v[118:121], v88 offset:49152
	ds_read_b128 v[122:125], v88 offset:53248
	s_waitcnt lgkmcnt(5)
	v_mfma_f32_32x32x16_bf16 v[50:65], v[162:165], v[182:185], v[50:65]
	s_waitcnt lgkmcnt(4)
	v_mfma_f32_32x32x16_bf16 v[34:49], v[162:165], v[186:189], v[34:49]
	v_mfma_f32_32x32x16_bf16 v[18:33], v[166:169], v[182:185], v[18:33]
	v_mfma_f32_32x32x16_bf16 v[2:17], v[166:169], v[186:189], v[2:17]
	ds_read_b128 v[162:165], v87 offset:16384
	ds_read_b128 v[166:169], v87 offset:20480
	ds_read_b128 v[182:185], v86 offset:49152
	ds_read_b128 v[186:189], v86 offset:53248
	s_waitcnt lgkmcnt(5)
	v_mfma_f32_32x32x16_bf16 v[50:65], v[110:113], v[118:121], v[50:65]
	s_waitcnt vmcnt(0)
	s_waitcnt lgkmcnt(0)
	s_barrier
	s_add_u32 m0, s32, 0x4000
	s_nop 0
	global_load_lds_dwordx4 v[66:67], off
	s_add_u32 m0, s32, 0x5000
	s_nop 0
	global_load_lds_dwordx4 v[70:71], off
	s_add_u32 m0, s32, 0x6000
	s_nop 0
	global_load_lds_dwordx4 v[74:75], off
	s_add_u32 m0, s32, 0x7000
	s_nop 0
	global_load_lds_dwordx4 v[78:79], off
	s_add_u32 m0, s32, 0xc000
	s_nop 0
	global_load_lds_dwordx4 v[68:69], off
	s_add_u32 m0, s32, 0xd000
	s_nop 0
	global_load_lds_dwordx4 v[72:73], off
	s_add_u32 m0, s32, 0xe000
	s_nop 0
	global_load_lds_dwordx4 v[76:77], off
	s_add_u32 m0, s32, 0xf000
	s_nop 0
	global_load_lds_dwordx4 v[80:81], off
	v_lshl_add_u64 v[66:67], v[66:67], 0, 64
	v_lshl_add_u64 v[66:67], v[66:67], 0, 64
	v_lshl_add_u64 v[70:71], v[70:71], 0, 64
	v_lshl_add_u64 v[70:71], v[70:71], 0, 64
	v_lshl_add_u64 v[74:75], v[74:75], 0, 64
	v_lshl_add_u64 v[74:75], v[74:75], 0, 64
	v_lshl_add_u64 v[78:79], v[78:79], 0, 64
	v_lshl_add_u64 v[78:79], v[78:79], 0, 64
	v_lshl_add_u64 v[68:69], v[68:69], 0, 64
	v_lshl_add_u64 v[68:69], v[68:69], 0, 64
	v_lshl_add_u64 v[72:73], v[72:73], 0, 64
	v_lshl_add_u64 v[72:73], v[72:73], 0, 64
	v_lshl_add_u64 v[76:77], v[76:77], 0, 64
	v_lshl_add_u64 v[76:77], v[76:77], 0, 64
	v_lshl_add_u64 v[80:81], v[80:81], 0, 64
	v_lshl_add_u64 v[80:81], v[80:81], 0, 64
	v_mfma_f32_32x32x16_bf16 v[34:49], v[110:113], v[122:125], v[34:49]
	v_mfma_f32_32x32x16_bf16 v[18:33], v[114:117], v[118:121], v[18:33]
	v_mfma_f32_32x32x16_bf16 v[2:17], v[114:117], v[122:125], v[2:17]
	ds_read_b128 v[110:113], v91
	ds_read_b128 v[114:117], v91 offset:4096
	ds_read_b128 v[118:121], v92 offset:32768
	ds_read_b128 v[122:125], v92 offset:36864
	ds_read_b128 v[126:129], v93
	ds_read_b128 v[134:137], v93 offset:4096
	ds_read_b128 v[138:141], v90 offset:32768
	ds_read_b128 v[142:145], v90 offset:36864
	v_mfma_f32_32x32x16_bf16 v[50:65], v[162:165], v[182:185], v[50:65]
	v_mfma_f32_32x32x16_bf16 v[34:49], v[162:165], v[186:189], v[34:49]
	v_mfma_f32_32x32x16_bf16 v[18:33], v[166:169], v[182:185], v[18:33]
	v_mfma_f32_32x32x16_bf16 v[2:17], v[166:169], v[186:189], v[2:17]
	s_waitcnt lgkmcnt(5)
	v_mfma_f32_32x32x16_bf16 v[50:65], v[110:113], v[118:121], v[50:65]
	s_waitcnt lgkmcnt(4)
	v_mfma_f32_32x32x16_bf16 v[34:49], v[110:113], v[122:125], v[34:49]
	v_mfma_f32_32x32x16_bf16 v[18:33], v[114:117], v[118:121], v[18:33]
	v_mfma_f32_32x32x16_bf16 v[2:17], v[114:117], v[122:125], v[2:17]
	ds_read_b128 v[110:113], v89
	ds_read_b128 v[114:117], v89 offset:4096
	ds_read_b128 v[118:121], v88 offset:32768
	ds_read_b128 v[122:125], v88 offset:36864
	s_waitcnt lgkmcnt(5)
	v_mfma_f32_32x32x16_bf16 v[50:65], v[126:129], v[138:141], v[50:65]
	s_waitcnt lgkmcnt(4)
	v_mfma_f32_32x32x16_bf16 v[34:49], v[126:129], v[142:145], v[34:49]
	v_mfma_f32_32x32x16_bf16 v[18:33], v[134:137], v[138:141], v[18:33]
	v_mfma_f32_32x32x16_bf16 v[2:17], v[134:137], v[142:145], v[2:17]
	ds_read_b128 v[126:129], v87
	ds_read_b128 v[134:137], v87 offset:4096
	ds_read_b128 v[138:141], v86 offset:32768
	ds_read_b128 v[142:145], v86 offset:36864
	s_waitcnt lgkmcnt(5)
	v_mfma_f32_32x32x16_bf16 v[50:65], v[110:113], v[118:121], v[50:65]
	s_waitcnt vmcnt(0)
	s_waitcnt lgkmcnt(0)
	s_barrier
	ds_read_b128 v[66:69], v91 offset:16384
	ds_read_b128 v[70:73], v91 offset:20480
	ds_read_b128 v[74:77], v92 offset:49152
	ds_read_b128 v[78:81], v92 offset:53248
	ds_read_b128 v[94:97], v93 offset:16384
	ds_read_b128 v[98:101], v93 offset:20480
	ds_read_b128 v[102:105], v90 offset:49152
	ds_read_b128 v[90:93], v90 offset:53248
	v_mfma_f32_32x32x16_bf16 v[34:49], v[110:113], v[122:125], v[34:49]
	v_mfma_f32_32x32x16_bf16 v[18:33], v[114:117], v[118:121], v[18:33]
	v_mfma_f32_32x32x16_bf16 v[2:17], v[114:117], v[122:125], v[2:17]
	v_mfma_f32_32x32x16_bf16 v[50:65], v[126:129], v[138:141], v[50:65]
	v_mfma_f32_32x32x16_bf16 v[34:49], v[126:129], v[142:145], v[34:49]
	v_mfma_f32_32x32x16_bf16 v[18:33], v[134:137], v[138:141], v[18:33]
	v_mfma_f32_32x32x16_bf16 v[2:17], v[134:137], v[142:145], v[2:17]
	s_waitcnt lgkmcnt(5)
	v_mfma_f32_32x32x16_bf16 v[50:65], v[66:69], v[74:77], v[50:65]
	s_waitcnt lgkmcnt(4)
	v_mfma_f32_32x32x16_bf16 v[34:49], v[66:69], v[78:81], v[34:49]
	v_mfma_f32_32x32x16_bf16 v[18:33], v[70:73], v[74:77], v[18:33]
	v_mfma_f32_32x32x16_bf16 v[2:17], v[70:73], v[78:81], v[2:17]
	ds_read_b128 v[66:69], v89 offset:16384
	ds_read_b128 v[70:73], v89 offset:20480
	ds_read_b128 v[74:77], v88 offset:49152
	ds_read_b128 v[78:81], v88 offset:53248
	s_waitcnt lgkmcnt(5)
	v_mfma_f32_32x32x16_bf16 v[50:65], v[94:97], v[102:105], v[50:65]
	s_waitcnt lgkmcnt(4)
	v_mfma_f32_32x32x16_bf16 v[34:49], v[94:97], v[90:93], v[34:49]
	v_mfma_f32_32x32x16_bf16 v[18:33], v[98:101], v[102:105], v[18:33]
	v_mfma_f32_32x32x16_bf16 v[2:17], v[98:101], v[90:93], v[2:17]
	ds_read_b128 v[88:91], v87 offset:16384
	ds_read_b128 v[92:95], v87 offset:20480
	ds_read_b128 v[96:99], v86 offset:49152
	ds_read_b128 v[100:103], v86 offset:53248
	s_waitcnt lgkmcnt(5)
	v_mfma_f32_32x32x16_bf16 v[50:65], v[66:69], v[74:77], v[50:65]
	v_lshlrev_b32_e32 v0, 6, v85
	v_subrev_u32_e32 v0, s2, v0
	s_lshl_b32 s3, s34, 7
	s_movk_i32 s2, 0x9c0
	s_waitcnt lgkmcnt(0)
	s_barrier
	v_mfma_f32_32x32x16_bf16 v[34:49], v[66:69], v[78:81], v[34:49]
	v_add_u32_e32 v66, s7, v0
	v_lshl_add_u32 v68, v83, 6, s3
	v_add_u32_e32 v0, v66, v84
	v_cmp_lt_i32_e64 s[40:41], s63, v0
	v_cmp_gt_u32_e32 vcc, s2, v66
	v_lshl_add_u64 v[66:67], v[0:1], 1, s[48:49]
	v_mfma_f32_32x32x16_bf16 v[18:33], v[70:73], v[74:77], v[18:33]
	v_mfma_f32_32x32x16_bf16 v[2:17], v[70:73], v[78:81], v[2:17]
	v_lshl_or_b32 v70, v82, 2, v68
	v_mfma_f32_32x32x16_bf16 v[50:65], v[88:91], v[96:99], v[50:65]
	v_mfma_f32_32x32x16_bf16 v[34:49], v[88:91], v[100:103], v[34:49]
	v_mfma_f32_32x32x16_bf16 v[18:33], v[92:95], v[96:99], v[18:33]
	v_mfma_f32_32x32x16_bf16 v[2:17], v[92:95], v[100:103], v[2:17]
	s_and_saveexec_b64 s[2:3], s[40:41]
	s_xor_b64 s[2:3], exec, s[2:3]
	s_cbranch_execz .LBB0_236
	s_and_saveexec_b64 s[4:5], vcc
	s_cbranch_execz .LBB0_235
	s_nop 3
	v_cvt_pk_bf16_f32 v71, v50, s0
	v_mad_i64_i32 v[68:69], s[34:35], v70, s68, v[66:67]
	global_store_short v[68:69], v71, off offset:-1920

.LBB0_1186:
	s_ashr_i32 s5, s4, 31
	s_lshr_b32 s5, s5, 29
	s_add_i32 s5, s4, s5
	s_ashr_i32 s34, s5, 3
	s_ashr_i32 s35, s34, 31
	v_readlane_b32 s36, v210, 50
	v_mov_b32_e32 v36, v133
	s_lshl_b64 s[6:7], s[34:35], 18
	v_readlane_b32 s38, v210, 52
	v_readlane_b32 s39, v210, 53
	v_ashrrev_i32_e32 v34, 3, v36
	s_add_u32 s6, s38, s6
	v_ashrrev_i32_e32 v35, 31, v34
	s_addc_u32 s7, s39, s7
	v_lshlrev_b64 v[2:3], 11, v[34:35]
	v_lshlrev_b32_e32 v0, 4, v36
	v_lshl_add_u64 v[2:3], s[6:7], 0, v[2:3]
	v_and_b32_e32 v0, 0x70, v0
	s_lshl_b32 s5, s34, 10
	v_lshl_add_u64 v[66:67], v[2:3], 0, v[0:1]
	v_subrev_u32_e32 v2, s5, v34
	v_add_u32_e32 v2, s3, v2
	v_ashrrev_i32_e32 v3, 31, v2
	v_lshlrev_b64 v[2:3], 11, v[2:3]
	v_lshl_add_u64 v[2:3], s[0:1], 0, v[2:3]
	v_add_co_u32_e32 v70, vcc, s10, v66
	v_lshl_add_u64 v[68:69], v[2:3], 0, v[0:1]
	s_nop 0
	v_addc_co_u32_e32 v71, vcc, 0, v67, vcc
	v_add_co_u32_e32 v72, vcc, s10, v68
	v_addc_co_u32_e32 v73, vcc, 0, v69, vcc
	v_add_co_u32_e32 v74, vcc, s63, v66
	s_nop 0
	v_addc_co_u32_e32 v75, vcc, 0, v67, vcc
	v_add_co_u32_e32 v76, vcc, s63, v68
	s_nop 0
	v_addc_co_u32_e32 v77, vcc, 0, v69, vcc
	v_add_co_u32_e32 v78, vcc, s61, v66
	s_nop 0
	v_addc_co_u32_e32 v79, vcc, 0, v67, vcc
	v_add_co_u32_e32 v80, vcc, s61, v68
	v_lshlrev_b32_e32 v0, 7, v34
	s_nop 0
	v_addc_co_u32_e32 v81, vcc, 0, v69, vcc
	v_lshrrev_b32_e32 v216, 4, v133
	v_xor_b32_e32 v216, v216, v133
	v_and_b32_e32 v216, 7, v216
	v_lshlrev_b32_e32 v216, 4, v216
	v_mov_b32_e32 v217, 0x70
	v_lshrrev_b32_e32 v218, 6, v133
	v_lshlrev_b32_e32 v218, 10, v218
	s_nop 0
	v_readfirstlane_b32 s32, v218
	v_bfi_b32 v66, v217, v216, v66
	v_bfi_b32 v70, v217, v216, v70
	v_bfi_b32 v74, v217, v216, v74
	v_bfi_b32 v78, v217, v216, v78
	v_bfi_b32 v68, v217, v216, v68
	v_bfi_b32 v72, v217, v216, v72
	v_bfi_b32 v76, v217, v216, v76
	v_bfi_b32 v80, v217, v216, v80
	s_add_u32 m0, s32, 0x0
	s_nop 0
	global_load_lds_dwordx4 v[66:67], off
	s_add_u32 m0, s32, 0x1000
	s_nop 0
	global_load_lds_dwordx4 v[70:71], off
	s_add_u32 m0, s32, 0x2000
	s_nop 0
	global_load_lds_dwordx4 v[74:75], off
	s_add_u32 m0, s32, 0x3000
	s_nop 0
	global_load_lds_dwordx4 v[78:79], off
	s_add_u32 m0, s32, 0x8000
	s_nop 0
	global_load_lds_dwordx4 v[68:69], off
	s_add_u32 m0, s32, 0x9000
	s_nop 0
	global_load_lds_dwordx4 v[72:73], off
	s_add_u32 m0, s32, 0xa000
	s_nop 0
	global_load_lds_dwordx4 v[76:77], off
	s_add_u32 m0, s32, 0xb000
	s_nop 0
	global_load_lds_dwordx4 v[80:81], off
	v_lshl_add_u64 v[66:67], v[66:67], 0, 64
	v_lshl_add_u64 v[66:67], v[66:67], 0, 64
	v_lshl_add_u64 v[70:71], v[70:71], 0, 64
	v_lshl_add_u64 v[70:71], v[70:71], 0, 64
	v_lshl_add_u64 v[74:75], v[74:75], 0, 64
	v_lshl_add_u64 v[74:75], v[74:75], 0, 64
	v_lshl_add_u64 v[78:79], v[78:79], 0, 64
	v_lshl_add_u64 v[78:79], v[78:79], 0, 64
	v_lshl_add_u64 v[68:69], v[68:69], 0, 64
	v_lshl_add_u64 v[68:69], v[68:69], 0, 64
	v_lshl_add_u64 v[72:73], v[72:73], 0, 64
	v_lshl_add_u64 v[72:73], v[72:73], 0, 64
	v_lshl_add_u64 v[76:77], v[76:77], 0, 64
	v_lshl_add_u64 v[76:77], v[76:77], 0, 64
	v_lshl_add_u64 v[80:81], v[80:81], 0, 64
	v_lshl_add_u64 v[80:81], v[80:81], 0, 64
	v_lshrrev_b32_e32 v34, 1, v34
	v_xor_b32_e32 v34, v34, v36
	v_lshlrev_b32_e32 v34, 4, v34
	s_movk_i32 s6, 0x70
	v_and_or_b32 v0, v34, s6, v0
	s_waitcnt vmcnt(26)
	v_and_b32_e32 v82, 31, v36
	v_bfe_u32 v85, v36, 5, 1
	v_ashrrev_i32_e32 v84, 7, v36
	v_bfe_u32 v83, v36, 6, 1
	v_readlane_b32 s37, v210, 51
	v_readlane_b32 s40, v210, 54
	v_readlane_b32 s41, v210, 55
	v_readlane_b32 s42, v210, 56
	v_readlane_b32 s43, v210, 57
	v_readlane_b32 s44, v210, 58
	v_readlane_b32 s45, v210, 59
	v_readlane_b32 s46, v210, 60
	v_readlane_b32 s47, v210, 61
	v_readlane_b32 s48, v210, 62
	v_readlane_b32 s49, v210, 63
	v_readlane_b32 s50, v209, 0
	v_readlane_b32 s51, v209, 1
	s_waitcnt vmcnt(0)
	s_waitcnt lgkmcnt(0)
	s_barrier
	s_add_u32 m0, s32, 0x4000
	s_nop 0
	global_load_lds_dwordx4 v[66:67], off
	s_add_u32 m0, s32, 0x5000
	s_nop 0
	global_load_lds_dwordx4 v[70:71], off
	s_add_u32 m0, s32, 0x6000
	s_nop 0
	global_load_lds_dwordx4 v[74:75], off
	s_add_u32 m0, s32, 0x7000
	s_nop 0
	global_load_lds_dwordx4 v[78:79], off
	s_add_u32 m0, s32, 0xc000
	s_nop 0
	global_load_lds_dwordx4 v[68:69], off
	s_add_u32 m0, s32, 0xd000
	s_nop 0
	global_load_lds_dwordx4 v[72:73], off
	s_add_u32 m0, s32, 0xe000
	s_nop 0
	global_load_lds_dwordx4 v[76:77], off
	s_add_u32 m0, s32, 0xf000
	s_nop 0
	global_load_lds_dwordx4 v[80:81], off
	v_lshl_add_u64 v[66:67], v[66:67], 0, 64
	v_lshl_add_u64 v[66:67], v[66:67], 0, 64
	v_lshl_add_u64 v[70:71], v[70:71], 0, 64
	v_lshl_add_u64 v[70:71], v[70:71], 0, 64
	v_lshl_add_u64 v[74:75], v[74:75], 0, 64
	v_lshl_add_u64 v[74:75], v[74:75], 0, 64
	v_lshl_add_u64 v[78:79], v[78:79], 0, 64
	v_lshl_add_u64 v[78:79], v[78:79], 0, 64
	v_lshl_add_u64 v[68:69], v[68:69], 0, 64
	v_lshl_add_u64 v[68:69], v[68:69], 0, 64
	v_lshl_add_u64 v[72:73], v[72:73], 0, 64
	v_lshl_add_u64 v[72:73], v[72:73], 0, 64
	v_lshl_add_u64 v[76:77], v[76:77], 0, 64
	v_lshl_add_u64 v[76:77], v[76:77], 0, 64
	v_lshl_add_u64 v[80:81], v[80:81], 0, 64
	v_lshl_add_u64 v[80:81], v[80:81], 0, 64
	v_lshrrev_b32_e32 v4, 1, v36
	v_lshlrev_b32_e32 v2, 7, v82
	v_bitop3_b32 v4, v4, v85, 7 bitop3:0x6c
	v_lshl_or_b32 v3, v84, 13, v2
	v_bfe_u32 v5, v36, 1, 3
	v_lshlrev_b32_e32 v4, 4, v4
	v_lshl_or_b32 v2, v83, 13, v2
	v_or_b32_e32 v91, v3, v4
	v_or_b32_e32 v92, v2, v4
	v_bitop3_b32 v4, v85, v5, 2 bitop3:0x36
	v_lshlrev_b32_e32 v4, 4, v4
	v_or_b32_e32 v93, v3, v4
	v_or_b32_e32 v90, v2, v4
	v_bitop3_b32 v4, v85, v5, 4 bitop3:0x36
	v_lshlrev_b32_e32 v4, 4, v4
	v_or_b32_e32 v89, v3, v4
	v_or_b32_e32 v88, v2, v4
	v_bitop3_b32 v4, v85, v5, 6 bitop3:0x36
	v_lshlrev_b32_e32 v4, 4, v4
	v_or_b32_e32 v87, v3, v4
	v_or_b32_e32 v86, v2, v4
	ds_read_b128 v[2:5], v91
	ds_read_b128 v[6:9], v92 offset:32768
	ds_read_b128 v[10:13], v91 offset:4096
	ds_read_b128 v[14:17], v92 offset:36864
	ds_read_b128 v[162:165], v93
	ds_read_b128 v[166:169], v90 offset:32768
	ds_read_b128 v[182:185], v93 offset:4096
	ds_read_b128 v[186:189], v90 offset:36864
	s_waitcnt lgkmcnt(6)
	v_mfma_f32_32x32x16_bf16 v[50:65], v[2:5], v[6:9], 0
	s_waitcnt lgkmcnt(4)
	v_mfma_f32_32x32x16_bf16 v[18:33], v[2:5], v[14:17], 0
	v_mfma_f32_32x32x16_bf16 v[34:49], v[10:13], v[6:9], 0
	v_mfma_f32_32x32x16_bf16 v[2:17], v[10:13], v[14:17], 0
	ds_read_b128 v[190:193], v89
	ds_read_b128 v[194:197], v89 offset:4096
	ds_read_b128 v[198:201], v88 offset:32768
	ds_read_b128 v[202:205], v88 offset:36864
	s_waitcnt lgkmcnt(6)
	v_mfma_f32_32x32x16_bf16 v[50:65], v[162:165], v[166:169], v[50:65]
	s_waitcnt lgkmcnt(4)
	v_mfma_f32_32x32x16_bf16 v[18:33], v[162:165], v[186:189], v[18:33]
	v_mfma_f32_32x32x16_bf16 v[34:49], v[182:185], v[166:169], v[34:49]
	v_mfma_f32_32x32x16_bf16 v[2:17], v[182:185], v[186:189], v[2:17]
	ds_read_b128 v[162:165], v87
	ds_read_b128 v[166:169], v87 offset:4096
	ds_read_b128 v[182:185], v86 offset:32768
	ds_read_b128 v[186:189], v86 offset:36864
	s_waitcnt vmcnt(0)
	s_waitcnt lgkmcnt(0)
	s_barrier
	s_add_u32 m0, s32, 0x0
	s_nop 0
	global_load_lds_dwordx4 v[66:67], off
	s_add_u32 m0, s32, 0x1000
	s_nop 0
	global_load_lds_dwordx4 v[70:71], off
	s_add_u32 m0, s32, 0x2000
	s_nop 0
	global_load_lds_dwordx4 v[74:75], off
	s_add_u32 m0, s32, 0x3000
	s_nop 0
	global_load_lds_dwordx4 v[78:79], off
	s_add_u32 m0, s32, 0x8000
	s_nop 0
	global_load_lds_dwordx4 v[68:69], off
	s_add_u32 m0, s32, 0x9000
	s_nop 0
	global_load_lds_dwordx4 v[72:73], off
	s_add_u32 m0, s32, 0xa000
	s_nop 0
	global_load_lds_dwordx4 v[76:77], off
	s_add_u32 m0, s32, 0xb000
	s_nop 0
	global_load_lds_dwordx4 v[80:81], off
	v_lshl_add_u64 v[66:67], v[66:67], 0, 64
	v_lshl_add_u64 v[66:67], v[66:67], 0, 64
	v_lshl_add_u64 v[70:71], v[70:71], 0, 64
	v_lshl_add_u64 v[70:71], v[70:71], 0, 64
	v_lshl_add_u64 v[74:75], v[74:75], 0, 64
	v_lshl_add_u64 v[74:75], v[74:75], 0, 64
	v_lshl_add_u64 v[78:79], v[78:79], 0, 64
	v_lshl_add_u64 v[78:79], v[78:79], 0, 64
	v_lshl_add_u64 v[68:69], v[68:69], 0, 64
	v_lshl_add_u64 v[68:69], v[68:69], 0, 64
	v_lshl_add_u64 v[72:73], v[72:73], 0, 64
	v_lshl_add_u64 v[72:73], v[72:73], 0, 64
	v_lshl_add_u64 v[76:77], v[76:77], 0, 64
	v_lshl_add_u64 v[76:77], v[76:77], 0, 64
	v_lshl_add_u64 v[80:81], v[80:81], 0, 64
	v_lshl_add_u64 v[80:81], v[80:81], 0, 64
	v_mfma_f32_32x32x16_bf16 v[50:65], v[190:193], v[198:201], v[50:65]
	v_mfma_f32_32x32x16_bf16 v[18:33], v[190:193], v[202:205], v[18:33]
	v_mfma_f32_32x32x16_bf16 v[34:49], v[194:197], v[198:201], v[34:49]
	v_mfma_f32_32x32x16_bf16 v[2:17], v[194:197], v[202:205], v[2:17]
	v_mfma_f32_32x32x16_bf16 v[50:65], v[162:165], v[182:185], v[50:65]
	v_mfma_f32_32x32x16_bf16 v[18:33], v[162:165], v[186:189], v[18:33]
	v_mfma_f32_32x32x16_bf16 v[34:49], v[166:169], v[182:185], v[34:49]
	v_mfma_f32_32x32x16_bf16 v[2:17], v[166:169], v[186:189], v[2:17]
	ds_read_b128 v[162:165], v91 offset:16384
	ds_read_b128 v[166:169], v92 offset:49152
	ds_read_b128 v[182:185], v91 offset:20480
	ds_read_b128 v[186:189], v92 offset:53248
	ds_read_b128 v[190:193], v93 offset:16384
	ds_read_b128 v[194:197], v90 offset:49152
	ds_read_b128 v[198:201], v93 offset:20480
	ds_read_b128 v[202:205], v90 offset:53248
	s_waitcnt lgkmcnt(6)
	v_mfma_f32_32x32x16_bf16 v[50:65], v[162:165], v[166:169], v[50:65]
	s_waitcnt lgkmcnt(4)
	v_mfma_f32_32x32x16_bf16 v[18:33], v[162:165], v[186:189], v[18:33]
	v_mfma_f32_32x32x16_bf16 v[34:49], v[182:185], v[166:169], v[34:49]
	v_mfma_f32_32x32x16_bf16 v[2:17], v[182:185], v[186:189], v[2:17]
	ds_read_b128 v[162:165], v89 offset:16384
	ds_read_b128 v[166:169], v89 offset:20480
	ds_read_b128 v[182:185], v88 offset:49152
	ds_read_b128 v[186:189], v88 offset:53248
	s_waitcnt lgkmcnt(6)
	v_mfma_f32_32x32x16_bf16 v[50:65], v[190:193], v[194:197], v[50:65]
	s_waitcnt lgkmcnt(4)
	v_mfma_f32_32x32x16_bf16 v[18:33], v[190:193], v[202:205], v[18:33]
	v_mfma_f32_32x32x16_bf16 v[34:49], v[198:201], v[194:197], v[34:49]
	v_mfma_f32_32x32x16_bf16 v[2:17], v[198:201], v[202:205], v[2:17]
	ds_read_b128 v[190:193], v87 offset:16384
	ds_read_b128 v[194:197], v87 offset:20480
	ds_read_b128 v[198:201], v86 offset:49152
	ds_read_b128 v[202:205], v86 offset:53248
	s_waitcnt vmcnt(0)
	s_waitcnt lgkmcnt(0)
	s_barrier
	s_add_u32 m0, s32, 0x4000
	s_nop 0
	global_load_lds_dwordx4 v[66:67], off
	s_add_u32 m0, s32, 0x5000
	s_nop 0
	global_load_lds_dwordx4 v[70:71], off
	s_add_u32 m0, s32, 0x6000
	s_nop 0
	global_load_lds_dwordx4 v[74:75], off
	s_add_u32 m0, s32, 0x7000
	s_nop 0
	global_load_lds_dwordx4 v[78:79], off
	s_add_u32 m0, s32, 0xc000
	s_nop 0
	global_load_lds_dwordx4 v[68:69], off
	s_add_u32 m0, s32, 0xd000
	s_nop 0
	global_load_lds_dwordx4 v[72:73], off
	s_add_u32 m0, s32, 0xe000
	s_nop 0
	global_load_lds_dwordx4 v[76:77], off
	s_add_u32 m0, s32, 0xf000
	s_nop 0
	global_load_lds_dwordx4 v[80:81], off
	v_lshl_add_u64 v[66:67], v[66:67], 0, 64
	v_lshl_add_u64 v[66:67], v[66:67], 0, 64
	v_lshl_add_u64 v[70:71], v[70:71], 0, 64
	v_lshl_add_u64 v[70:71], v[70:71], 0, 64
	v_lshl_add_u64 v[74:75], v[74:75], 0, 64
	v_lshl_add_u64 v[74:75], v[74:75], 0, 64
	v_lshl_add_u64 v[78:79], v[78:79], 0, 64
	v_lshl_add_u64 v[78:79], v[78:79], 0, 64
	v_lshl_add_u64 v[68:69], v[68:69], 0, 64
	v_lshl_add_u64 v[68:69], v[68:69], 0, 64
	v_lshl_add_u64 v[72:73], v[72:73], 0, 64
	v_lshl_add_u64 v[72:73], v[72:73], 0, 64
	v_lshl_add_u64 v[76:77], v[76:77], 0, 64
	v_lshl_add_u64 v[76:77], v[76:77], 0, 64
	v_lshl_add_u64 v[80:81], v[80:81], 0, 64
	v_lshl_add_u64 v[80:81], v[80:81], 0, 64
	v_mfma_f32_32x32x16_bf16 v[50:65], v[162:165], v[182:185], v[50:65]
	v_mfma_f32_32x32x16_bf16 v[18:33], v[162:165], v[186:189], v[18:33]
	v_mfma_f32_32x32x16_bf16 v[34:49], v[166:169], v[182:185], v[34:49]
	v_mfma_f32_32x32x16_bf16 v[2:17], v[166:169], v[186:189], v[2:17]
	v_mfma_f32_32x32x16_bf16 v[50:65], v[190:193], v[198:201], v[50:65]
	v_mfma_f32_32x32x16_bf16 v[18:33], v[190:193], v[202:205], v[18:33]
	v_mfma_f32_32x32x16_bf16 v[34:49], v[194:197], v[198:201], v[34:49]
	v_mfma_f32_32x32x16_bf16 v[2:17], v[194:197], v[202:205], v[2:17]
	ds_read_b128 v[162:165], v91
	ds_read_b128 v[166:169], v92 offset:32768
	ds_read_b128 v[182:185], v91 offset:4096
	ds_read_b128 v[186:189], v92 offset:36864
	ds_read_b128 v[190:193], v93
	ds_read_b128 v[194:197], v90 offset:32768
	ds_read_b128 v[198:201], v93 offset:4096
	ds_read_b128 v[202:205], v90 offset:36864
	s_waitcnt lgkmcnt(6)
	v_mfma_f32_32x32x16_bf16 v[50:65], v[162:165], v[166:169], v[50:65]
	s_waitcnt lgkmcnt(4)
	v_mfma_f32_32x32x16_bf16 v[18:33], v[162:165], v[186:189], v[18:33]
	v_mfma_f32_32x32x16_bf16 v[34:49], v[182:185], v[166:169], v[34:49]
	v_mfma_f32_32x32x16_bf16 v[2:17], v[182:185], v[186:189], v[2:17]
	ds_read_b128 v[162:165], v89
	ds_read_b128 v[166:169], v89 offset:4096
	ds_read_b128 v[182:185], v88 offset:32768
	ds_read_b128 v[186:189], v88 offset:36864
	s_waitcnt lgkmcnt(6)
	v_mfma_f32_32x32x16_bf16 v[50:65], v[190:193], v[194:197], v[50:65]
	s_waitcnt lgkmcnt(4)
	v_mfma_f32_32x32x16_bf16 v[18:33], v[190:193], v[202:205], v[18:33]
	v_mfma_f32_32x32x16_bf16 v[34:49], v[198:201], v[194:197], v[34:49]
	v_mfma_f32_32x32x16_bf16 v[2:17], v[198:201], v[202:205], v[2:17]
	ds_read_b128 v[190:193], v87
	ds_read_b128 v[194:197], v87 offset:4096
	ds_read_b128 v[198:201], v86 offset:32768
	ds_read_b128 v[202:205], v86 offset:36864
	s_waitcnt vmcnt(0)
	s_waitcnt lgkmcnt(0)
	s_barrier
	s_add_u32 m0, s32, 0x0
	s_nop 0
	global_load_lds_dwordx4 v[66:67], off
	s_add_u32 m0, s32, 0x1000
	s_nop 0
	global_load_lds_dwordx4 v[70:71], off
	s_add_u32 m0, s32, 0x2000
	s_nop 0
	global_load_lds_dwordx4 v[74:75], off
	s_add_u32 m0, s32, 0x3000
	s_nop 0
	global_load_lds_dwordx4 v[78:79], off
	s_add_u32 m0, s32, 0x8000
	s_nop 0
	global_load_lds_dwordx4 v[68:69], off
	s_add_u32 m0, s32, 0x9000
	s_nop 0
	global_load_lds_dwordx4 v[72:73], off
	s_add_u32 m0, s32, 0xa000
	s_nop 0
	global_load_lds_dwordx4 v[76:77], off
	s_add_u32 m0, s32, 0xb000
	s_nop 0
	global_load_lds_dwordx4 v[80:81], off
	v_lshl_add_u64 v[66:67], v[66:67], 0, 64
	v_lshl_add_u64 v[66:67], v[66:67], 0, 64
	v_lshl_add_u64 v[70:71], v[70:71], 0, 64
	v_lshl_add_u64 v[70:71], v[70:71], 0, 64
	v_lshl_add_u64 v[74:75], v[74:75], 0, 64
	v_lshl_add_u64 v[74:75], v[74:75], 0, 64
	v_lshl_add_u64 v[78:79], v[78:79], 0, 64
	v_lshl_add_u64 v[78:79], v[78:79], 0, 64
	v_lshl_add_u64 v[68:69], v[68:69], 0, 64
	v_lshl_add_u64 v[68:69], v[68:69], 0, 64
	v_lshl_add_u64 v[72:73], v[72:73], 0, 64
	v_lshl_add_u64 v[72:73], v[72:73], 0, 64
	v_lshl_add_u64 v[76:77], v[76:77], 0, 64
	v_lshl_add_u64 v[76:77], v[76:77], 0, 64
	v_lshl_add_u64 v[80:81], v[80:81], 0, 64
	v_lshl_add_u64 v[80:81], v[80:81], 0, 64
	v_mfma_f32_32x32x16_bf16 v[50:65], v[162:165], v[182:185], v[50:65]
	v_mfma_f32_32x32x16_bf16 v[18:33], v[162:165], v[186:189], v[18:33]
	v_mfma_f32_32x32x16_bf16 v[34:49], v[166:169], v[182:185], v[34:49]
	v_mfma_f32_32x32x16_bf16 v[2:17], v[166:169], v[186:189], v[2:17]
	v_mfma_f32_32x32x16_bf16 v[50:65], v[190:193], v[198:201], v[50:65]
	v_mfma_f32_32x32x16_bf16 v[18:33], v[190:193], v[202:205], v[18:33]
	v_mfma_f32_32x32x16_bf16 v[34:49], v[194:197], v[198:201], v[34:49]
	v_mfma_f32_32x32x16_bf16 v[2:17], v[194:197], v[202:205], v[2:17]
	ds_read_b128 v[162:165], v91 offset:16384
	ds_read_b128 v[166:169], v92 offset:49152
	ds_read_b128 v[182:185], v91 offset:20480
	ds_read_b128 v[186:189], v92 offset:53248
	ds_read_b128 v[190:193], v93 offset:16384
	ds_read_b128 v[194:197], v90 offset:49152
	ds_read_b128 v[198:201], v93 offset:20480
	ds_read_b128 v[202:205], v90 offset:53248
	s_waitcnt lgkmcnt(6)
	v_mfma_f32_32x32x16_bf16 v[50:65], v[162:165], v[166:169], v[50:65]
	s_waitcnt lgkmcnt(4)
	v_mfma_f32_32x32x16_bf16 v[18:33], v[162:165], v[186:189], v[18:33]
	v_mfma_f32_32x32x16_bf16 v[34:49], v[182:185], v[166:169], v[34:49]
	v_mfma_f32_32x32x16_bf16 v[2:17], v[182:185], v[186:189], v[2:17]
	ds_read_b128 v[162:165], v89 offset:16384
	ds_read_b128 v[166:169], v89 offset:20480
	ds_read_b128 v[182:185], v88 offset:49152
	ds_read_b128 v[186:189], v88 offset:53248
	s_waitcnt lgkmcnt(6)
	v_mfma_f32_32x32x16_bf16 v[50:65], v[190:193], v[194:197], v[50:65]
	s_waitcnt lgkmcnt(4)
	v_mfma_f32_32x32x16_bf16 v[18:33], v[190:193], v[202:205], v[18:33]
	v_mfma_f32_32x32x16_bf16 v[34:49], v[198:201], v[194:197], v[34:49]
	v_mfma_f32_32x32x16_bf16 v[2:17], v[198:201], v[202:205], v[2:17]
	ds_read_b128 v[190:193], v87 offset:16384
	ds_read_b128 v[194:197], v87 offset:20480
	ds_read_b128 v[198:201], v86 offset:49152
	ds_read_b128 v[202:205], v86 offset:53248
	s_waitcnt vmcnt(0)
	s_waitcnt lgkmcnt(0)
	s_barrier
	s_add_u32 m0, s32, 0x4000
	s_nop 0
	global_load_lds_dwordx4 v[66:67], off
	s_add_u32 m0, s32, 0x5000
	s_nop 0
	global_load_lds_dwordx4 v[70:71], off
	s_add_u32 m0, s32, 0x6000
	s_nop 0
	global_load_lds_dwordx4 v[74:75], off
	s_add_u32 m0, s32, 0x7000
	s_nop 0
	global_load_lds_dwordx4 v[78:79], off
	s_add_u32 m0, s32, 0xc000
	s_nop 0
	global_load_lds_dwordx4 v[68:69], off
	s_add_u32 m0, s32, 0xd000
	s_nop 0
	global_load_lds_dwordx4 v[72:73], off
	s_add_u32 m0, s32, 0xe000
	s_nop 0
	global_load_lds_dwordx4 v[76:77], off
	s_add_u32 m0, s32, 0xf000
	s_nop 0
	global_load_lds_dwordx4 v[80:81], off
	v_lshl_add_u64 v[66:67], v[66:67], 0, 64
	v_lshl_add_u64 v[66:67], v[66:67], 0, 64
	v_lshl_add_u64 v[70:71], v[70:71], 0, 64
	v_lshl_add_u64 v[70:71], v[70:71], 0, 64
	v_lshl_add_u64 v[74:75], v[74:75], 0, 64
	v_lshl_add_u64 v[74:75], v[74:75], 0, 64
	v_lshl_add_u64 v[78:79], v[78:79], 0, 64
	v_lshl_add_u64 v[78:79], v[78:79], 0, 64
	v_lshl_add_u64 v[68:69], v[68:69], 0, 64
	v_lshl_add_u64 v[68:69], v[68:69], 0, 64
	v_lshl_add_u64 v[72:73], v[72:73], 0, 64
	v_lshl_add_u64 v[72:73], v[72:73], 0, 64
	v_lshl_add_u64 v[76:77], v[76:77], 0, 64
	v_lshl_add_u64 v[76:77], v[76:77], 0, 64
	v_lshl_add_u64 v[80:81], v[80:81], 0, 64
	v_lshl_add_u64 v[80:81], v[80:81], 0, 64
	v_mfma_f32_32x32x16_bf16 v[50:65], v[162:165], v[182:185], v[50:65]
	v_mfma_f32_32x32x16_bf16 v[18:33], v[162:165], v[186:189], v[18:33]
	v_mfma_f32_32x32x16_bf16 v[34:49], v[166:169], v[182:185], v[34:49]
	v_mfma_f32_32x32x16_bf16 v[2:17], v[166:169], v[186:189], v[2:17]
	v_mfma_f32_32x32x16_bf16 v[50:65], v[190:193], v[198:201], v[50:65]
	v_mfma_f32_32x32x16_bf16 v[18:33], v[190:193], v[202:205], v[18:33]
	v_mfma_f32_32x32x16_bf16 v[34:49], v[194:197], v[198:201], v[34:49]
	v_mfma_f32_32x32x16_bf16 v[2:17], v[194:197], v[202:205], v[2:17]
	ds_read_b128 v[162:165], v91
	ds_read_b128 v[166:169], v92 offset:32768
	ds_read_b128 v[182:185], v91 offset:4096
	ds_read_b128 v[186:189], v92 offset:36864
	ds_read_b128 v[190:193], v93
	ds_read_b128 v[194:197], v90 offset:32768
	ds_read_b128 v[198:201], v93 offset:4096
	ds_read_b128 v[202:205], v90 offset:36864
	s_waitcnt lgkmcnt(6)
	v_mfma_f32_32x32x16_bf16 v[50:65], v[162:165], v[166:169], v[50:65]
	s_waitcnt lgkmcnt(4)
	v_mfma_f32_32x32x16_bf16 v[18:33], v[162:165], v[186:189], v[18:33]
	v_mfma_f32_32x32x16_bf16 v[34:49], v[182:185], v[166:169], v[34:49]
	v_mfma_f32_32x32x16_bf16 v[2:17], v[182:185], v[186:189], v[2:17]
	ds_read_b128 v[162:165], v89
	ds_read_b128 v[166:169], v89 offset:4096
	ds_read_b128 v[182:185], v88 offset:32768
	ds_read_b128 v[186:189], v88 offset:36864
	s_waitcnt lgkmcnt(6)
	v_mfma_f32_32x32x16_bf16 v[50:65], v[190:193], v[194:197], v[50:65]
	s_waitcnt lgkmcnt(4)
	v_mfma_f32_32x32x16_bf16 v[18:33], v[190:193], v[202:205], v[18:33]
	v_mfma_f32_32x32x16_bf16 v[34:49], v[198:201], v[194:197], v[34:49]
	v_mfma_f32_32x32x16_bf16 v[2:17], v[198:201], v[202:205], v[2:17]
	ds_read_b128 v[190:193], v87
	ds_read_b128 v[194:197], v87 offset:4096
	ds_read_b128 v[198:201], v86 offset:32768
	ds_read_b128 v[202:205], v86 offset:36864
	s_waitcnt vmcnt(0)
	s_waitcnt lgkmcnt(0)
	s_barrier
	s_add_u32 m0, s32, 0x0
	s_nop 0
	global_load_lds_dwordx4 v[66:67], off
	s_add_u32 m0, s32, 0x1000
	s_nop 0
	global_load_lds_dwordx4 v[70:71], off
	s_add_u32 m0, s32, 0x2000
	s_nop 0
	global_load_lds_dwordx4 v[74:75], off
	s_add_u32 m0, s32, 0x3000
	s_nop 0
	global_load_lds_dwordx4 v[78:79], off
	s_add_u32 m0, s32, 0x8000
	s_nop 0
	global_load_lds_dwordx4 v[68:69], off
	s_add_u32 m0, s32, 0x9000
	s_nop 0
	global_load_lds_dwordx4 v[72:73], off
	s_add_u32 m0, s32, 0xa000
	s_nop 0
	global_load_lds_dwordx4 v[76:77], off
	s_add_u32 m0, s32, 0xb000
	s_nop 0
	global_load_lds_dwordx4 v[80:81], off
	v_lshl_add_u64 v[66:67], v[66:67], 0, 64
	v_lshl_add_u64 v[66:67], v[66:67], 0, 64
	v_lshl_add_u64 v[70:71], v[70:71], 0, 64
	v_lshl_add_u64 v[70:71], v[70:71], 0, 64
	v_lshl_add_u64 v[74:75], v[74:75], 0, 64
	v_lshl_add_u64 v[74:75], v[74:75], 0, 64
	v_lshl_add_u64 v[78:79], v[78:79], 0, 64
	v_lshl_add_u64 v[78:79], v[78:79], 0, 64
	v_lshl_add_u64 v[68:69], v[68:69], 0, 64
	v_lshl_add_u64 v[68:69], v[68:69], 0, 64
	v_lshl_add_u64 v[72:73], v[72:73], 0, 64
	v_lshl_add_u64 v[72:73], v[72:73], 0, 64
	v_lshl_add_u64 v[76:77], v[76:77], 0, 64
	v_lshl_add_u64 v[76:77], v[76:77], 0, 64
	v_lshl_add_u64 v[80:81], v[80:81], 0, 64
	v_lshl_add_u64 v[80:81], v[80:81], 0, 64
	v_mfma_f32_32x32x16_bf16 v[50:65], v[162:165], v[182:185], v[50:65]
	v_mfma_f32_32x32x16_bf16 v[18:33], v[162:165], v[186:189], v[18:33]
	v_mfma_f32_32x32x16_bf16 v[34:49], v[166:169], v[182:185], v[34:49]
	v_mfma_f32_32x32x16_bf16 v[2:17], v[166:169], v[186:189], v[2:17]
	v_mfma_f32_32x32x16_bf16 v[50:65], v[190:193], v[198:201], v[50:65]
	v_mfma_f32_32x32x16_bf16 v[18:33], v[190:193], v[202:205], v[18:33]
	v_mfma_f32_32x32x16_bf16 v[34:49], v[194:197], v[198:201], v[34:49]
	v_mfma_f32_32x32x16_bf16 v[2:17], v[194:197], v[202:205], v[2:17]
	ds_read_b128 v[162:165], v91 offset:16384
	ds_read_b128 v[166:169], v92 offset:49152
	ds_read_b128 v[182:185], v91 offset:20480
	ds_read_b128 v[186:189], v92 offset:53248
	ds_read_b128 v[190:193], v93 offset:16384
	ds_read_b128 v[194:197], v90 offset:49152
	ds_read_b128 v[198:201], v93 offset:20480
	ds_read_b128 v[202:205], v90 offset:53248
	s_waitcnt lgkmcnt(6)
	v_mfma_f32_32x32x16_bf16 v[50:65], v[162:165], v[166:169], v[50:65]
	s_waitcnt lgkmcnt(4)
	v_mfma_f32_32x32x16_bf16 v[18:33], v[162:165], v[186:189], v[18:33]
	v_mfma_f32_32x32x16_bf16 v[34:49], v[182:185], v[166:169], v[34:49]
	v_mfma_f32_32x32x16_bf16 v[2:17], v[182:185], v[186:189], v[2:17]
	ds_read_b128 v[162:165], v89 offset:16384
	ds_read_b128 v[166:169], v89 offset:20480
	ds_read_b128 v[182:185], v88 offset:49152
	ds_read_b128 v[186:189], v88 offset:53248
	s_waitcnt lgkmcnt(6)
	v_mfma_f32_32x32x16_bf16 v[50:65], v[190:193], v[194:197], v[50:65]
	s_waitcnt lgkmcnt(4)
	v_mfma_f32_32x32x16_bf16 v[18:33], v[190:193], v[202:205], v[18:33]
	v_mfma_f32_32x32x16_bf16 v[34:49], v[198:201], v[194:197], v[34:49]
	v_mfma_f32_32x32x16_bf16 v[2:17], v[198:201], v[202:205], v[2:17]
	ds_read_b128 v[190:193], v87 offset:16384
	ds_read_b128 v[194:197], v87 offset:20480
	ds_read_b128 v[198:201], v86 offset:49152
	ds_read_b128 v[202:205], v86 offset:53248
	s_waitcnt vmcnt(0)
	s_waitcnt lgkmcnt(0)
	s_barrier
	s_add_u32 m0, s32, 0x4000
	s_nop 0
	global_load_lds_dwordx4 v[66:67], off
	s_add_u32 m0, s32, 0x5000
	s_nop 0
	global_load_lds_dwordx4 v[70:71], off
	s_add_u32 m0, s32, 0x6000
	s_nop 0
	global_load_lds_dwordx4 v[74:75], off
	s_add_u32 m0, s32, 0x7000
	s_nop 0
	global_load_lds_dwordx4 v[78:79], off
	s_add_u32 m0, s32, 0xc000
	s_nop 0
	global_load_lds_dwordx4 v[68:69], off
	s_add_u32 m0, s32, 0xd000
	s_nop 0
	global_load_lds_dwordx4 v[72:73], off
	s_add_u32 m0, s32, 0xe000
	s_nop 0
	global_load_lds_dwordx4 v[76:77], off
	s_add_u32 m0, s32, 0xf000
	s_nop 0
	global_load_lds_dwordx4 v[80:81], off
	v_lshl_add_u64 v[66:67], v[66:67], 0, 64
	v_lshl_add_u64 v[66:67], v[66:67], 0, 64
	v_lshl_add_u64 v[70:71], v[70:71], 0, 64
	v_lshl_add_u64 v[70:71], v[70:71], 0, 64
	v_lshl_add_u64 v[74:75], v[74:75], 0, 64
	v_lshl_add_u64 v[74:75], v[74:75], 0, 64
	v_lshl_add_u64 v[78:79], v[78:79], 0, 64
	v_lshl_add_u64 v[78:79], v[78:79], 0, 64
	v_lshl_add_u64 v[68:69], v[68:69], 0, 64
	v_lshl_add_u64 v[68:69], v[68:69], 0, 64
	v_lshl_add_u64 v[72:73], v[72:73], 0, 64
	v_lshl_add_u64 v[72:73], v[72:73], 0, 64
	v_lshl_add_u64 v[76:77], v[76:77], 0, 64
	v_lshl_add_u64 v[76:77], v[76:77], 0, 64
	v_lshl_add_u64 v[80:81], v[80:81], 0, 64
	v_lshl_add_u64 v[80:81], v[80:81], 0, 64
	v_mfma_f32_32x32x16_bf16 v[50:65], v[162:165], v[182:185], v[50:65]
	v_mfma_f32_32x32x16_bf16 v[18:33], v[162:165], v[186:189], v[18:33]
	v_mfma_f32_32x32x16_bf16 v[34:49], v[166:169], v[182:185], v[34:49]
	v_mfma_f32_32x32x16_bf16 v[2:17], v[166:169], v[186:189], v[2:17]
	v_mfma_f32_32x32x16_bf16 v[50:65], v[190:193], v[198:201], v[50:65]
	v_mfma_f32_32x32x16_bf16 v[18:33], v[190:193], v[202:205], v[18:33]
	v_mfma_f32_32x32x16_bf16 v[34:49], v[194:197], v[198:201], v[34:49]
	v_mfma_f32_32x32x16_bf16 v[2:17], v[194:197], v[202:205], v[2:17]
	ds_read_b128 v[162:165], v91
	ds_read_b128 v[166:169], v92 offset:32768
	ds_read_b128 v[182:185], v91 offset:4096
	ds_read_b128 v[186:189], v92 offset:36864
	ds_read_b128 v[190:193], v93
	ds_read_b128 v[194:197], v90 offset:32768
	ds_read_b128 v[198:201], v93 offset:4096
	ds_read_b128 v[202:205], v90 offset:36864
	s_waitcnt lgkmcnt(6)
	v_mfma_f32_32x32x16_bf16 v[50:65], v[162:165], v[166:169], v[50:65]
	s_waitcnt lgkmcnt(4)
	v_mfma_f32_32x32x16_bf16 v[18:33], v[162:165], v[186:189], v[18:33]
	v_mfma_f32_32x32x16_bf16 v[34:49], v[182:185], v[166:169], v[34:49]
	v_mfma_f32_32x32x16_bf16 v[2:17], v[182:185], v[186:189], v[2:17]
	ds_read_b128 v[162:165], v89
	ds_read_b128 v[166:169], v89 offset:4096
	ds_read_b128 v[182:185], v88 offset:32768
	ds_read_b128 v[186:189], v88 offset:36864
	s_waitcnt lgkmcnt(6)
	v_mfma_f32_32x32x16_bf16 v[50:65], v[190:193], v[194:197], v[50:65]
	s_waitcnt lgkmcnt(4)
	v_mfma_f32_32x32x16_bf16 v[18:33], v[190:193], v[202:205], v[18:33]
	v_mfma_f32_32x32x16_bf16 v[34:49], v[198:201], v[194:197], v[34:49]
	v_mfma_f32_32x32x16_bf16 v[2:17], v[198:201], v[202:205], v[2:17]
	ds_read_b128 v[190:193], v87
	ds_read_b128 v[194:197], v87 offset:4096
	ds_read_b128 v[198:201], v86 offset:32768
	ds_read_b128 v[202:205], v86 offset:36864
	s_waitcnt vmcnt(0)
	s_waitcnt lgkmcnt(0)
	s_barrier
	s_add_u32 m0, s32, 0x0
	s_nop 0
	global_load_lds_dwordx4 v[66:67], off
	s_add_u32 m0, s32, 0x1000
	s_nop 0
	global_load_lds_dwordx4 v[70:71], off
	s_add_u32 m0, s32, 0x2000
	s_nop 0
	global_load_lds_dwordx4 v[74:75], off
	s_add_u32 m0, s32, 0x3000
	s_nop 0
	global_load_lds_dwordx4 v[78:79], off
	s_add_u32 m0, s32, 0x8000
	s_nop 0
	global_load_lds_dwordx4 v[68:69], off
	s_add_u32 m0, s32, 0x9000
	s_nop 0
	global_load_lds_dwordx4 v[72:73], off
	s_add_u32 m0, s32, 0xa000
	s_nop 0
	global_load_lds_dwordx4 v[76:77], off
	s_add_u32 m0, s32, 0xb000
	s_nop 0
	global_load_lds_dwordx4 v[80:81], off
	v_lshl_add_u64 v[66:67], v[66:67], 0, 64
	v_lshl_add_u64 v[66:67], v[66:67], 0, 64
	v_lshl_add_u64 v[70:71], v[70:71], 0, 64
	v_lshl_add_u64 v[70:71], v[70:71], 0, 64
	v_lshl_add_u64 v[74:75], v[74:75], 0, 64
	v_lshl_add_u64 v[74:75], v[74:75], 0, 64
	v_lshl_add_u64 v[78:79], v[78:79], 0, 64
	v_lshl_add_u64 v[78:79], v[78:79], 0, 64
	v_lshl_add_u64 v[68:69], v[68:69], 0, 64
	v_lshl_add_u64 v[68:69], v[68:69], 0, 64
	v_lshl_add_u64 v[72:73], v[72:73], 0, 64
	v_lshl_add_u64 v[72:73], v[72:73], 0, 64
	v_lshl_add_u64 v[76:77], v[76:77], 0, 64
	v_lshl_add_u64 v[76:77], v[76:77], 0, 64
	v_lshl_add_u64 v[80:81], v[80:81], 0, 64
	v_lshl_add_u64 v[80:81], v[80:81], 0, 64
	v_mfma_f32_32x32x16_bf16 v[50:65], v[162:165], v[182:185], v[50:65]
	v_mfma_f32_32x32x16_bf16 v[18:33], v[162:165], v[186:189], v[18:33]
	v_mfma_f32_32x32x16_bf16 v[34:49], v[166:169], v[182:185], v[34:49]
	v_mfma_f32_32x32x16_bf16 v[2:17], v[166:169], v[186:189], v[2:17]
	v_mfma_f32_32x32x16_bf16 v[50:65], v[190:193], v[198:201], v[50:65]
	v_mfma_f32_32x32x16_bf16 v[18:33], v[190:193], v[202:205], v[18:33]
	v_mfma_f32_32x32x16_bf16 v[34:49], v[194:197], v[198:201], v[34:49]
	v_mfma_f32_32x32x16_bf16 v[2:17], v[194:197], v[202:205], v[2:17]
	ds_read_b128 v[162:165], v91 offset:16384
	ds_read_b128 v[166:169], v92 offset:49152
	ds_read_b128 v[182:185], v91 offset:20480
	ds_read_b128 v[186:189], v92 offset:53248
	ds_read_b128 v[190:193], v93 offset:16384
	ds_read_b128 v[194:197], v90 offset:49152
	ds_read_b128 v[198:201], v93 offset:20480
	ds_read_b128 v[202:205], v90 offset:53248
	s_waitcnt lgkmcnt(6)
	v_mfma_f32_32x32x16_bf16 v[50:65], v[162:165], v[166:169], v[50:65]
	s_waitcnt lgkmcnt(4)
	v_mfma_f32_32x32x16_bf16 v[18:33], v[162:165], v[186:189], v[18:33]
	v_mfma_f32_32x32x16_bf16 v[34:49], v[182:185], v[166:169], v[34:49]
	v_mfma_f32_32x32x16_bf16 v[2:17], v[182:185], v[186:189], v[2:17]
	ds_read_b128 v[162:165], v89 offset:16384
	ds_read_b128 v[166:169], v89 offset:20480
	ds_read_b128 v[182:185], v88 offset:49152
	ds_read_b128 v[186:189], v88 offset:53248
	s_waitcnt lgkmcnt(6)
	v_mfma_f32_32x32x16_bf16 v[50:65], v[190:193], v[194:197], v[50:65]
	s_waitcnt lgkmcnt(4)
	v_mfma_f32_32x32x16_bf16 v[18:33], v[190:193], v[202:205], v[18:33]
	v_mfma_f32_32x32x16_bf16 v[34:49], v[198:201], v[194:197], v[34:49]
	v_mfma_f32_32x32x16_bf16 v[2:17], v[198:201], v[202:205], v[2:17]
	ds_read_b128 v[190:193], v87 offset:16384
	ds_read_b128 v[194:197], v87 offset:20480
	ds_read_b128 v[198:201], v86 offset:49152
	ds_read_b128 v[202:205], v86 offset:53248
	s_waitcnt vmcnt(0)
	s_waitcnt lgkmcnt(0)
	s_barrier
	s_add_u32 m0, s32, 0x4000
	s_nop 0
	global_load_lds_dwordx4 v[66:67], off
	s_add_u32 m0, s32, 0x5000
	s_nop 0
	global_load_lds_dwordx4 v[70:71], off
	s_add_u32 m0, s32, 0x6000
	s_nop 0
	global_load_lds_dwordx4 v[74:75], off
	s_add_u32 m0, s32, 0x7000
	s_nop 0
	global_load_lds_dwordx4 v[78:79], off
	s_add_u32 m0, s32, 0xc000
	s_nop 0
	global_load_lds_dwordx4 v[68:69], off
	s_add_u32 m0, s32, 0xd000
	s_nop 0
	global_load_lds_dwordx4 v[72:73], off
	s_add_u32 m0, s32, 0xe000
	s_nop 0
	global_load_lds_dwordx4 v[76:77], off
	s_add_u32 m0, s32, 0xf000
	s_nop 0
	global_load_lds_dwordx4 v[80:81], off
	v_lshl_add_u64 v[66:67], v[66:67], 0, 64
	v_lshl_add_u64 v[66:67], v[66:67], 0, 64
	v_lshl_add_u64 v[70:71], v[70:71], 0, 64
	v_lshl_add_u64 v[70:71], v[70:71], 0, 64
	v_lshl_add_u64 v[74:75], v[74:75], 0, 64
	v_lshl_add_u64 v[74:75], v[74:75], 0, 64
	v_lshl_add_u64 v[78:79], v[78:79], 0, 64
	v_lshl_add_u64 v[78:79], v[78:79], 0, 64
	v_lshl_add_u64 v[68:69], v[68:69], 0, 64
	v_lshl_add_u64 v[68:69], v[68:69], 0, 64
	v_lshl_add_u64 v[72:73], v[72:73], 0, 64
	v_lshl_add_u64 v[72:73], v[72:73], 0, 64
	v_lshl_add_u64 v[76:77], v[76:77], 0, 64
	v_lshl_add_u64 v[76:77], v[76:77], 0, 64
	v_lshl_add_u64 v[80:81], v[80:81], 0, 64
	v_lshl_add_u64 v[80:81], v[80:81], 0, 64
	v_mfma_f32_32x32x16_bf16 v[50:65], v[162:165], v[182:185], v[50:65]
	v_mfma_f32_32x32x16_bf16 v[18:33], v[162:165], v[186:189], v[18:33]
	v_mfma_f32_32x32x16_bf16 v[34:49], v[166:169], v[182:185], v[34:49]
	v_mfma_f32_32x32x16_bf16 v[2:17], v[166:169], v[186:189], v[2:17]
	v_mfma_f32_32x32x16_bf16 v[50:65], v[190:193], v[198:201], v[50:65]
	v_mfma_f32_32x32x16_bf16 v[18:33], v[190:193], v[202:205], v[18:33]
	v_mfma_f32_32x32x16_bf16 v[34:49], v[194:197], v[198:201], v[34:49]
	v_mfma_f32_32x32x16_bf16 v[2:17], v[194:197], v[202:205], v[2:17]
	ds_read_b128 v[162:165], v91
	ds_read_b128 v[166:169], v92 offset:32768
	ds_read_b128 v[182:185], v91 offset:4096
	ds_read_b128 v[186:189], v92 offset:36864
	ds_read_b128 v[190:193], v93
	ds_read_b128 v[194:197], v90 offset:32768
	ds_read_b128 v[198:201], v93 offset:4096
	ds_read_b128 v[202:205], v90 offset:36864
	s_waitcnt lgkmcnt(6)
	v_mfma_f32_32x32x16_bf16 v[50:65], v[162:165], v[166:169], v[50:65]
	s_waitcnt lgkmcnt(4)
	v_mfma_f32_32x32x16_bf16 v[18:33], v[162:165], v[186:189], v[18:33]
	v_mfma_f32_32x32x16_bf16 v[34:49], v[182:185], v[166:169], v[34:49]
	v_mfma_f32_32x32x16_bf16 v[2:17], v[182:185], v[186:189], v[2:17]
	ds_read_b128 v[162:165], v89
	ds_read_b128 v[166:169], v89 offset:4096
	ds_read_b128 v[182:185], v88 offset:32768
	ds_read_b128 v[186:189], v88 offset:36864
	s_waitcnt lgkmcnt(6)
	v_mfma_f32_32x32x16_bf16 v[50:65], v[190:193], v[194:197], v[50:65]
	s_waitcnt lgkmcnt(4)
	v_mfma_f32_32x32x16_bf16 v[18:33], v[190:193], v[202:205], v[18:33]
	v_mfma_f32_32x32x16_bf16 v[34:49], v[198:201], v[194:197], v[34:49]
	v_mfma_f32_32x32x16_bf16 v[2:17], v[198:201], v[202:205], v[2:17]
	ds_read_b128 v[190:193], v87
	ds_read_b128 v[194:197], v87 offset:4096
	ds_read_b128 v[198:201], v86 offset:32768
	ds_read_b128 v[202:205], v86 offset:36864
	s_waitcnt vmcnt(0)
	s_waitcnt lgkmcnt(0)
	s_barrier
	s_add_u32 m0, s32, 0x0
	s_nop 0
	global_load_lds_dwordx4 v[66:67], off
	s_add_u32 m0, s32, 0x1000
	s_nop 0
	global_load_lds_dwordx4 v[70:71], off
	s_add_u32 m0, s32, 0x2000
	s_nop 0
	global_load_lds_dwordx4 v[74:75], off
	s_add_u32 m0, s32, 0x3000
	s_nop 0
	global_load_lds_dwordx4 v[78:79], off
	s_add_u32 m0, s32, 0x8000
	s_nop 0
	global_load_lds_dwordx4 v[68:69], off
	s_add_u32 m0, s32, 0x9000
	s_nop 0
	global_load_lds_dwordx4 v[72:73], off
	s_add_u32 m0, s32, 0xa000
	s_nop 0
	global_load_lds_dwordx4 v[76:77], off
	s_add_u32 m0, s32, 0xb000
	s_nop 0
	global_load_lds_dwordx4 v[80:81], off
	v_lshl_add_u64 v[66:67], v[66:67], 0, 64
	v_lshl_add_u64 v[66:67], v[66:67], 0, 64
	v_lshl_add_u64 v[70:71], v[70:71], 0, 64
	v_lshl_add_u64 v[70:71], v[70:71], 0, 64
	v_lshl_add_u64 v[74:75], v[74:75], 0, 64
	v_lshl_add_u64 v[74:75], v[74:75], 0, 64
	v_lshl_add_u64 v[78:79], v[78:79], 0, 64
	v_lshl_add_u64 v[78:79], v[78:79], 0, 64
	v_lshl_add_u64 v[68:69], v[68:69], 0, 64
	v_lshl_add_u64 v[68:69], v[68:69], 0, 64
	v_lshl_add_u64 v[72:73], v[72:73], 0, 64
	v_lshl_add_u64 v[72:73], v[72:73], 0, 64
	v_lshl_add_u64 v[76:77], v[76:77], 0, 64
	v_lshl_add_u64 v[76:77], v[76:77], 0, 64
	v_lshl_add_u64 v[80:81], v[80:81], 0, 64
	v_lshl_add_u64 v[80:81], v[80:81], 0, 64
	v_mfma_f32_32x32x16_bf16 v[50:65], v[162:165], v[182:185], v[50:65]
	v_mfma_f32_32x32x16_bf16 v[18:33], v[162:165], v[186:189], v[18:33]
	v_mfma_f32_32x32x16_bf16 v[34:49], v[166:169], v[182:185], v[34:49]
	v_mfma_f32_32x32x16_bf16 v[2:17], v[166:169], v[186:189], v[2:17]
	v_mfma_f32_32x32x16_bf16 v[50:65], v[190:193], v[198:201], v[50:65]
	v_mfma_f32_32x32x16_bf16 v[18:33], v[190:193], v[202:205], v[18:33]
	v_mfma_f32_32x32x16_bf16 v[34:49], v[194:197], v[198:201], v[34:49]
	v_mfma_f32_32x32x16_bf16 v[2:17], v[194:197], v[202:205], v[2:17]
	ds_read_b128 v[162:165], v91 offset:16384
	ds_read_b128 v[166:169], v92 offset:49152
	ds_read_b128 v[182:185], v91 offset:20480
	ds_read_b128 v[186:189], v92 offset:53248
	ds_read_b128 v[190:193], v93 offset:16384
	ds_read_b128 v[194:197], v90 offset:49152
	ds_read_b128 v[198:201], v93 offset:20480
	ds_read_b128 v[202:205], v90 offset:53248
	s_waitcnt lgkmcnt(6)
	v_mfma_f32_32x32x16_bf16 v[50:65], v[162:165], v[166:169], v[50:65]
	s_waitcnt lgkmcnt(4)
	v_mfma_f32_32x32x16_bf16 v[18:33], v[162:165], v[186:189], v[18:33]
	v_mfma_f32_32x32x16_bf16 v[34:49], v[182:185], v[166:169], v[34:49]
	v_mfma_f32_32x32x16_bf16 v[2:17], v[182:185], v[186:189], v[2:17]
	ds_read_b128 v[162:165], v89 offset:16384
	ds_read_b128 v[166:169], v89 offset:20480
	ds_read_b128 v[182:185], v88 offset:49152
	ds_read_b128 v[186:189], v88 offset:53248
	s_waitcnt lgkmcnt(6)
	v_mfma_f32_32x32x16_bf16 v[50:65], v[190:193], v[194:197], v[50:65]
	s_waitcnt lgkmcnt(4)
	v_mfma_f32_32x32x16_bf16 v[18:33], v[190:193], v[202:205], v[18:33]
	v_mfma_f32_32x32x16_bf16 v[34:49], v[198:201], v[194:197], v[34:49]
	v_mfma_f32_32x32x16_bf16 v[2:17], v[198:201], v[202:205], v[2:17]
	ds_read_b128 v[190:193], v87 offset:16384
	ds_read_b128 v[194:197], v87 offset:20480
	ds_read_b128 v[198:201], v86 offset:49152
	ds_read_b128 v[202:205], v86 offset:53248
	s_waitcnt vmcnt(0)
	s_waitcnt lgkmcnt(0)
	s_barrier
	s_add_u32 m0, s32, 0x4000
	s_nop 0
	global_load_lds_dwordx4 v[66:67], off
	s_add_u32 m0, s32, 0x5000
	s_nop 0
	global_load_lds_dwordx4 v[70:71], off
	s_add_u32 m0, s32, 0x6000
	s_nop 0
	global_load_lds_dwordx4 v[74:75], off
	s_add_u32 m0, s32, 0x7000
	s_nop 0
	global_load_lds_dwordx4 v[78:79], off
	s_add_u32 m0, s32, 0xc000
	s_nop 0
	global_load_lds_dwordx4 v[68:69], off
	s_add_u32 m0, s32, 0xd000
	s_nop 0
	global_load_lds_dwordx4 v[72:73], off
	s_add_u32 m0, s32, 0xe000
	s_nop 0
	global_load_lds_dwordx4 v[76:77], off
	s_add_u32 m0, s32, 0xf000
	s_nop 0
	global_load_lds_dwordx4 v[80:81], off
	v_lshl_add_u64 v[66:67], v[66:67], 0, 64
	v_lshl_add_u64 v[66:67], v[66:67], 0, 64
	v_lshl_add_u64 v[70:71], v[70:71], 0, 64
	v_lshl_add_u64 v[70:71], v[70:71], 0, 64
	v_lshl_add_u64 v[74:75], v[74:75], 0, 64
	v_lshl_add_u64 v[74:75], v[74:75], 0, 64
	v_lshl_add_u64 v[78:79], v[78:79], 0, 64
	v_lshl_add_u64 v[78:79], v[78:79], 0, 64
	v_lshl_add_u64 v[68:69], v[68:69], 0, 64
	v_lshl_add_u64 v[68:69], v[68:69], 0, 64
	v_lshl_add_u64 v[72:73], v[72:73], 0, 64
	v_lshl_add_u64 v[72:73], v[72:73], 0, 64
	v_lshl_add_u64 v[76:77], v[76:77], 0, 64
	v_lshl_add_u64 v[76:77], v[76:77], 0, 64
	v_lshl_add_u64 v[80:81], v[80:81], 0, 64
	v_lshl_add_u64 v[80:81], v[80:81], 0, 64
	v_mfma_f32_32x32x16_bf16 v[50:65], v[162:165], v[182:185], v[50:65]
	v_mfma_f32_32x32x16_bf16 v[18:33], v[162:165], v[186:189], v[18:33]
	v_mfma_f32_32x32x16_bf16 v[34:49], v[166:169], v[182:185], v[34:49]
	v_mfma_f32_32x32x16_bf16 v[2:17], v[166:169], v[186:189], v[2:17]
	v_mfma_f32_32x32x16_bf16 v[50:65], v[190:193], v[198:201], v[50:65]
	v_mfma_f32_32x32x16_bf16 v[18:33], v[190:193], v[202:205], v[18:33]
	v_mfma_f32_32x32x16_bf16 v[34:49], v[194:197], v[198:201], v[34:49]
	v_mfma_f32_32x32x16_bf16 v[2:17], v[194:197], v[202:205], v[2:17]
	ds_read_b128 v[162:165], v91
	ds_read_b128 v[166:169], v92 offset:32768
	ds_read_b128 v[182:185], v91 offset:4096
	ds_read_b128 v[186:189], v92 offset:36864
	ds_read_b128 v[190:193], v93
	ds_read_b128 v[194:197], v90 offset:32768
	ds_read_b128 v[198:201], v93 offset:4096
	ds_read_b128 v[202:205], v90 offset:36864
	s_waitcnt lgkmcnt(6)
	v_mfma_f32_32x32x16_bf16 v[50:65], v[162:165], v[166:169], v[50:65]
	s_waitcnt lgkmcnt(4)
	v_mfma_f32_32x32x16_bf16 v[18:33], v[162:165], v[186:189], v[18:33]
	v_mfma_f32_32x32x16_bf16 v[34:49], v[182:185], v[166:169], v[34:49]
	v_mfma_f32_32x32x16_bf16 v[2:17], v[182:185], v[186:189], v[2:17]
	ds_read_b128 v[162:165], v89
	ds_read_b128 v[166:169], v89 offset:4096
	ds_read_b128 v[182:185], v88 offset:32768
	ds_read_b128 v[186:189], v88 offset:36864
	s_waitcnt lgkmcnt(6)
	v_mfma_f32_32x32x16_bf16 v[50:65], v[190:193], v[194:197], v[50:65]
	s_waitcnt lgkmcnt(4)
	v_mfma_f32_32x32x16_bf16 v[18:33], v[190:193], v[202:205], v[18:33]
	v_mfma_f32_32x32x16_bf16 v[34:49], v[198:201], v[194:197], v[34:49]
	v_mfma_f32_32x32x16_bf16 v[2:17], v[198:201], v[202:205], v[2:17]
	ds_read_b128 v[190:193], v87
	ds_read_b128 v[194:197], v87 offset:4096
	ds_read_b128 v[198:201], v86 offset:32768
	ds_read_b128 v[202:205], v86 offset:36864
	s_waitcnt vmcnt(0)
	s_waitcnt lgkmcnt(0)
	s_barrier
	s_add_u32 m0, s32, 0x0
	s_nop 0
	global_load_lds_dwordx4 v[66:67], off
	s_add_u32 m0, s32, 0x1000
	s_nop 0
	global_load_lds_dwordx4 v[70:71], off
	s_add_u32 m0, s32, 0x2000
	s_nop 0
	global_load_lds_dwordx4 v[74:75], off
	s_add_u32 m0, s32, 0x3000
	s_nop 0
	global_load_lds_dwordx4 v[78:79], off
	s_add_u32 m0, s32, 0x8000
	s_nop 0
	global_load_lds_dwordx4 v[68:69], off
	s_add_u32 m0, s32, 0x9000
	s_nop 0
	global_load_lds_dwordx4 v[72:73], off
	s_add_u32 m0, s32, 0xa000
	s_nop 0
	global_load_lds_dwordx4 v[76:77], off
	s_add_u32 m0, s32, 0xb000
	s_nop 0
	global_load_lds_dwordx4 v[80:81], off
	v_lshl_add_u64 v[66:67], v[66:67], 0, 64
	v_lshl_add_u64 v[66:67], v[66:67], 0, 64
	v_lshl_add_u64 v[70:71], v[70:71], 0, 64
	v_lshl_add_u64 v[70:71], v[70:71], 0, 64
	v_lshl_add_u64 v[74:75], v[74:75], 0, 64
	v_lshl_add_u64 v[74:75], v[74:75], 0, 64
	v_lshl_add_u64 v[78:79], v[78:79], 0, 64
	v_lshl_add_u64 v[78:79], v[78:79], 0, 64
	v_lshl_add_u64 v[68:69], v[68:69], 0, 64
	v_lshl_add_u64 v[68:69], v[68:69], 0, 64
	v_lshl_add_u64 v[72:73], v[72:73], 0, 64
	v_lshl_add_u64 v[72:73], v[72:73], 0, 64
	v_lshl_add_u64 v[76:77], v[76:77], 0, 64
	v_lshl_add_u64 v[76:77], v[76:77], 0, 64
	v_lshl_add_u64 v[80:81], v[80:81], 0, 64
	v_lshl_add_u64 v[80:81], v[80:81], 0, 64
	v_mfma_f32_32x32x16_bf16 v[50:65], v[162:165], v[182:185], v[50:65]
	v_mfma_f32_32x32x16_bf16 v[18:33], v[162:165], v[186:189], v[18:33]
	v_mfma_f32_32x32x16_bf16 v[34:49], v[166:169], v[182:185], v[34:49]
	v_mfma_f32_32x32x16_bf16 v[2:17], v[166:169], v[186:189], v[2:17]
	v_mfma_f32_32x32x16_bf16 v[50:65], v[190:193], v[198:201], v[50:65]
	v_mfma_f32_32x32x16_bf16 v[18:33], v[190:193], v[202:205], v[18:33]
	v_mfma_f32_32x32x16_bf16 v[34:49], v[194:197], v[198:201], v[34:49]
	v_mfma_f32_32x32x16_bf16 v[2:17], v[194:197], v[202:205], v[2:17]
	ds_read_b128 v[162:165], v91 offset:16384
	ds_read_b128 v[166:169], v92 offset:49152
	ds_read_b128 v[182:185], v91 offset:20480
	ds_read_b128 v[186:189], v92 offset:53248
	ds_read_b128 v[190:193], v93 offset:16384
	ds_read_b128 v[194:197], v90 offset:49152
	ds_read_b128 v[198:201], v93 offset:20480
	ds_read_b128 v[202:205], v90 offset:53248
	s_waitcnt lgkmcnt(6)
	v_mfma_f32_32x32x16_bf16 v[50:65], v[162:165], v[166:169], v[50:65]
	s_waitcnt lgkmcnt(4)
	v_mfma_f32_32x32x16_bf16 v[18:33], v[162:165], v[186:189], v[18:33]
	v_mfma_f32_32x32x16_bf16 v[34:49], v[182:185], v[166:169], v[34:49]
	v_mfma_f32_32x32x16_bf16 v[2:17], v[182:185], v[186:189], v[2:17]
	ds_read_b128 v[162:165], v89 offset:16384
	ds_read_b128 v[166:169], v89 offset:20480
	ds_read_b128 v[182:185], v88 offset:49152
	ds_read_b128 v[186:189], v88 offset:53248
	s_waitcnt lgkmcnt(6)
	v_mfma_f32_32x32x16_bf16 v[50:65], v[190:193], v[194:197], v[50:65]
	s_waitcnt lgkmcnt(4)
	v_mfma_f32_32x32x16_bf16 v[18:33], v[190:193], v[202:205], v[18:33]
	v_mfma_f32_32x32x16_bf16 v[34:49], v[198:201], v[194:197], v[34:49]
	v_mfma_f32_32x32x16_bf16 v[2:17], v[198:201], v[202:205], v[2:17]
	ds_read_b128 v[190:193], v87 offset:16384
	ds_read_b128 v[194:197], v87 offset:20480
	ds_read_b128 v[198:201], v86 offset:49152
	ds_read_b128 v[202:205], v86 offset:53248
	s_waitcnt vmcnt(0)
	s_waitcnt lgkmcnt(0)
	s_barrier
	s_add_u32 m0, s32, 0x4000
	s_nop 0
	global_load_lds_dwordx4 v[66:67], off
	s_add_u32 m0, s32, 0x5000
	s_nop 0
	global_load_lds_dwordx4 v[70:71], off
	s_add_u32 m0, s32, 0x6000
	s_nop 0
	global_load_lds_dwordx4 v[74:75], off
	s_add_u32 m0, s32, 0x7000
	s_nop 0
	global_load_lds_dwordx4 v[78:79], off
	s_add_u32 m0, s32, 0xc000
	s_nop 0
	global_load_lds_dwordx4 v[68:69], off
	s_add_u32 m0, s32, 0xd000
	s_nop 0
	global_load_lds_dwordx4 v[72:73], off
	s_add_u32 m0, s32, 0xe000
	s_nop 0
	global_load_lds_dwordx4 v[76:77], off
	s_add_u32 m0, s32, 0xf000
	s_nop 0
	global_load_lds_dwordx4 v[80:81], off
	v_lshl_add_u64 v[66:67], v[66:67], 0, 64
	v_lshl_add_u64 v[66:67], v[66:67], 0, 64
	v_lshl_add_u64 v[70:71], v[70:71], 0, 64
	v_lshl_add_u64 v[70:71], v[70:71], 0, 64
	v_lshl_add_u64 v[74:75], v[74:75], 0, 64
	v_lshl_add_u64 v[74:75], v[74:75], 0, 64
	v_lshl_add_u64 v[78:79], v[78:79], 0, 64
	v_lshl_add_u64 v[78:79], v[78:79], 0, 64
	v_lshl_add_u64 v[68:69], v[68:69], 0, 64
	v_lshl_add_u64 v[68:69], v[68:69], 0, 64
	v_lshl_add_u64 v[72:73], v[72:73], 0, 64
	v_lshl_add_u64 v[72:73], v[72:73], 0, 64
	v_lshl_add_u64 v[76:77], v[76:77], 0, 64
	v_lshl_add_u64 v[76:77], v[76:77], 0, 64
	v_lshl_add_u64 v[80:81], v[80:81], 0, 64
	v_lshl_add_u64 v[80:81], v[80:81], 0, 64
	v_mfma_f32_32x32x16_bf16 v[50:65], v[162:165], v[182:185], v[50:65]
	v_mfma_f32_32x32x16_bf16 v[18:33], v[162:165], v[186:189], v[18:33]
	v_mfma_f32_32x32x16_bf16 v[34:49], v[166:169], v[182:185], v[34:49]
	v_mfma_f32_32x32x16_bf16 v[2:17], v[166:169], v[186:189], v[2:17]
	v_mfma_f32_32x32x16_bf16 v[50:65], v[190:193], v[198:201], v[50:65]
	v_mfma_f32_32x32x16_bf16 v[18:33], v[190:193], v[202:205], v[18:33]
	v_mfma_f32_32x32x16_bf16 v[34:49], v[194:197], v[198:201], v[34:49]
	v_mfma_f32_32x32x16_bf16 v[2:17], v[194:197], v[202:205], v[2:17]
	ds_read_b128 v[162:165], v91
	ds_read_b128 v[166:169], v92 offset:32768
	ds_read_b128 v[182:185], v91 offset:4096
	ds_read_b128 v[186:189], v92 offset:36864
	ds_read_b128 v[190:193], v93
	ds_read_b128 v[194:197], v90 offset:32768
	ds_read_b128 v[198:201], v93 offset:4096
	ds_read_b128 v[202:205], v90 offset:36864
	s_waitcnt lgkmcnt(6)
	v_mfma_f32_32x32x16_bf16 v[50:65], v[162:165], v[166:169], v[50:65]
	s_waitcnt lgkmcnt(4)
	v_mfma_f32_32x32x16_bf16 v[18:33], v[162:165], v[186:189], v[18:33]
	v_mfma_f32_32x32x16_bf16 v[34:49], v[182:185], v[166:169], v[34:49]
	v_mfma_f32_32x32x16_bf16 v[2:17], v[182:185], v[186:189], v[2:17]
	ds_read_b128 v[162:165], v89
	ds_read_b128 v[166:169], v89 offset:4096
	ds_read_b128 v[182:185], v88 offset:32768
	ds_read_b128 v[186:189], v88 offset:36864
	s_waitcnt lgkmcnt(6)
	v_mfma_f32_32x32x16_bf16 v[50:65], v[190:193], v[194:197], v[50:65]
	s_waitcnt lgkmcnt(4)
	v_mfma_f32_32x32x16_bf16 v[18:33], v[190:193], v[202:205], v[18:33]
	v_mfma_f32_32x32x16_bf16 v[34:49], v[198:201], v[194:197], v[34:49]
	v_mfma_f32_32x32x16_bf16 v[2:17], v[198:201], v[202:205], v[2:17]
	ds_read_b128 v[190:193], v87
	ds_read_b128 v[194:197], v87 offset:4096
	ds_read_b128 v[198:201], v86 offset:32768
	ds_read_b128 v[202:205], v86 offset:36864
	s_waitcnt vmcnt(0)
	s_waitcnt lgkmcnt(0)
	s_barrier
	s_add_u32 m0, s32, 0x0
	s_nop 0
	global_load_lds_dwordx4 v[66:67], off
	s_add_u32 m0, s32, 0x1000
	s_nop 0
	global_load_lds_dwordx4 v[70:71], off
	s_add_u32 m0, s32, 0x2000
	s_nop 0
	global_load_lds_dwordx4 v[74:75], off
	s_add_u32 m0, s32, 0x3000
	s_nop 0
	global_load_lds_dwordx4 v[78:79], off
	s_add_u32 m0, s32, 0x8000
	s_nop 0
	global_load_lds_dwordx4 v[68:69], off
	s_add_u32 m0, s32, 0x9000
	s_nop 0
	global_load_lds_dwordx4 v[72:73], off
	s_add_u32 m0, s32, 0xa000
	s_nop 0
	global_load_lds_dwordx4 v[76:77], off
	s_add_u32 m0, s32, 0xb000
	s_nop 0
	global_load_lds_dwordx4 v[80:81], off
	v_lshl_add_u64 v[66:67], v[66:67], 0, 64
	v_lshl_add_u64 v[66:67], v[66:67], 0, 64
	v_lshl_add_u64 v[70:71], v[70:71], 0, 64
	v_lshl_add_u64 v[70:71], v[70:71], 0, 64
	v_lshl_add_u64 v[74:75], v[74:75], 0, 64
	v_lshl_add_u64 v[74:75], v[74:75], 0, 64
	v_lshl_add_u64 v[78:79], v[78:79], 0, 64
	v_lshl_add_u64 v[78:79], v[78:79], 0, 64
	v_lshl_add_u64 v[68:69], v[68:69], 0, 64
	v_lshl_add_u64 v[68:69], v[68:69], 0, 64
	v_lshl_add_u64 v[72:73], v[72:73], 0, 64
	v_lshl_add_u64 v[72:73], v[72:73], 0, 64
	v_lshl_add_u64 v[76:77], v[76:77], 0, 64
	v_lshl_add_u64 v[76:77], v[76:77], 0, 64
	v_lshl_add_u64 v[80:81], v[80:81], 0, 64
	v_lshl_add_u64 v[80:81], v[80:81], 0, 64
	s_nop 0
	s_nop 0
	s_nop 0
	s_nop 0
	s_nop 0
	s_nop 0
	s_nop 0
	v_mfma_f32_32x32x16_bf16 v[50:65], v[162:165], v[182:185], v[50:65]
	v_mfma_f32_32x32x16_bf16 v[18:33], v[162:165], v[186:189], v[18:33]
	v_mfma_f32_32x32x16_bf16 v[34:49], v[166:169], v[182:185], v[34:49]
	v_mfma_f32_32x32x16_bf16 v[2:17], v[166:169], v[186:189], v[2:17]
	ds_read_b128 v[110:113], v91 offset:16384
	ds_read_b128 v[114:117], v91 offset:20480
	ds_read_b128 v[118:121], v92 offset:49152
	ds_read_b128 v[122:125], v92 offset:53248
	ds_read_b128 v[162:165], v93 offset:16384
	ds_read_b128 v[166:169], v93 offset:20480
	ds_read_b128 v[182:185], v90 offset:49152
	ds_read_b128 v[186:189], v90 offset:53248
	v_mfma_f32_32x32x16_bf16 v[50:65], v[190:193], v[198:201], v[50:65]
	v_mfma_f32_32x32x16_bf16 v[18:33], v[190:193], v[202:205], v[18:33]
	v_mfma_f32_32x32x16_bf16 v[34:49], v[194:197], v[198:201], v[34:49]
	v_mfma_f32_32x32x16_bf16 v[2:17], v[194:197], v[202:205], v[2:17]
	s_waitcnt lgkmcnt(5)
	v_mfma_f32_32x32x16_bf16 v[50:65], v[110:113], v[118:121], v[50:65]
	s_waitcnt lgkmcnt(4)
	v_mfma_f32_32x32x16_bf16 v[18:33], v[110:113], v[122:125], v[18:33]
	v_mfma_f32_32x32x16_bf16 v[34:49], v[114:117], v[118:121], v[34:49]
	v_mfma_f32_32x32x16_bf16 v[2:17], v[114:117], v[122:125], v[2:17]
	ds_read_b128 v[110:113], v89 offset:16384
	ds_read_b128 v[114:117], v89 offset:20480
	ds_read_b128 v[118:121], v88 offset:49152
	ds_read_b128 v[122:125], v88 offset:53248
	s_waitcnt lgkmcnt(5)
	v_mfma_f32_32x32x16_bf16 v[50:65], v[162:165], v[182:185], v[50:65]
	s_waitcnt lgkmcnt(4)
	v_mfma_f32_32x32x16_bf16 v[18:33], v[162:165], v[186:189], v[18:33]
	v_mfma_f32_32x32x16_bf16 v[34:49], v[166:169], v[182:185], v[34:49]
	v_mfma_f32_32x32x16_bf16 v[2:17], v[166:169], v[186:189], v[2:17]
	ds_read_b128 v[162:165], v87 offset:16384
	ds_read_b128 v[166:169], v87 offset:20480
	ds_read_b128 v[182:185], v86 offset:49152
	ds_read_b128 v[186:189], v86 offset:53248
	s_waitcnt lgkmcnt(5)
	v_mfma_f32_32x32x16_bf16 v[50:65], v[110:113], v[118:121], v[50:65]
	s_waitcnt vmcnt(0)
	s_waitcnt lgkmcnt(0)
	s_barrier
	s_add_u32 m0, s32, 0x4000
	s_nop 0
	global_load_lds_dwordx4 v[66:67], off
	s_add_u32 m0, s32, 0x5000
	s_nop 0
	global_load_lds_dwordx4 v[70:71], off
	s_add_u32 m0, s32, 0x6000
	s_nop 0
	global_load_lds_dwordx4 v[74:75], off
	s_add_u32 m0, s32, 0x7000
	s_nop 0
	global_load_lds_dwordx4 v[78:79], off
	s_add_u32 m0, s32, 0xc000
	s_nop 0
	global_load_lds_dwordx4 v[68:69], off
	s_add_u32 m0, s32, 0xd000
	s_nop 0
	global_load_lds_dwordx4 v[72:73], off
	s_add_u32 m0, s32, 0xe000
	s_nop 0
	global_load_lds_dwordx4 v[76:77], off
	s_add_u32 m0, s32, 0xf000
	s_nop 0
	global_load_lds_dwordx4 v[80:81], off
	v_lshl_add_u64 v[66:67], v[66:67], 0, 64
	v_lshl_add_u64 v[66:67], v[66:67], 0, 64
	v_lshl_add_u64 v[70:71], v[70:71], 0, 64
	v_lshl_add_u64 v[70:71], v[70:71], 0, 64
	v_lshl_add_u64 v[74:75], v[74:75], 0, 64
	v_lshl_add_u64 v[74:75], v[74:75], 0, 64
	v_lshl_add_u64 v[78:79], v[78:79], 0, 64
	v_lshl_add_u64 v[78:79], v[78:79], 0, 64
	v_lshl_add_u64 v[68:69], v[68:69], 0, 64
	v_lshl_add_u64 v[68:69], v[68:69], 0, 64
	v_lshl_add_u64 v[72:73], v[72:73], 0, 64
	v_lshl_add_u64 v[72:73], v[72:73], 0, 64
	v_lshl_add_u64 v[76:77], v[76:77], 0, 64
	v_lshl_add_u64 v[76:77], v[76:77], 0, 64
	v_lshl_add_u64 v[80:81], v[80:81], 0, 64
	v_lshl_add_u64 v[80:81], v[80:81], 0, 64
	v_mfma_f32_32x32x16_bf16 v[18:33], v[110:113], v[122:125], v[18:33]
	v_mfma_f32_32x32x16_bf16 v[34:49], v[114:117], v[118:121], v[34:49]
	v_mfma_f32_32x32x16_bf16 v[2:17], v[114:117], v[122:125], v[2:17]
	ds_read_b128 v[110:113], v91
	ds_read_b128 v[114:117], v91 offset:4096
	ds_read_b128 v[118:121], v92 offset:32768
	ds_read_b128 v[122:125], v92 offset:36864
	ds_read_b128 v[126:129], v93
	ds_read_b128 v[134:137], v93 offset:4096
	ds_read_b128 v[138:141], v90 offset:32768
	ds_read_b128 v[142:145], v90 offset:36864
	v_mfma_f32_32x32x16_bf16 v[50:65], v[162:165], v[182:185], v[50:65]
	v_mfma_f32_32x32x16_bf16 v[18:33], v[162:165], v[186:189], v[18:33]
	v_mfma_f32_32x32x16_bf16 v[34:49], v[166:169], v[182:185], v[34:49]
	v_mfma_f32_32x32x16_bf16 v[2:17], v[166:169], v[186:189], v[2:17]
	s_waitcnt lgkmcnt(5)
	v_mfma_f32_32x32x16_bf16 v[50:65], v[110:113], v[118:121], v[50:65]
	s_waitcnt lgkmcnt(4)
	v_mfma_f32_32x32x16_bf16 v[18:33], v[110:113], v[122:125], v[18:33]
	v_mfma_f32_32x32x16_bf16 v[34:49], v[114:117], v[118:121], v[34:49]
	v_mfma_f32_32x32x16_bf16 v[2:17], v[114:117], v[122:125], v[2:17]
	ds_read_b128 v[110:113], v89
	ds_read_b128 v[114:117], v89 offset:4096
	ds_read_b128 v[118:121], v88 offset:32768
	ds_read_b128 v[122:125], v88 offset:36864
	s_waitcnt lgkmcnt(5)
	v_mfma_f32_32x32x16_bf16 v[50:65], v[126:129], v[138:141], v[50:65]
	s_waitcnt lgkmcnt(4)
	v_mfma_f32_32x32x16_bf16 v[18:33], v[126:129], v[142:145], v[18:33]
	v_mfma_f32_32x32x16_bf16 v[34:49], v[134:137], v[138:141], v[34:49]
	v_mfma_f32_32x32x16_bf16 v[2:17], v[134:137], v[142:145], v[2:17]
	ds_read_b128 v[126:129], v87
	ds_read_b128 v[134:137], v87 offset:4096
	ds_read_b128 v[138:141], v86 offset:32768
	ds_read_b128 v[142:145], v86 offset:36864
	s_waitcnt vmcnt(0)
	s_waitcnt lgkmcnt(0)
	s_barrier
	ds_read_b128 v[66:69], v91 offset:16384
	ds_read_b128 v[70:73], v91 offset:20480
	ds_read_b128 v[74:77], v92 offset:49152
	ds_read_b128 v[78:81], v92 offset:53248
	ds_read_b128 v[94:97], v93 offset:16384
	ds_read_b128 v[98:101], v93 offset:20480
	ds_read_b128 v[102:105], v90 offset:49152
	ds_read_b128 v[90:93], v90 offset:53248
	v_mfma_f32_32x32x16_bf16 v[50:65], v[110:113], v[118:121], v[50:65]
	v_mfma_f32_32x32x16_bf16 v[18:33], v[110:113], v[122:125], v[18:33]
	v_mfma_f32_32x32x16_bf16 v[34:49], v[114:117], v[118:121], v[34:49]
	v_mfma_f32_32x32x16_bf16 v[2:17], v[114:117], v[122:125], v[2:17]
	v_mfma_f32_32x32x16_bf16 v[50:65], v[126:129], v[138:141], v[50:65]
	v_mfma_f32_32x32x16_bf16 v[18:33], v[126:129], v[142:145], v[18:33]
	v_mfma_f32_32x32x16_bf16 v[34:49], v[134:137], v[138:141], v[34:49]
	v_mfma_f32_32x32x16_bf16 v[2:17], v[134:137], v[142:145], v[2:17]
	s_waitcnt lgkmcnt(5)
	v_mfma_f32_32x32x16_bf16 v[50:65], v[66:69], v[74:77], v[50:65]
	s_waitcnt lgkmcnt(4)
	v_mfma_f32_32x32x16_bf16 v[18:33], v[66:69], v[78:81], v[18:33]
	v_mfma_f32_32x32x16_bf16 v[34:49], v[70:73], v[74:77], v[34:49]
	v_mfma_f32_32x32x16_bf16 v[2:17], v[70:73], v[78:81], v[2:17]
	ds_read_b128 v[66:69], v89 offset:16384
	ds_read_b128 v[70:73], v89 offset:20480
	ds_read_b128 v[74:77], v88 offset:49152
	ds_read_b128 v[78:81], v88 offset:53248
	s_waitcnt lgkmcnt(5)
	v_mfma_f32_32x32x16_bf16 v[50:65], v[94:97], v[102:105], v[50:65]
	s_waitcnt lgkmcnt(4)
	v_mfma_f32_32x32x16_bf16 v[18:33], v[94:97], v[90:93], v[18:33]
	v_mfma_f32_32x32x16_bf16 v[34:49], v[98:101], v[102:105], v[34:49]
	v_mfma_f32_32x32x16_bf16 v[2:17], v[98:101], v[90:93], v[2:17]
	ds_read_b128 v[88:91], v87 offset:16384
	ds_read_b128 v[92:95], v87 offset:20480
	ds_read_b128 v[96:99], v86 offset:49152
	ds_read_b128 v[100:103], v86 offset:53248
	s_lshl_b32 s6, s34, 7
	v_lshl_add_u32 v0, v84, 6, s6
	s_min_i32 s7, s6, 0x4000
	v_lshl_or_b32 v0, v85, 2, v0
	s_movk_i32 s6, 0x4000
	s_waitcnt lgkmcnt(5)
	v_mfma_f32_32x32x16_bf16 v[50:65], v[66:69], v[74:77], v[50:65]
	v_cmp_gt_i32_e32 vcc, s6, v0
	v_readlane_b32 s36, v210, 2
	v_readlane_b32 s40, v210, 6
	s_ashr_i32 s7, s7, 12
	s_add_i32 s7, s7, s70
	s_mul_hi_i32 s8, s7, 0x6000
	s_mulk_i32 s7, 0x6000
	s_waitcnt lgkmcnt(4)
	v_mfma_f32_32x32x16_bf16 v[18:33], v[66:69], v[78:81], v[18:33]
	v_add_u32_e32 v66, 0xffffc000, v0
	v_ashrrev_i32_e32 v67, 31, v0
	v_cndmask_b32_e32 v66, v66, v0, vcc
	v_mov_b32_e32 v0, s95
	v_mov_b32_e32 v68, s89
	v_cndmask_b32_e32 v69, v0, v68, vcc
	v_mov_b32_e32 v0, s94
	v_mov_b32_e32 v68, s88
	v_mfma_f32_32x32x16_bf16 v[34:49], v[70:73], v[74:77], v[34:49]
	v_cndmask_b32_e32 v67, 0, v67, vcc
	v_cndmask_b32_e32 v68, v0, v68, vcc
	v_mov_b32_e32 v0, s40
	v_lshlrev_b64 v[66:67], 12, v[66:67]
	v_lshl_add_u64 v[134:135], v[68:69], 0, v[66:67]
	v_readlane_b32 s37, v210, 3
	v_readlane_b32 s41, v210, 7
	v_mfma_f32_32x32x16_bf16 v[2:17], v[70:73], v[78:81], v[2:17]
	v_mov_b32_e32 v70, s36
	v_cndmask_b32_e32 v0, v0, v70, vcc
	v_cndmask_b32_e64 v68, v68, v0, s[52:53]
	v_lshl_or_b32 v0, v83, 6, v82
	s_add_u32 s7, s90, s7
	v_mov_b32_e32 v70, s41
	v_mov_b32_e32 v71, s37
	v_subrev_u32_e32 v0, s5, v0
	s_addc_u32 s8, s91, s8
	v_cndmask_b32_e32 v70, v70, v71, vcc
	v_add_u32_e32 v168, s3, v0
	s_add_u32 s34, s7, 0x2000
	v_cndmask_b32_e64 v69, v69, v70, s[52:53]
	v_ashrrev_i32_e32 v169, 31, v168
	s_addc_u32 s35, s8, 0
	v_lshl_add_u64 v[66:67], v[68:69], 0, v[66:67]
	v_lshlrev_b64 v[136:137], 2, v[168:169]
	v_lshl_add_u64 v[68:69], s[34:35], 0, v[136:137]
	v_lshl_add_u64 v[66:67], v[66:67], 0, v[136:137]
	s_movk_i32 s8, 0x1000
	s_waitcnt lgkmcnt(0)
	s_barrier
	global_load_dword v0, v[68:69], off
	v_add_co_u32_e32 v68, vcc, s8, v66
	s_movk_i32 s6, 0x2000
	s_nop 0
	v_addc_co_u32_e32 v69, vcc, 0, v67, vcc
	global_load_dword v138, v[66:67], off
	v_add_co_u32_e32 v70, vcc, s6, v66
	v_readlane_b32 s38, v210, 4
	s_nop 0
	v_addc_co_u32_e32 v71, vcc, 0, v67, vcc
	global_load_dword v139, v[70:71], off offset:-4096
	global_load_dword v140, v[70:71], off
	s_movk_i32 s38, 0x3000
	v_add_co_u32_e32 v72, vcc, s38, v66
	s_mov_b32 s7, 0x8000
	s_nop 0
	v_addc_co_u32_e32 v73, vcc, 0, v67, vcc
	global_load_dword v141, v[72:73], off
	v_add_co_u32_e32 v74, vcc, s7, v66
	s_mov_b32 s36, 0x9000
	s_nop 0
	v_addc_co_u32_e32 v75, vcc, 0, v67, vcc
	v_add_co_u32_e32 v76, vcc, s36, v66
	s_mov_b32 s37, 0xa000
	s_nop 0
	v_addc_co_u32_e32 v77, vcc, 0, v67, vcc
	v_add_co_u32_e32 v78, vcc, s37, v66
	s_mov_b32 s5, 0xb000
	s_nop 0
	v_addc_co_u32_e32 v79, vcc, 0, v67, vcc
	global_load_dword v142, v[76:77], off offset:-4096
	global_load_dword v143, v[76:77], off
	v_add_co_u32_e32 v80, vcc, s5, v66
	v_readlane_b32 s39, v210, 5
	s_nop 0
	v_addc_co_u32_e32 v81, vcc, 0, v67, vcc
	v_add_co_u32_e32 v82, vcc, s10, v66
	s_mov_b32 s39, 0x11000
	s_nop 0
	v_addc_co_u32_e32 v83, vcc, 0, v67, vcc
	global_load_dword v144, v[80:81], off offset:-4096
	global_load_dword v145, v[80:81], off
	v_add_co_u32_e32 v84, vcc, s39, v66
	v_mfma_f32_32x32x16_bf16 v[50:65], v[88:91], v[96:99], v[50:65]
	s_nop 0
	v_addc_co_u32_e32 v85, vcc, 0, v67, vcc
	v_add_co_u32_e32 v86, vcc, s62, v66
	global_load_dword v146, v[84:85], off offset:-4096
	global_load_dword v147, v[84:85], off
	v_addc_co_u32_e32 v87, vcc, 0, v67, vcc
	v_mfma_f32_32x32x16_bf16 v[18:33], v[88:91], v[100:103], v[18:33]
	v_add_co_u32_e32 v88, vcc, s57, v66
	v_lshl_add_u64 v[134:135], v[134:135], 0, v[136:137]
	s_nop 0
	v_addc_co_u32_e32 v89, vcc, 0, v67, vcc
	v_add_co_u32_e32 v90, vcc, s54, v66
	v_mfma_f32_32x32x16_bf16 v[34:49], v[92:95], v[96:99], v[34:49]
	s_nop 0
	v_addc_co_u32_e32 v91, vcc, 0, v67, vcc
	global_load_dword v148, v[88:89], off offset:-4096
	global_load_dword v149, v[88:89], off
	s_add_i32 s4, s4, s66
	s_add_i32 s3, s3, s2
	s_cmp_lt_i32 s4, s59
	v_readlane_b32 s42, v210, 8
	v_mfma_f32_32x32x16_bf16 v[2:17], v[92:95], v[100:103], v[2:17]
	v_add_co_u32_e32 v92, vcc, s55, v66
	v_readlane_b32 s43, v210, 9
	s_nop 0
	v_addc_co_u32_e32 v93, vcc, 0, v67, vcc
	v_add_co_u32_e32 v94, vcc, s72, v66
	global_load_dword v150, v[92:93], off offset:-4096
	global_load_dword v151, v[92:93], off
	v_addc_co_u32_e32 v95, vcc, 0, v67, vcc
	v_add_co_u32_e32 v96, vcc, s73, v66
	s_waitcnt vmcnt(13)
	v_fmac_f32_e32 v138, v50, v0
	v_addc_co_u32_e32 v97, vcc, 0, v67, vcc
	v_add_co_u32_e32 v98, vcc, s63, v66
	global_load_dword v152, v[96:97], off offset:-4096
	global_load_dword v153, v[96:97], off
	v_addc_co_u32_e32 v99, vcc, 0, v67, vcc
	v_add_co_u32_e32 v100, vcc, s74, v66
	s_waitcnt vmcnt(14)
	v_fmac_f32_e32 v139, v51, v0
	v_addc_co_u32_e32 v101, vcc, 0, v67, vcc
	v_add_co_u32_e32 v102, vcc, s75, v66
	global_load_dword v154, v[100:101], off offset:-4096
	global_load_dword v155, v[100:101], off
	v_addc_co_u32_e32 v103, vcc, 0, v67, vcc
	v_add_co_u32_e32 v104, vcc, s76, v66
	s_waitcnt vmcnt(15)
	v_fmac_f32_e32 v140, v52, v0
	v_addc_co_u32_e32 v105, vcc, 0, v67, vcc
	v_add_co_u32_e32 v106, vcc, s77, v66
	global_load_dword v156, v[104:105], off offset:-4096
	global_load_dword v157, v[104:105], off
	v_addc_co_u32_e32 v107, vcc, 0, v67, vcc
	v_add_co_u32_e32 v108, vcc, s78, v66
	s_waitcnt vmcnt(16)
	v_fmac_f32_e32 v141, v53, v0
	v_addc_co_u32_e32 v109, vcc, 0, v67, vcc
	v_add_co_u32_e32 v110, vcc, s79, v66
	global_load_dword v158, v[108:109], off offset:-4096
	global_load_dword v159, v[108:109], off
	v_addc_co_u32_e32 v111, vcc, 0, v67, vcc
	v_add_co_u32_e32 v112, vcc, s58, v66
	s_waitcnt vmcnt(17)
	v_fmac_f32_e32 v142, v54, v0
	v_addc_co_u32_e32 v113, vcc, 0, v67, vcc
	v_add_co_u32_e32 v114, vcc, s61, v66
	global_load_dword v160, v[112:113], off offset:-4096
	global_load_dword v161, v[112:113], off
	v_addc_co_u32_e32 v115, vcc, 0, v67, vcc
	v_add_co_u32_e32 v116, vcc, s56, v66
	s_waitcnt vmcnt(18)
	v_fmac_f32_e32 v143, v55, v0
	v_addc_co_u32_e32 v117, vcc, 0, v67, vcc
	v_add_co_u32_e32 v118, vcc, s97, v66
	global_load_dword v162, v[116:117], off offset:-4096
	global_load_dword v163, v[116:117], off
	v_addc_co_u32_e32 v119, vcc, 0, v67, vcc
	v_add_co_u32_e32 v120, vcc, s9, v66
	s_waitcnt vmcnt(19)
	v_fmac_f32_e32 v144, v56, v0
	v_addc_co_u32_e32 v121, vcc, 0, v67, vcc
	v_add_co_u32_e32 v122, vcc, s69, v66
	global_load_dword v164, v[120:121], off offset:-4096
	global_load_dword v165, v[120:121], off
	v_addc_co_u32_e32 v123, vcc, 0, v67, vcc
	v_add_co_u32_e32 v124, vcc, s67, v66
	s_waitcnt vmcnt(20)
	v_fmac_f32_e32 v145, v57, v0
	v_addc_co_u32_e32 v125, vcc, 0, v67, vcc
	v_add_co_u32_e32 v126, vcc, s60, v66
	global_load_dword v166, v[124:125], off offset:-4096
	global_load_dword v167, v[124:125], off
	v_addc_co_u32_e32 v127, vcc, 0, v67, vcc
	v_add_co_u32_e32 v128, vcc, s33, v66
	s_waitcnt vmcnt(21)
	v_fmac_f32_e32 v146, v58, v0
	v_addc_co_u32_e32 v129, vcc, 0, v67, vcc
	global_load_dword v169, v[128:129], off offset:-4096
	global_load_dword v181, v[128:129], off
	v_add_co_u32_e32 v50, vcc, s8, v134
	global_store_dword v[134:135], v138, off
	s_nop 0
	v_addc_co_u32_e32 v51, vcc, 0, v135, vcc
	v_add_co_u32_e32 v136, vcc, s6, v134
	s_waitcnt vmcnt(23)
	v_fmac_f32_e32 v147, v59, v0
	v_addc_co_u32_e32 v137, vcc, 0, v135, vcc
	v_add_co_u32_e32 v52, vcc, s38, v134
	global_store_dword v[136:137], v139, off offset:-4096
	s_nop 0
	v_addc_co_u32_e32 v53, vcc, 0, v135, vcc
	v_add_co_u32_e32 v138, vcc, s7, v134
	global_store_dword v[136:137], v140, off
	s_nop 0
	v_addc_co_u32_e32 v139, vcc, 0, v135, vcc
	v_add_co_u32_e32 v140, vcc, s36, v134
	global_store_dword v[52:53], v141, off
	s_nop 0
	v_addc_co_u32_e32 v141, vcc, 0, v135, vcc
	v_add_co_u32_e32 v54, vcc, s37, v134
	global_store_dword v[140:141], v142, off offset:-4096
	s_nop 0
	v_addc_co_u32_e32 v55, vcc, 0, v135, vcc
	v_add_co_u32_e32 v142, vcc, s5, v134
	global_store_dword v[140:141], v143, off
	s_nop 0
	v_addc_co_u32_e32 v143, vcc, 0, v135, vcc
	v_add_co_u32_e32 v56, vcc, s10, v134
	global_store_dword v[142:143], v144, off offset:-4096
	s_nop 0
	v_addc_co_u32_e32 v57, vcc, 0, v135, vcc
	v_add_co_u32_e32 v144, vcc, s39, v134
	global_store_dword v[142:143], v145, off
	s_nop 0
	v_addc_co_u32_e32 v145, vcc, 0, v135, vcc
	v_add_co_u32_e32 v58, vcc, s62, v134
	global_store_dword v[144:145], v146, off offset:-4096
	s_nop 0
	v_addc_co_u32_e32 v59, vcc, 0, v135, vcc
	v_add_co_u32_e32 v146, vcc, s57, v134
	global_store_dword v[144:145], v147, off
	s_nop 0
	v_addc_co_u32_e32 v147, vcc, 0, v135, vcc
	s_waitcnt vmcnt(31)
	v_fmac_f32_e32 v148, v60, v0
	v_add_co_u32_e32 v60, vcc, s54, v134
	s_waitcnt vmcnt(30)
	v_fmac_f32_e32 v149, v61, v0
	v_addc_co_u32_e32 v61, vcc, 0, v135, vcc
	global_store_dword v[146:147], v148, off offset:-4096
	v_add_co_u32_e32 v148, vcc, s55, v134
	global_store_dword v[146:147], v149, off
	s_nop 0
	v_addc_co_u32_e32 v149, vcc, 0, v135, vcc
	s_waitcnt vmcnt(31)
	v_fmac_f32_e32 v150, v62, v0
	v_add_co_u32_e32 v62, vcc, s72, v134
	s_waitcnt vmcnt(30)
	v_fmac_f32_e32 v151, v63, v0
	v_addc_co_u32_e32 v63, vcc, 0, v135, vcc
	global_store_dword v[148:149], v150, off offset:-4096
	v_add_co_u32_e32 v150, vcc, s73, v134
	global_store_dword v[148:149], v151, off
	s_nop 0
	v_addc_co_u32_e32 v151, vcc, 0, v135, vcc
	s_waitcnt vmcnt(31)
	v_fmac_f32_e32 v152, v64, v0
	v_add_co_u32_e32 v64, vcc, s63, v134
	s_waitcnt vmcnt(30)
	v_fmac_f32_e32 v153, v65, v0
	v_addc_co_u32_e32 v65, vcc, 0, v135, vcc
	global_store_dword v[150:151], v152, off offset:-4096
	v_add_co_u32_e32 v152, vcc, s74, v134
	global_store_dword v[150:151], v153, off
	s_nop 0
	v_addc_co_u32_e32 v153, vcc, 0, v135, vcc
	s_waitcnt vmcnt(31)
	v_fmac_f32_e32 v154, v34, v0
	v_add_co_u32_e32 v34, vcc, s75, v134
	s_waitcnt vmcnt(30)
	v_fmac_f32_e32 v155, v35, v0
	v_addc_co_u32_e32 v35, vcc, 0, v135, vcc
	global_store_dword v[152:153], v154, off offset:-4096
	v_add_co_u32_e32 v154, vcc, s76, v134
	global_store_dword v[152:153], v155, off
	s_nop 0
	v_addc_co_u32_e32 v155, vcc, 0, v135, vcc
	s_waitcnt vmcnt(31)
	v_fmac_f32_e32 v156, v36, v0
	v_add_co_u32_e32 v36, vcc, s77, v134
	s_waitcnt vmcnt(30)
	v_fmac_f32_e32 v157, v37, v0
	v_addc_co_u32_e32 v37, vcc, 0, v135, vcc
	global_store_dword v[154:155], v156, off offset:-4096
	v_add_co_u32_e32 v156, vcc, s78, v134
	global_store_dword v[154:155], v157, off
	s_nop 0
	v_addc_co_u32_e32 v157, vcc, 0, v135, vcc
	s_waitcnt vmcnt(31)
	v_fmac_f32_e32 v158, v38, v0
	v_add_co_u32_e32 v38, vcc, s79, v134
	s_waitcnt vmcnt(30)
	v_fmac_f32_e32 v159, v39, v0
	v_addc_co_u32_e32 v39, vcc, 0, v135, vcc
	global_store_dword v[156:157], v158, off offset:-4096
	v_add_co_u32_e32 v158, vcc, s58, v134
	global_store_dword v[156:157], v159, off
	s_nop 0
	v_addc_co_u32_e32 v159, vcc, 0, v135, vcc
	s_waitcnt vmcnt(31)
	v_fmac_f32_e32 v160, v40, v0
	v_add_co_u32_e32 v40, vcc, s61, v134
	s_waitcnt vmcnt(30)
	v_fmac_f32_e32 v161, v41, v0
	v_addc_co_u32_e32 v41, vcc, 0, v135, vcc
	global_store_dword v[158:159], v160, off offset:-4096
	v_add_co_u32_e32 v160, vcc, s56, v134
	global_store_dword v[158:159], v161, off
	s_nop 0
	v_addc_co_u32_e32 v161, vcc, 0, v135, vcc
	s_waitcnt vmcnt(31)
	v_fmac_f32_e32 v162, v42, v0
	v_add_co_u32_e32 v42, vcc, s97, v134
	s_waitcnt vmcnt(30)
	v_fmac_f32_e32 v163, v43, v0
	v_addc_co_u32_e32 v43, vcc, 0, v135, vcc
	global_store_dword v[160:161], v162, off offset:-4096
	v_add_co_u32_e32 v162, vcc, s9, v134
	global_store_dword v[160:161], v163, off
	s_nop 0
	v_addc_co_u32_e32 v163, vcc, 0, v135, vcc
	s_waitcnt vmcnt(31)
	v_fmac_f32_e32 v164, v44, v0
	v_add_co_u32_e32 v44, vcc, s69, v134
	s_waitcnt vmcnt(30)
	v_fmac_f32_e32 v165, v45, v0
	v_addc_co_u32_e32 v45, vcc, 0, v135, vcc
	global_store_dword v[162:163], v164, off offset:-4096
	v_add_co_u32_e32 v164, vcc, s67, v134
	global_store_dword v[162:163], v165, off
	s_nop 0
	v_addc_co_u32_e32 v165, vcc, 0, v135, vcc
	s_waitcnt vmcnt(31)
	v_fmac_f32_e32 v166, v46, v0
	v_add_co_u32_e32 v46, vcc, s60, v134
	s_waitcnt vmcnt(30)
	v_fmac_f32_e32 v167, v47, v0
	v_addc_co_u32_e32 v47, vcc, 0, v135, vcc
	global_store_dword v[164:165], v166, off offset:-4096
	s_waitcnt vmcnt(30)
	v_fmac_f32_e32 v169, v48, v0
	v_add_co_u32_e32 v166, vcc, s33, v134
	v_add_u32_e32 v48, 32, v168
	global_store_dword v[164:165], v167, off
	v_addc_co_u32_e32 v167, vcc, 0, v135, vcc
	s_waitcnt vmcnt(30)
	v_fmac_f32_e32 v181, v49, v0
	v_ashrrev_i32_e32 v49, 31, v48
	global_store_dword v[166:167], v169, off offset:-4096
	global_store_dword v[166:167], v181, off
	v_lshl_add_u64 v[48:49], v[48:49], 2, s[34:35]
	global_load_dword v0, v[48:49], off
	s_nop 0
	global_load_dword v48, v[66:67], off offset:128
	global_load_dword v49, v[68:69], off offset:128
	s_nop 0
	global_load_dword v66, v[70:71], off offset:128
	global_load_dword v67, v[72:73], off offset:128
	global_load_dword v68, v[74:75], off offset:128
	global_load_dword v69, v[76:77], off offset:128
	s_nop 0
	global_load_dword v70, v[78:79], off offset:128
	global_load_dword v71, v[80:81], off offset:128
	global_load_dword v72, v[82:83], off offset:128
	global_load_dword v73, v[84:85], off offset:128
	global_load_dword v74, v[86:87], off offset:128
	global_load_dword v75, v[88:89], off offset:128
	global_load_dword v76, v[90:91], off offset:128
	global_load_dword v77, v[92:93], off offset:128
	global_load_dword v78, v[94:95], off offset:128
	global_load_dword v79, v[96:97], off offset:128
	global_load_dword v80, v[98:99], off offset:128
	global_load_dword v81, v[100:101], off offset:128
	global_load_dword v82, v[102:103], off offset:128
	global_load_dword v83, v[104:105], off offset:128
	global_load_dword v84, v[106:107], off offset:128
	global_load_dword v85, v[108:109], off offset:128
	global_load_dword v86, v[110:111], off offset:128
	global_load_dword v87, v[112:113], off offset:128
	global_load_dword v88, v[114:115], off offset:128
	global_load_dword v89, v[116:117], off offset:128
	global_load_dword v90, v[118:119], off offset:128
	global_load_dword v91, v[120:121], off offset:128
	global_load_dword v92, v[122:123], off offset:128
	global_load_dword v93, v[124:125], off offset:128
	global_load_dword v94, v[126:127], off offset:128
	global_load_dword v95, v[128:129], off offset:128
	v_readlane_b32 s44, v210, 10
	v_readlane_b32 s45, v210, 11
	v_readlane_b32 s46, v210, 12
	v_readlane_b32 s47, v210, 13
	v_readlane_b32 s48, v210, 14
	v_readlane_b32 s49, v210, 15
	v_readlane_b32 s50, v210, 16
	v_readlane_b32 s51, v210, 17
	s_waitcnt vmcnt(31)
	v_fmac_f32_e32 v48, v18, v0
	s_waitcnt vmcnt(30)
	v_fmac_f32_e32 v49, v19, v0
	s_waitcnt vmcnt(29)
	v_fmac_f32_e32 v66, v20, v0
	s_waitcnt vmcnt(28)
	v_fmac_f32_e32 v67, v21, v0
	s_waitcnt vmcnt(27)
	v_fmac_f32_e32 v68, v22, v0
	s_waitcnt vmcnt(26)
	v_fmac_f32_e32 v69, v23, v0
	s_waitcnt vmcnt(25)
	v_fmac_f32_e32 v70, v24, v0
	s_waitcnt vmcnt(24)
	v_fmac_f32_e32 v71, v25, v0
	s_waitcnt vmcnt(23)
	v_fmac_f32_e32 v72, v26, v0
	s_waitcnt vmcnt(22)
	v_fmac_f32_e32 v73, v27, v0
	s_waitcnt vmcnt(21)
	v_fmac_f32_e32 v74, v28, v0
	s_waitcnt vmcnt(20)
	v_fmac_f32_e32 v75, v29, v0
	s_waitcnt vmcnt(19)
	v_fmac_f32_e32 v76, v30, v0
	s_waitcnt vmcnt(18)
	v_fmac_f32_e32 v77, v31, v0
	s_waitcnt vmcnt(17)
	v_fmac_f32_e32 v78, v32, v0
	s_waitcnt vmcnt(16)
	v_fmac_f32_e32 v79, v33, v0
	s_waitcnt vmcnt(15)
	v_fmac_f32_e32 v80, v2, v0
	s_waitcnt vmcnt(14)
	v_fmac_f32_e32 v81, v3, v0
	s_waitcnt vmcnt(13)
	v_fmac_f32_e32 v82, v4, v0
	s_waitcnt vmcnt(12)
	v_fmac_f32_e32 v83, v5, v0
	s_waitcnt vmcnt(11)
	v_fmac_f32_e32 v84, v6, v0
	s_waitcnt vmcnt(10)
	v_fmac_f32_e32 v85, v7, v0
	s_waitcnt vmcnt(9)
	v_fmac_f32_e32 v86, v8, v0
	s_waitcnt vmcnt(8)
	v_fmac_f32_e32 v87, v9, v0
	s_waitcnt vmcnt(7)
	v_fmac_f32_e32 v88, v10, v0
	s_waitcnt vmcnt(6)
	v_fmac_f32_e32 v89, v11, v0
	s_waitcnt vmcnt(5)
	v_fmac_f32_e32 v90, v12, v0
	s_waitcnt vmcnt(4)
	v_fmac_f32_e32 v91, v13, v0
	s_waitcnt vmcnt(3)
	v_fmac_f32_e32 v92, v14, v0
	s_waitcnt vmcnt(2)
	v_fmac_f32_e32 v93, v15, v0
	s_waitcnt vmcnt(1)
	v_fmac_f32_e32 v94, v16, v0
	s_waitcnt vmcnt(0)
	v_fmac_f32_e32 v95, v17, v0
	global_store_dword v[134:135], v48, off offset:128
	global_store_dword v[50:51], v49, off offset:128
	global_store_dword v[136:137], v66, off offset:128
	global_store_dword v[52:53], v67, off offset:128
	global_store_dword v[138:139], v68, off offset:128
	global_store_dword v[140:141], v69, off offset:128
	global_store_dword v[54:55], v70, off offset:128
	global_store_dword v[142:143], v71, off offset:128
	global_store_dword v[56:57], v72, off offset:128
	global_store_dword v[144:145], v73, off offset:128
	global_store_dword v[58:59], v74, off offset:128
	global_store_dword v[146:147], v75, off offset:128
	global_store_dword v[60:61], v76, off offset:128
	global_store_dword v[148:149], v77, off offset:128
	global_store_dword v[62:63], v78, off offset:128
	global_store_dword v[150:151], v79, off offset:128
	global_store_dword v[64:65], v80, off offset:128
	global_store_dword v[152:153], v81, off offset:128
	global_store_dword v[34:35], v82, off offset:128
	global_store_dword v[154:155], v83, off offset:128
	global_store_dword v[36:37], v84, off offset:128
	global_store_dword v[156:157], v85, off offset:128
	global_store_dword v[38:39], v86, off offset:128
	global_store_dword v[158:159], v87, off offset:128
	global_store_dword v[40:41], v88, off offset:128
	global_store_dword v[160:161], v89, off offset:128
	global_store_dword v[42:43], v90, off offset:128
	global_store_dword v[162:163], v91, off offset:128
	global_store_dword v[44:45], v92, off offset:128
	global_store_dword v[164:165], v93, off offset:128
	global_store_dword v[46:47], v94, off offset:128
	global_store_dword v[166:167], v95, off offset:128
	s_cbranch_scc1 .LBB0_1186
	v_readlane_b32 s72, v208, 43
	v_readlane_b32 s42, v208, 51
	v_readlane_b32 s54, v209, 14
	s_mov_b32 s62, 0x3b000
	v_readlane_b32 s73, v208, 44
	v_readlane_b32 s74, v208, 45
	v_readlane_b32 s75, v208, 46
	v_readlane_b32 s76, v208, 47
	v_readlane_b32 s77, v208, 48
	v_readlane_b32 s78, v208, 49
	v_readlane_b32 s79, v208, 50
	v_readlane_b32 s43, v208, 52
	v_readlane_b32 s55, v209, 15
	s_mov_b32 s67, 0x3a000
	v_readlane_b32 s97, v209, 2
	v_readlane_b32 s60, v208, 63
	s_mov_b32 s56, 0x10000
	s_mov_b32 s57, 0x20000
	s_mov_b32 s58, 0x30000
	s_movk_i32 s59, 0x70
	s_movk_i32 s53, 0x2000
	s_mov_b32 s52, 0xb000

.LBB0_1298:
	s_ashr_i32 s6, s5, 31
	s_lshr_b32 s6, s6, 27
	s_add_i32 s6, s5, s6
	s_ashr_i32 s34, s6, 5
	s_ashr_i32 s35, s34, 31
	v_mov_b32_e32 v36, v133
	s_lshl_b64 s[6:7], s[34:35], 18
	s_add_u32 s6, s38, s6
	v_ashrrev_i32_e32 v34, 3, v36
	v_ashrrev_i32_e32 v35, 31, v34
	s_addc_u32 s7, s39, s7
	v_lshlrev_b64 v[2:3], 11, v[34:35]
	v_lshlrev_b32_e32 v0, 4, v36
	v_lshl_add_u64 v[2:3], s[6:7], 0, v[2:3]
	v_and_b32_e32 v0, 0x70, v0
	s_lshl_b32 s6, s34, 12
	v_lshl_add_u64 v[66:67], v[2:3], 0, v[0:1]
	v_subrev_u32_e32 v2, s6, v34
	v_add_u32_e32 v2, s4, v2
	v_ashrrev_i32_e32 v3, 31, v2
	v_lshlrev_b64 v[2:3], 11, v[2:3]
	v_lshl_add_u64 v[2:3], s[0:1], 0, v[2:3]
	v_add_co_u32_e32 v70, vcc, s56, v66
	v_lshl_add_u64 v[68:69], v[2:3], 0, v[0:1]
	s_nop 0
	v_addc_co_u32_e32 v71, vcc, 0, v67, vcc
	v_add_co_u32_e32 v72, vcc, s56, v68
	v_addc_co_u32_e32 v73, vcc, 0, v69, vcc
	v_add_co_u32_e32 v74, vcc, s57, v66
	s_nop 0
	v_addc_co_u32_e32 v75, vcc, 0, v67, vcc
	v_add_co_u32_e32 v76, vcc, s57, v68
	s_nop 0
	v_addc_co_u32_e32 v77, vcc, 0, v69, vcc
	v_add_co_u32_e32 v78, vcc, s58, v66
	s_nop 0
	v_addc_co_u32_e32 v79, vcc, 0, v67, vcc
	v_add_co_u32_e32 v80, vcc, s58, v68
	v_lshlrev_b32_e32 v0, 7, v34
	s_nop 0
	v_addc_co_u32_e32 v81, vcc, 0, v69, vcc
	v_lshrrev_b32_e32 v216, 4, v133
	v_xor_b32_e32 v216, v216, v133
	v_and_b32_e32 v216, 7, v216
	v_lshlrev_b32_e32 v216, 4, v216
	v_mov_b32_e32 v217, 0x70
	v_lshrrev_b32_e32 v218, 6, v133
	v_lshlrev_b32_e32 v218, 10, v218
	s_nop 0
	v_readfirstlane_b32 s32, v218
	v_bfi_b32 v66, v217, v216, v66
	v_bfi_b32 v70, v217, v216, v70
	v_bfi_b32 v74, v217, v216, v74
	v_bfi_b32 v78, v217, v216, v78
	v_bfi_b32 v68, v217, v216, v68
	v_bfi_b32 v72, v217, v216, v72
	v_bfi_b32 v76, v217, v216, v76
	v_bfi_b32 v80, v217, v216, v80
	s_add_u32 m0, s32, 0x0
	s_nop 0
	global_load_lds_dwordx4 v[66:67], off
	s_add_u32 m0, s32, 0x1000
	s_nop 0
	global_load_lds_dwordx4 v[70:71], off
	s_add_u32 m0, s32, 0x2000
	s_nop 0
	global_load_lds_dwordx4 v[74:75], off
	s_add_u32 m0, s32, 0x3000
	s_nop 0
	global_load_lds_dwordx4 v[78:79], off
	s_add_u32 m0, s32, 0x8000
	s_nop 0
	global_load_lds_dwordx4 v[68:69], off
	s_add_u32 m0, s32, 0x9000
	s_nop 0
	global_load_lds_dwordx4 v[72:73], off
	s_add_u32 m0, s32, 0xa000
	s_nop 0
	global_load_lds_dwordx4 v[76:77], off
	s_add_u32 m0, s32, 0xb000
	s_nop 0
	global_load_lds_dwordx4 v[80:81], off
	v_lshl_add_u64 v[66:67], v[66:67], 0, 64
	v_lshl_add_u64 v[66:67], v[66:67], 0, 64
	v_lshl_add_u64 v[70:71], v[70:71], 0, 64
	v_lshl_add_u64 v[70:71], v[70:71], 0, 64
	v_lshl_add_u64 v[74:75], v[74:75], 0, 64
	v_lshl_add_u64 v[74:75], v[74:75], 0, 64
	v_lshl_add_u64 v[78:79], v[78:79], 0, 64
	v_lshl_add_u64 v[78:79], v[78:79], 0, 64
	v_lshl_add_u64 v[68:69], v[68:69], 0, 64
	v_lshl_add_u64 v[68:69], v[68:69], 0, 64
	v_lshl_add_u64 v[72:73], v[72:73], 0, 64
	v_lshl_add_u64 v[72:73], v[72:73], 0, 64
	v_lshl_add_u64 v[76:77], v[76:77], 0, 64
	v_lshl_add_u64 v[76:77], v[76:77], 0, 64
	v_lshl_add_u64 v[80:81], v[80:81], 0, 64
	v_lshl_add_u64 v[80:81], v[80:81], 0, 64
	v_lshrrev_b32_e32 v34, 1, v34
	v_xor_b32_e32 v34, v34, v36
	v_lshlrev_b32_e32 v34, 4, v34
	v_and_or_b32 v0, v34, s59, v0
	s_waitcnt vmcnt(26)
	v_and_b32_e32 v82, 31, v36
	v_bfe_u32 v83, v36, 5, 1
	v_ashrrev_i32_e32 v84, 7, v36
	v_bfe_u32 v85, v36, 6, 1
	s_waitcnt vmcnt(0)
	s_waitcnt lgkmcnt(0)
	s_barrier
	s_add_u32 m0, s32, 0x4000
	s_nop 0
	global_load_lds_dwordx4 v[66:67], off
	s_add_u32 m0, s32, 0x5000
	s_nop 0
	global_load_lds_dwordx4 v[70:71], off
	s_add_u32 m0, s32, 0x6000
	s_nop 0
	global_load_lds_dwordx4 v[74:75], off
	s_add_u32 m0, s32, 0x7000
	s_nop 0
	global_load_lds_dwordx4 v[78:79], off
	s_add_u32 m0, s32, 0xc000
	s_nop 0
	global_load_lds_dwordx4 v[68:69], off
	s_add_u32 m0, s32, 0xd000
	s_nop 0
	global_load_lds_dwordx4 v[72:73], off
	s_add_u32 m0, s32, 0xe000
	s_nop 0
	global_load_lds_dwordx4 v[76:77], off
	s_add_u32 m0, s32, 0xf000
	s_nop 0
	global_load_lds_dwordx4 v[80:81], off
	v_lshl_add_u64 v[66:67], v[66:67], 0, 64
	v_lshl_add_u64 v[66:67], v[66:67], 0, 64
	v_lshl_add_u64 v[70:71], v[70:71], 0, 64
	v_lshl_add_u64 v[70:71], v[70:71], 0, 64
	v_lshl_add_u64 v[74:75], v[74:75], 0, 64
	v_lshl_add_u64 v[74:75], v[74:75], 0, 64
	v_lshl_add_u64 v[78:79], v[78:79], 0, 64
	v_lshl_add_u64 v[78:79], v[78:79], 0, 64
	v_lshl_add_u64 v[68:69], v[68:69], 0, 64
	v_lshl_add_u64 v[68:69], v[68:69], 0, 64
	v_lshl_add_u64 v[72:73], v[72:73], 0, 64
	v_lshl_add_u64 v[72:73], v[72:73], 0, 64
	v_lshl_add_u64 v[76:77], v[76:77], 0, 64
	v_lshl_add_u64 v[76:77], v[76:77], 0, 64
	v_lshl_add_u64 v[80:81], v[80:81], 0, 64
	v_lshl_add_u64 v[80:81], v[80:81], 0, 64
	v_lshrrev_b32_e32 v4, 1, v36
	v_lshlrev_b32_e32 v2, 7, v82
	v_bitop3_b32 v4, v4, v83, 7 bitop3:0x6c
	v_lshl_or_b32 v3, v84, 13, v2
	v_bfe_u32 v5, v36, 1, 3
	v_lshlrev_b32_e32 v4, 4, v4
	v_lshl_or_b32 v2, v85, 13, v2
	v_or_b32_e32 v91, v3, v4
	v_or_b32_e32 v92, v2, v4
	v_bitop3_b32 v4, v83, v5, 2 bitop3:0x36
	v_lshlrev_b32_e32 v4, 4, v4
	v_or_b32_e32 v93, v3, v4
	v_or_b32_e32 v90, v2, v4
	v_bitop3_b32 v4, v83, v5, 4 bitop3:0x36
	v_lshlrev_b32_e32 v4, 4, v4
	v_or_b32_e32 v89, v3, v4
	v_or_b32_e32 v88, v2, v4
	v_bitop3_b32 v4, v83, v5, 6 bitop3:0x36
	v_lshlrev_b32_e32 v4, 4, v4
	v_or_b32_e32 v87, v3, v4
	v_or_b32_e32 v86, v2, v4
	ds_read_b128 v[2:5], v91
	ds_read_b128 v[6:9], v92 offset:32768
	ds_read_b128 v[10:13], v91 offset:4096
	ds_read_b128 v[14:17], v92 offset:36864
	ds_read_b128 v[162:165], v93
	ds_read_b128 v[166:169], v90 offset:32768
	ds_read_b128 v[182:185], v93 offset:4096
	ds_read_b128 v[186:189], v90 offset:36864
	s_waitcnt lgkmcnt(6)
	v_mfma_f32_32x32x16_bf16 v[50:65], v[2:5], v[6:9], 0
	s_waitcnt lgkmcnt(4)
	v_mfma_f32_32x32x16_bf16 v[34:49], v[2:5], v[14:17], 0
	v_mfma_f32_32x32x16_bf16 v[18:33], v[10:13], v[6:9], 0
	v_mfma_f32_32x32x16_bf16 v[2:17], v[10:13], v[14:17], 0
	ds_read_b128 v[190:193], v89
	ds_read_b128 v[194:197], v89 offset:4096
	ds_read_b128 v[198:201], v88 offset:32768
	ds_read_b128 v[202:205], v88 offset:36864
	s_waitcnt lgkmcnt(6)
	v_mfma_f32_32x32x16_bf16 v[50:65], v[162:165], v[166:169], v[50:65]
	s_waitcnt lgkmcnt(4)
	v_mfma_f32_32x32x16_bf16 v[34:49], v[162:165], v[186:189], v[34:49]
	v_mfma_f32_32x32x16_bf16 v[18:33], v[182:185], v[166:169], v[18:33]
	v_mfma_f32_32x32x16_bf16 v[2:17], v[182:185], v[186:189], v[2:17]
	ds_read_b128 v[162:165], v87
	ds_read_b128 v[166:169], v87 offset:4096
	ds_read_b128 v[182:185], v86 offset:32768
	ds_read_b128 v[186:189], v86 offset:36864
	s_waitcnt vmcnt(0)
	s_waitcnt lgkmcnt(0)
	s_barrier
	s_add_u32 m0, s32, 0x0
	s_nop 0
	global_load_lds_dwordx4 v[66:67], off
	s_add_u32 m0, s32, 0x1000
	s_nop 0
	global_load_lds_dwordx4 v[70:71], off
	s_add_u32 m0, s32, 0x2000
	s_nop 0
	global_load_lds_dwordx4 v[74:75], off
	s_add_u32 m0, s32, 0x3000
	s_nop 0
	global_load_lds_dwordx4 v[78:79], off
	s_add_u32 m0, s32, 0x8000
	s_nop 0
	global_load_lds_dwordx4 v[68:69], off
	s_add_u32 m0, s32, 0x9000
	s_nop 0
	global_load_lds_dwordx4 v[72:73], off
	s_add_u32 m0, s32, 0xa000
	s_nop 0
	global_load_lds_dwordx4 v[76:77], off
	s_add_u32 m0, s32, 0xb000
	s_nop 0
	global_load_lds_dwordx4 v[80:81], off
	v_lshl_add_u64 v[66:67], v[66:67], 0, 64
	v_lshl_add_u64 v[66:67], v[66:67], 0, 64
	v_lshl_add_u64 v[70:71], v[70:71], 0, 64
	v_lshl_add_u64 v[70:71], v[70:71], 0, 64
	v_lshl_add_u64 v[74:75], v[74:75], 0, 64
	v_lshl_add_u64 v[74:75], v[74:75], 0, 64
	v_lshl_add_u64 v[78:79], v[78:79], 0, 64
	v_lshl_add_u64 v[78:79], v[78:79], 0, 64
	v_lshl_add_u64 v[68:69], v[68:69], 0, 64
	v_lshl_add_u64 v[68:69], v[68:69], 0, 64
	v_lshl_add_u64 v[72:73], v[72:73], 0, 64
	v_lshl_add_u64 v[72:73], v[72:73], 0, 64
	v_lshl_add_u64 v[76:77], v[76:77], 0, 64
	v_lshl_add_u64 v[76:77], v[76:77], 0, 64
	v_lshl_add_u64 v[80:81], v[80:81], 0, 64
	v_lshl_add_u64 v[80:81], v[80:81], 0, 64
	v_mfma_f32_32x32x16_bf16 v[50:65], v[190:193], v[198:201], v[50:65]
	v_mfma_f32_32x32x16_bf16 v[34:49], v[190:193], v[202:205], v[34:49]
	v_mfma_f32_32x32x16_bf16 v[18:33], v[194:197], v[198:201], v[18:33]
	v_mfma_f32_32x32x16_bf16 v[2:17], v[194:197], v[202:205], v[2:17]
	v_mfma_f32_32x32x16_bf16 v[50:65], v[162:165], v[182:185], v[50:65]
	v_mfma_f32_32x32x16_bf16 v[34:49], v[162:165], v[186:189], v[34:49]
	v_mfma_f32_32x32x16_bf16 v[18:33], v[166:169], v[182:185], v[18:33]
	v_mfma_f32_32x32x16_bf16 v[2:17], v[166:169], v[186:189], v[2:17]
	ds_read_b128 v[162:165], v91 offset:16384
	ds_read_b128 v[166:169], v92 offset:49152
	ds_read_b128 v[182:185], v91 offset:20480
	ds_read_b128 v[186:189], v92 offset:53248
	ds_read_b128 v[190:193], v93 offset:16384
	ds_read_b128 v[194:197], v90 offset:49152
	ds_read_b128 v[198:201], v93 offset:20480
	ds_read_b128 v[202:205], v90 offset:53248
	s_waitcnt lgkmcnt(6)
	v_mfma_f32_32x32x16_bf16 v[50:65], v[162:165], v[166:169], v[50:65]
	s_waitcnt lgkmcnt(4)
	v_mfma_f32_32x32x16_bf16 v[34:49], v[162:165], v[186:189], v[34:49]
	v_mfma_f32_32x32x16_bf16 v[18:33], v[182:185], v[166:169], v[18:33]
	v_mfma_f32_32x32x16_bf16 v[2:17], v[182:185], v[186:189], v[2:17]
	ds_read_b128 v[162:165], v89 offset:16384
	ds_read_b128 v[166:169], v89 offset:20480
	ds_read_b128 v[182:185], v88 offset:49152
	ds_read_b128 v[186:189], v88 offset:53248
	s_waitcnt lgkmcnt(6)
	v_mfma_f32_32x32x16_bf16 v[50:65], v[190:193], v[194:197], v[50:65]
	s_waitcnt lgkmcnt(4)
	v_mfma_f32_32x32x16_bf16 v[34:49], v[190:193], v[202:205], v[34:49]
	v_mfma_f32_32x32x16_bf16 v[18:33], v[198:201], v[194:197], v[18:33]
	v_mfma_f32_32x32x16_bf16 v[2:17], v[198:201], v[202:205], v[2:17]
	ds_read_b128 v[190:193], v87 offset:16384
	ds_read_b128 v[194:197], v87 offset:20480
	ds_read_b128 v[198:201], v86 offset:49152
	ds_read_b128 v[202:205], v86 offset:53248
	s_waitcnt vmcnt(0)
	s_waitcnt lgkmcnt(0)
	s_barrier
	s_add_u32 m0, s32, 0x4000
	s_nop 0
	global_load_lds_dwordx4 v[66:67], off
	s_add_u32 m0, s32, 0x5000
	s_nop 0
	global_load_lds_dwordx4 v[70:71], off
	s_add_u32 m0, s32, 0x6000
	s_nop 0
	global_load_lds_dwordx4 v[74:75], off
	s_add_u32 m0, s32, 0x7000
	s_nop 0
	global_load_lds_dwordx4 v[78:79], off
	s_add_u32 m0, s32, 0xc000
	s_nop 0
	global_load_lds_dwordx4 v[68:69], off
	s_add_u32 m0, s32, 0xd000
	s_nop 0
	global_load_lds_dwordx4 v[72:73], off
	s_add_u32 m0, s32, 0xe000
	s_nop 0
	global_load_lds_dwordx4 v[76:77], off
	s_add_u32 m0, s32, 0xf000
	s_nop 0
	global_load_lds_dwordx4 v[80:81], off
	v_lshl_add_u64 v[66:67], v[66:67], 0, 64
	v_lshl_add_u64 v[66:67], v[66:67], 0, 64
	v_lshl_add_u64 v[70:71], v[70:71], 0, 64
	v_lshl_add_u64 v[70:71], v[70:71], 0, 64
	v_lshl_add_u64 v[74:75], v[74:75], 0, 64
	v_lshl_add_u64 v[74:75], v[74:75], 0, 64
	v_lshl_add_u64 v[78:79], v[78:79], 0, 64
	v_lshl_add_u64 v[78:79], v[78:79], 0, 64
	v_lshl_add_u64 v[68:69], v[68:69], 0, 64
	v_lshl_add_u64 v[68:69], v[68:69], 0, 64
	v_lshl_add_u64 v[72:73], v[72:73], 0, 64
	v_lshl_add_u64 v[72:73], v[72:73], 0, 64
	v_lshl_add_u64 v[76:77], v[76:77], 0, 64
	v_lshl_add_u64 v[76:77], v[76:77], 0, 64
	v_lshl_add_u64 v[80:81], v[80:81], 0, 64
	v_lshl_add_u64 v[80:81], v[80:81], 0, 64
	v_mfma_f32_32x32x16_bf16 v[50:65], v[162:165], v[182:185], v[50:65]
	v_mfma_f32_32x32x16_bf16 v[34:49], v[162:165], v[186:189], v[34:49]
	v_mfma_f32_32x32x16_bf16 v[18:33], v[166:169], v[182:185], v[18:33]
	v_mfma_f32_32x32x16_bf16 v[2:17], v[166:169], v[186:189], v[2:17]
	v_mfma_f32_32x32x16_bf16 v[50:65], v[190:193], v[198:201], v[50:65]
	v_mfma_f32_32x32x16_bf16 v[34:49], v[190:193], v[202:205], v[34:49]
	v_mfma_f32_32x32x16_bf16 v[18:33], v[194:197], v[198:201], v[18:33]
	v_mfma_f32_32x32x16_bf16 v[2:17], v[194:197], v[202:205], v[2:17]
	ds_read_b128 v[162:165], v91
	ds_read_b128 v[166:169], v92 offset:32768
	ds_read_b128 v[182:185], v91 offset:4096
	ds_read_b128 v[186:189], v92 offset:36864
	ds_read_b128 v[190:193], v93
	ds_read_b128 v[194:197], v90 offset:32768
	ds_read_b128 v[198:201], v93 offset:4096
	ds_read_b128 v[202:205], v90 offset:36864
	s_waitcnt lgkmcnt(6)
	v_mfma_f32_32x32x16_bf16 v[50:65], v[162:165], v[166:169], v[50:65]
	s_waitcnt lgkmcnt(4)
	v_mfma_f32_32x32x16_bf16 v[34:49], v[162:165], v[186:189], v[34:49]
	v_mfma_f32_32x32x16_bf16 v[18:33], v[182:185], v[166:169], v[18:33]
	v_mfma_f32_32x32x16_bf16 v[2:17], v[182:185], v[186:189], v[2:17]
	ds_read_b128 v[162:165], v89
	ds_read_b128 v[166:169], v89 offset:4096
	ds_read_b128 v[182:185], v88 offset:32768
	ds_read_b128 v[186:189], v88 offset:36864
	s_waitcnt lgkmcnt(6)
	v_mfma_f32_32x32x16_bf16 v[50:65], v[190:193], v[194:197], v[50:65]
	s_waitcnt lgkmcnt(4)
	v_mfma_f32_32x32x16_bf16 v[34:49], v[190:193], v[202:205], v[34:49]
	v_mfma_f32_32x32x16_bf16 v[18:33], v[198:201], v[194:197], v[18:33]
	v_mfma_f32_32x32x16_bf16 v[2:17], v[198:201], v[202:205], v[2:17]
	ds_read_b128 v[190:193], v87
	ds_read_b128 v[194:197], v87 offset:4096
	ds_read_b128 v[198:201], v86 offset:32768
	ds_read_b128 v[202:205], v86 offset:36864
	s_waitcnt vmcnt(0)
	s_waitcnt lgkmcnt(0)
	s_barrier
	s_add_u32 m0, s32, 0x0
	s_nop 0
	global_load_lds_dwordx4 v[66:67], off
	s_add_u32 m0, s32, 0x1000
	s_nop 0
	global_load_lds_dwordx4 v[70:71], off
	s_add_u32 m0, s32, 0x2000
	s_nop 0
	global_load_lds_dwordx4 v[74:75], off
	s_add_u32 m0, s32, 0x3000
	s_nop 0
	global_load_lds_dwordx4 v[78:79], off
	s_add_u32 m0, s32, 0x8000
	s_nop 0
	global_load_lds_dwordx4 v[68:69], off
	s_add_u32 m0, s32, 0x9000
	s_nop 0
	global_load_lds_dwordx4 v[72:73], off
	s_add_u32 m0, s32, 0xa000
	s_nop 0
	global_load_lds_dwordx4 v[76:77], off
	s_add_u32 m0, s32, 0xb000
	s_nop 0
	global_load_lds_dwordx4 v[80:81], off
	v_lshl_add_u64 v[66:67], v[66:67], 0, 64
	v_lshl_add_u64 v[66:67], v[66:67], 0, 64
	v_lshl_add_u64 v[70:71], v[70:71], 0, 64
	v_lshl_add_u64 v[70:71], v[70:71], 0, 64
	v_lshl_add_u64 v[74:75], v[74:75], 0, 64
	v_lshl_add_u64 v[74:75], v[74:75], 0, 64
	v_lshl_add_u64 v[78:79], v[78:79], 0, 64
	v_lshl_add_u64 v[78:79], v[78:79], 0, 64
	v_lshl_add_u64 v[68:69], v[68:69], 0, 64
	v_lshl_add_u64 v[68:69], v[68:69], 0, 64
	v_lshl_add_u64 v[72:73], v[72:73], 0, 64
	v_lshl_add_u64 v[72:73], v[72:73], 0, 64
	v_lshl_add_u64 v[76:77], v[76:77], 0, 64
	v_lshl_add_u64 v[76:77], v[76:77], 0, 64
	v_lshl_add_u64 v[80:81], v[80:81], 0, 64
	v_lshl_add_u64 v[80:81], v[80:81], 0, 64
	v_mfma_f32_32x32x16_bf16 v[50:65], v[162:165], v[182:185], v[50:65]
	v_mfma_f32_32x32x16_bf16 v[34:49], v[162:165], v[186:189], v[34:49]
	v_mfma_f32_32x32x16_bf16 v[18:33], v[166:169], v[182:185], v[18:33]
	v_mfma_f32_32x32x16_bf16 v[2:17], v[166:169], v[186:189], v[2:17]
	v_mfma_f32_32x32x16_bf16 v[50:65], v[190:193], v[198:201], v[50:65]
	v_mfma_f32_32x32x16_bf16 v[34:49], v[190:193], v[202:205], v[34:49]
	v_mfma_f32_32x32x16_bf16 v[18:33], v[194:197], v[198:201], v[18:33]
	v_mfma_f32_32x32x16_bf16 v[2:17], v[194:197], v[202:205], v[2:17]
	ds_read_b128 v[162:165], v91 offset:16384
	ds_read_b128 v[166:169], v92 offset:49152
	ds_read_b128 v[182:185], v91 offset:20480
	ds_read_b128 v[186:189], v92 offset:53248
	ds_read_b128 v[190:193], v93 offset:16384
	ds_read_b128 v[194:197], v90 offset:49152
	ds_read_b128 v[198:201], v93 offset:20480
	ds_read_b128 v[202:205], v90 offset:53248
	s_waitcnt lgkmcnt(6)
	v_mfma_f32_32x32x16_bf16 v[50:65], v[162:165], v[166:169], v[50:65]
	s_waitcnt lgkmcnt(4)
	v_mfma_f32_32x32x16_bf16 v[34:49], v[162:165], v[186:189], v[34:49]
	v_mfma_f32_32x32x16_bf16 v[18:33], v[182:185], v[166:169], v[18:33]
	v_mfma_f32_32x32x16_bf16 v[2:17], v[182:185], v[186:189], v[2:17]
	ds_read_b128 v[162:165], v89 offset:16384
	ds_read_b128 v[166:169], v89 offset:20480
	ds_read_b128 v[182:185], v88 offset:49152
	ds_read_b128 v[186:189], v88 offset:53248
	s_waitcnt lgkmcnt(6)
	v_mfma_f32_32x32x16_bf16 v[50:65], v[190:193], v[194:197], v[50:65]
	s_waitcnt lgkmcnt(4)
	v_mfma_f32_32x32x16_bf16 v[34:49], v[190:193], v[202:205], v[34:49]
	v_mfma_f32_32x32x16_bf16 v[18:33], v[198:201], v[194:197], v[18:33]
	v_mfma_f32_32x32x16_bf16 v[2:17], v[198:201], v[202:205], v[2:17]
	ds_read_b128 v[190:193], v87 offset:16384
	ds_read_b128 v[194:197], v87 offset:20480
	ds_read_b128 v[198:201], v86 offset:49152
	ds_read_b128 v[202:205], v86 offset:53248
	s_waitcnt vmcnt(0)
	s_waitcnt lgkmcnt(0)
	s_barrier
	s_add_u32 m0, s32, 0x4000
	s_nop 0
	global_load_lds_dwordx4 v[66:67], off
	s_add_u32 m0, s32, 0x5000
	s_nop 0
	global_load_lds_dwordx4 v[70:71], off
	s_add_u32 m0, s32, 0x6000
	s_nop 0
	global_load_lds_dwordx4 v[74:75], off
	s_add_u32 m0, s32, 0x7000
	s_nop 0
	global_load_lds_dwordx4 v[78:79], off
	s_add_u32 m0, s32, 0xc000
	s_nop 0
	global_load_lds_dwordx4 v[68:69], off
	s_add_u32 m0, s32, 0xd000
	s_nop 0
	global_load_lds_dwordx4 v[72:73], off
	s_add_u32 m0, s32, 0xe000
	s_nop 0
	global_load_lds_dwordx4 v[76:77], off
	s_add_u32 m0, s32, 0xf000
	s_nop 0
	global_load_lds_dwordx4 v[80:81], off
	v_lshl_add_u64 v[66:67], v[66:67], 0, 64
	v_lshl_add_u64 v[66:67], v[66:67], 0, 64
	v_lshl_add_u64 v[70:71], v[70:71], 0, 64
	v_lshl_add_u64 v[70:71], v[70:71], 0, 64
	v_lshl_add_u64 v[74:75], v[74:75], 0, 64
	v_lshl_add_u64 v[74:75], v[74:75], 0, 64
	v_lshl_add_u64 v[78:79], v[78:79], 0, 64
	v_lshl_add_u64 v[78:79], v[78:79], 0, 64
	v_lshl_add_u64 v[68:69], v[68:69], 0, 64
	v_lshl_add_u64 v[68:69], v[68:69], 0, 64
	v_lshl_add_u64 v[72:73], v[72:73], 0, 64
	v_lshl_add_u64 v[72:73], v[72:73], 0, 64
	v_lshl_add_u64 v[76:77], v[76:77], 0, 64
	v_lshl_add_u64 v[76:77], v[76:77], 0, 64
	v_lshl_add_u64 v[80:81], v[80:81], 0, 64
	v_lshl_add_u64 v[80:81], v[80:81], 0, 64
	v_mfma_f32_32x32x16_bf16 v[50:65], v[162:165], v[182:185], v[50:65]
	v_mfma_f32_32x32x16_bf16 v[34:49], v[162:165], v[186:189], v[34:49]
	v_mfma_f32_32x32x16_bf16 v[18:33], v[166:169], v[182:185], v[18:33]
	v_mfma_f32_32x32x16_bf16 v[2:17], v[166:169], v[186:189], v[2:17]
	v_mfma_f32_32x32x16_bf16 v[50:65], v[190:193], v[198:201], v[50:65]
	v_mfma_f32_32x32x16_bf16 v[34:49], v[190:193], v[202:205], v[34:49]
	v_mfma_f32_32x32x16_bf16 v[18:33], v[194:197], v[198:201], v[18:33]
	v_mfma_f32_32x32x16_bf16 v[2:17], v[194:197], v[202:205], v[2:17]
	ds_read_b128 v[162:165], v91
	ds_read_b128 v[166:169], v92 offset:32768
	ds_read_b128 v[182:185], v91 offset:4096
	ds_read_b128 v[186:189], v92 offset:36864
	ds_read_b128 v[190:193], v93
	ds_read_b128 v[194:197], v90 offset:32768
	ds_read_b128 v[198:201], v93 offset:4096
	ds_read_b128 v[202:205], v90 offset:36864
	s_waitcnt lgkmcnt(6)
	v_mfma_f32_32x32x16_bf16 v[50:65], v[162:165], v[166:169], v[50:65]
	s_waitcnt lgkmcnt(4)
	v_mfma_f32_32x32x16_bf16 v[34:49], v[162:165], v[186:189], v[34:49]
	v_mfma_f32_32x32x16_bf16 v[18:33], v[182:185], v[166:169], v[18:33]
	v_mfma_f32_32x32x16_bf16 v[2:17], v[182:185], v[186:189], v[2:17]
	ds_read_b128 v[162:165], v89
	ds_read_b128 v[166:169], v89 offset:4096
	ds_read_b128 v[182:185], v88 offset:32768
	ds_read_b128 v[186:189], v88 offset:36864
	s_waitcnt lgkmcnt(6)
	v_mfma_f32_32x32x16_bf16 v[50:65], v[190:193], v[194:197], v[50:65]
	s_waitcnt lgkmcnt(4)
	v_mfma_f32_32x32x16_bf16 v[34:49], v[190:193], v[202:205], v[34:49]
	v_mfma_f32_32x32x16_bf16 v[18:33], v[198:201], v[194:197], v[18:33]
	v_mfma_f32_32x32x16_bf16 v[2:17], v[198:201], v[202:205], v[2:17]
	ds_read_b128 v[190:193], v87
	ds_read_b128 v[194:197], v87 offset:4096
	ds_read_b128 v[198:201], v86 offset:32768
	ds_read_b128 v[202:205], v86 offset:36864
	s_waitcnt vmcnt(0)
	s_waitcnt lgkmcnt(0)
	s_barrier
	s_add_u32 m0, s32, 0x0
	s_nop 0
	global_load_lds_dwordx4 v[66:67], off
	s_add_u32 m0, s32, 0x1000
	s_nop 0
	global_load_lds_dwordx4 v[70:71], off
	s_add_u32 m0, s32, 0x2000
	s_nop 0
	global_load_lds_dwordx4 v[74:75], off
	s_add_u32 m0, s32, 0x3000
	s_nop 0
	global_load_lds_dwordx4 v[78:79], off
	s_add_u32 m0, s32, 0x8000
	s_nop 0
	global_load_lds_dwordx4 v[68:69], off
	s_add_u32 m0, s32, 0x9000
	s_nop 0
	global_load_lds_dwordx4 v[72:73], off
	s_add_u32 m0, s32, 0xa000
	s_nop 0
	global_load_lds_dwordx4 v[76:77], off
	s_add_u32 m0, s32, 0xb000
	s_nop 0
	global_load_lds_dwordx4 v[80:81], off
	v_lshl_add_u64 v[66:67], v[66:67], 0, 64
	v_lshl_add_u64 v[66:67], v[66:67], 0, 64
	v_lshl_add_u64 v[70:71], v[70:71], 0, 64
	v_lshl_add_u64 v[70:71], v[70:71], 0, 64
	v_lshl_add_u64 v[74:75], v[74:75], 0, 64
	v_lshl_add_u64 v[74:75], v[74:75], 0, 64
	v_lshl_add_u64 v[78:79], v[78:79], 0, 64
	v_lshl_add_u64 v[78:79], v[78:79], 0, 64
	v_lshl_add_u64 v[68:69], v[68:69], 0, 64
	v_lshl_add_u64 v[68:69], v[68:69], 0, 64
	v_lshl_add_u64 v[72:73], v[72:73], 0, 64
	v_lshl_add_u64 v[72:73], v[72:73], 0, 64
	v_lshl_add_u64 v[76:77], v[76:77], 0, 64
	v_lshl_add_u64 v[76:77], v[76:77], 0, 64
	v_lshl_add_u64 v[80:81], v[80:81], 0, 64
	v_lshl_add_u64 v[80:81], v[80:81], 0, 64
	v_mfma_f32_32x32x16_bf16 v[50:65], v[162:165], v[182:185], v[50:65]
	v_mfma_f32_32x32x16_bf16 v[34:49], v[162:165], v[186:189], v[34:49]
	v_mfma_f32_32x32x16_bf16 v[18:33], v[166:169], v[182:185], v[18:33]
	v_mfma_f32_32x32x16_bf16 v[2:17], v[166:169], v[186:189], v[2:17]
	v_mfma_f32_32x32x16_bf16 v[50:65], v[190:193], v[198:201], v[50:65]
	v_mfma_f32_32x32x16_bf16 v[34:49], v[190:193], v[202:205], v[34:49]
	v_mfma_f32_32x32x16_bf16 v[18:33], v[194:197], v[198:201], v[18:33]
	v_mfma_f32_32x32x16_bf16 v[2:17], v[194:197], v[202:205], v[2:17]
	ds_read_b128 v[162:165], v91 offset:16384
	ds_read_b128 v[166:169], v92 offset:49152
	ds_read_b128 v[182:185], v91 offset:20480
	ds_read_b128 v[186:189], v92 offset:53248
	ds_read_b128 v[190:193], v93 offset:16384
	ds_read_b128 v[194:197], v90 offset:49152
	ds_read_b128 v[198:201], v93 offset:20480
	ds_read_b128 v[202:205], v90 offset:53248
	s_waitcnt lgkmcnt(6)
	v_mfma_f32_32x32x16_bf16 v[50:65], v[162:165], v[166:169], v[50:65]
	s_waitcnt lgkmcnt(4)
	v_mfma_f32_32x32x16_bf16 v[34:49], v[162:165], v[186:189], v[34:49]
	v_mfma_f32_32x32x16_bf16 v[18:33], v[182:185], v[166:169], v[18:33]
	v_mfma_f32_32x32x16_bf16 v[2:17], v[182:185], v[186:189], v[2:17]
	ds_read_b128 v[162:165], v89 offset:16384
	ds_read_b128 v[166:169], v89 offset:20480
	ds_read_b128 v[182:185], v88 offset:49152
	ds_read_b128 v[186:189], v88 offset:53248
	s_waitcnt lgkmcnt(6)
	v_mfma_f32_32x32x16_bf16 v[50:65], v[190:193], v[194:197], v[50:65]
	s_waitcnt lgkmcnt(4)
	v_mfma_f32_32x32x16_bf16 v[34:49], v[190:193], v[202:205], v[34:49]
	v_mfma_f32_32x32x16_bf16 v[18:33], v[198:201], v[194:197], v[18:33]
	v_mfma_f32_32x32x16_bf16 v[2:17], v[198:201], v[202:205], v[2:17]
	ds_read_b128 v[190:193], v87 offset:16384
	ds_read_b128 v[194:197], v87 offset:20480
	ds_read_b128 v[198:201], v86 offset:49152
	ds_read_b128 v[202:205], v86 offset:53248
	s_waitcnt vmcnt(0)
	s_waitcnt lgkmcnt(0)
	s_barrier
	s_add_u32 m0, s32, 0x4000
	s_nop 0
	global_load_lds_dwordx4 v[66:67], off
	s_add_u32 m0, s32, 0x5000
	s_nop 0
	global_load_lds_dwordx4 v[70:71], off
	s_add_u32 m0, s32, 0x6000
	s_nop 0
	global_load_lds_dwordx4 v[74:75], off
	s_add_u32 m0, s32, 0x7000
	s_nop 0
	global_load_lds_dwordx4 v[78:79], off
	s_add_u32 m0, s32, 0xc000
	s_nop 0
	global_load_lds_dwordx4 v[68:69], off
	s_add_u32 m0, s32, 0xd000
	s_nop 0
	global_load_lds_dwordx4 v[72:73], off
	s_add_u32 m0, s32, 0xe000
	s_nop 0
	global_load_lds_dwordx4 v[76:77], off
	s_add_u32 m0, s32, 0xf000
	s_nop 0
	global_load_lds_dwordx4 v[80:81], off
	v_lshl_add_u64 v[66:67], v[66:67], 0, 64
	v_lshl_add_u64 v[66:67], v[66:67], 0, 64
	v_lshl_add_u64 v[70:71], v[70:71], 0, 64
	v_lshl_add_u64 v[70:71], v[70:71], 0, 64
	v_lshl_add_u64 v[74:75], v[74:75], 0, 64
	v_lshl_add_u64 v[74:75], v[74:75], 0, 64
	v_lshl_add_u64 v[78:79], v[78:79], 0, 64
	v_lshl_add_u64 v[78:79], v[78:79], 0, 64
	v_lshl_add_u64 v[68:69], v[68:69], 0, 64
	v_lshl_add_u64 v[68:69], v[68:69], 0, 64
	v_lshl_add_u64 v[72:73], v[72:73], 0, 64
	v_lshl_add_u64 v[72:73], v[72:73], 0, 64
	v_lshl_add_u64 v[76:77], v[76:77], 0, 64
	v_lshl_add_u64 v[76:77], v[76:77], 0, 64
	v_lshl_add_u64 v[80:81], v[80:81], 0, 64
	v_lshl_add_u64 v[80:81], v[80:81], 0, 64
	v_mfma_f32_32x32x16_bf16 v[50:65], v[162:165], v[182:185], v[50:65]
	v_mfma_f32_32x32x16_bf16 v[34:49], v[162:165], v[186:189], v[34:49]
	v_mfma_f32_32x32x16_bf16 v[18:33], v[166:169], v[182:185], v[18:33]
	v_mfma_f32_32x32x16_bf16 v[2:17], v[166:169], v[186:189], v[2:17]
	v_mfma_f32_32x32x16_bf16 v[50:65], v[190:193], v[198:201], v[50:65]
	v_mfma_f32_32x32x16_bf16 v[34:49], v[190:193], v[202:205], v[34:49]
	v_mfma_f32_32x32x16_bf16 v[18:33], v[194:197], v[198:201], v[18:33]
	v_mfma_f32_32x32x16_bf16 v[2:17], v[194:197], v[202:205], v[2:17]
	ds_read_b128 v[162:165], v91
	ds_read_b128 v[166:169], v92 offset:32768
	ds_read_b128 v[182:185], v91 offset:4096
	ds_read_b128 v[186:189], v92 offset:36864
	ds_read_b128 v[190:193], v93
	ds_read_b128 v[194:197], v90 offset:32768
	ds_read_b128 v[198:201], v93 offset:4096
	ds_read_b128 v[202:205], v90 offset:36864
	s_waitcnt lgkmcnt(6)
	v_mfma_f32_32x32x16_bf16 v[50:65], v[162:165], v[166:169], v[50:65]
	s_waitcnt lgkmcnt(4)
	v_mfma_f32_32x32x16_bf16 v[34:49], v[162:165], v[186:189], v[34:49]
	v_mfma_f32_32x32x16_bf16 v[18:33], v[182:185], v[166:169], v[18:33]
	v_mfma_f32_32x32x16_bf16 v[2:17], v[182:185], v[186:189], v[2:17]
	ds_read_b128 v[162:165], v89
	ds_read_b128 v[166:169], v89 offset:4096
	ds_read_b128 v[182:185], v88 offset:32768
	ds_read_b128 v[186:189], v88 offset:36864
	s_waitcnt lgkmcnt(6)
	v_mfma_f32_32x32x16_bf16 v[50:65], v[190:193], v[194:197], v[50:65]
	s_waitcnt lgkmcnt(4)
	v_mfma_f32_32x32x16_bf16 v[34:49], v[190:193], v[202:205], v[34:49]
	v_mfma_f32_32x32x16_bf16 v[18:33], v[198:201], v[194:197], v[18:33]
	v_mfma_f32_32x32x16_bf16 v[2:17], v[198:201], v[202:205], v[2:17]
	ds_read_b128 v[190:193], v87
	ds_read_b128 v[194:197], v87 offset:4096
	ds_read_b128 v[198:201], v86 offset:32768
	ds_read_b128 v[202:205], v86 offset:36864
	s_waitcnt vmcnt(0)
	s_waitcnt lgkmcnt(0)
	s_barrier
	s_add_u32 m0, s32, 0x0
	s_nop 0
	global_load_lds_dwordx4 v[66:67], off
	s_add_u32 m0, s32, 0x1000
	s_nop 0
	global_load_lds_dwordx4 v[70:71], off
	s_add_u32 m0, s32, 0x2000
	s_nop 0
	global_load_lds_dwordx4 v[74:75], off
	s_add_u32 m0, s32, 0x3000
	s_nop 0
	global_load_lds_dwordx4 v[78:79], off
	s_add_u32 m0, s32, 0x8000
	s_nop 0
	global_load_lds_dwordx4 v[68:69], off
	s_add_u32 m0, s32, 0x9000
	s_nop 0
	global_load_lds_dwordx4 v[72:73], off
	s_add_u32 m0, s32, 0xa000
	s_nop 0
	global_load_lds_dwordx4 v[76:77], off
	s_add_u32 m0, s32, 0xb000
	s_nop 0
	global_load_lds_dwordx4 v[80:81], off
	v_lshl_add_u64 v[66:67], v[66:67], 0, 64
	v_lshl_add_u64 v[66:67], v[66:67], 0, 64
	v_lshl_add_u64 v[70:71], v[70:71], 0, 64
	v_lshl_add_u64 v[70:71], v[70:71], 0, 64
	v_lshl_add_u64 v[74:75], v[74:75], 0, 64
	v_lshl_add_u64 v[74:75], v[74:75], 0, 64
	v_lshl_add_u64 v[78:79], v[78:79], 0, 64
	v_lshl_add_u64 v[78:79], v[78:79], 0, 64
	v_lshl_add_u64 v[68:69], v[68:69], 0, 64
	v_lshl_add_u64 v[68:69], v[68:69], 0, 64
	v_lshl_add_u64 v[72:73], v[72:73], 0, 64
	v_lshl_add_u64 v[72:73], v[72:73], 0, 64
	v_lshl_add_u64 v[76:77], v[76:77], 0, 64
	v_lshl_add_u64 v[76:77], v[76:77], 0, 64
	v_lshl_add_u64 v[80:81], v[80:81], 0, 64
	v_lshl_add_u64 v[80:81], v[80:81], 0, 64
	v_mfma_f32_32x32x16_bf16 v[50:65], v[162:165], v[182:185], v[50:65]
	v_mfma_f32_32x32x16_bf16 v[34:49], v[162:165], v[186:189], v[34:49]
	v_mfma_f32_32x32x16_bf16 v[18:33], v[166:169], v[182:185], v[18:33]
	v_mfma_f32_32x32x16_bf16 v[2:17], v[166:169], v[186:189], v[2:17]
	v_mfma_f32_32x32x16_bf16 v[50:65], v[190:193], v[198:201], v[50:65]
	v_mfma_f32_32x32x16_bf16 v[34:49], v[190:193], v[202:205], v[34:49]
	v_mfma_f32_32x32x16_bf16 v[18:33], v[194:197], v[198:201], v[18:33]
	v_mfma_f32_32x32x16_bf16 v[2:17], v[194:197], v[202:205], v[2:17]
	ds_read_b128 v[162:165], v91 offset:16384
	ds_read_b128 v[166:169], v92 offset:49152
	ds_read_b128 v[182:185], v91 offset:20480
	ds_read_b128 v[186:189], v92 offset:53248
	ds_read_b128 v[190:193], v93 offset:16384
	ds_read_b128 v[194:197], v90 offset:49152
	ds_read_b128 v[198:201], v93 offset:20480
	ds_read_b128 v[202:205], v90 offset:53248
	s_waitcnt lgkmcnt(6)
	v_mfma_f32_32x32x16_bf16 v[50:65], v[162:165], v[166:169], v[50:65]
	s_waitcnt lgkmcnt(4)
	v_mfma_f32_32x32x16_bf16 v[34:49], v[162:165], v[186:189], v[34:49]
	v_mfma_f32_32x32x16_bf16 v[18:33], v[182:185], v[166:169], v[18:33]
	v_mfma_f32_32x32x16_bf16 v[2:17], v[182:185], v[186:189], v[2:17]
	ds_read_b128 v[162:165], v89 offset:16384
	ds_read_b128 v[166:169], v89 offset:20480
	ds_read_b128 v[182:185], v88 offset:49152
	ds_read_b128 v[186:189], v88 offset:53248
	s_waitcnt lgkmcnt(6)
	v_mfma_f32_32x32x16_bf16 v[50:65], v[190:193], v[194:197], v[50:65]
	s_waitcnt lgkmcnt(4)
	v_mfma_f32_32x32x16_bf16 v[34:49], v[190:193], v[202:205], v[34:49]
	v_mfma_f32_32x32x16_bf16 v[18:33], v[198:201], v[194:197], v[18:33]
	v_mfma_f32_32x32x16_bf16 v[2:17], v[198:201], v[202:205], v[2:17]
	ds_read_b128 v[190:193], v87 offset:16384
	ds_read_b128 v[194:197], v87 offset:20480
	ds_read_b128 v[198:201], v86 offset:49152
	ds_read_b128 v[202:205], v86 offset:53248
	s_waitcnt vmcnt(0)
	s_waitcnt lgkmcnt(0)
	s_barrier
	s_add_u32 m0, s32, 0x4000
	s_nop 0
	global_load_lds_dwordx4 v[66:67], off
	s_add_u32 m0, s32, 0x5000
	s_nop 0
	global_load_lds_dwordx4 v[70:71], off
	s_add_u32 m0, s32, 0x6000
	s_nop 0
	global_load_lds_dwordx4 v[74:75], off
	s_add_u32 m0, s32, 0x7000
	s_nop 0
	global_load_lds_dwordx4 v[78:79], off
	s_add_u32 m0, s32, 0xc000
	s_nop 0
	global_load_lds_dwordx4 v[68:69], off
	s_add_u32 m0, s32, 0xd000
	s_nop 0
	global_load_lds_dwordx4 v[72:73], off
	s_add_u32 m0, s32, 0xe000
	s_nop 0
	global_load_lds_dwordx4 v[76:77], off
	s_add_u32 m0, s32, 0xf000
	s_nop 0
	global_load_lds_dwordx4 v[80:81], off
	v_lshl_add_u64 v[66:67], v[66:67], 0, 64
	v_lshl_add_u64 v[66:67], v[66:67], 0, 64
	v_lshl_add_u64 v[70:71], v[70:71], 0, 64
	v_lshl_add_u64 v[70:71], v[70:71], 0, 64
	v_lshl_add_u64 v[74:75], v[74:75], 0, 64
	v_lshl_add_u64 v[74:75], v[74:75], 0, 64
	v_lshl_add_u64 v[78:79], v[78:79], 0, 64
	v_lshl_add_u64 v[78:79], v[78:79], 0, 64
	v_lshl_add_u64 v[68:69], v[68:69], 0, 64
	v_lshl_add_u64 v[68:69], v[68:69], 0, 64
	v_lshl_add_u64 v[72:73], v[72:73], 0, 64
	v_lshl_add_u64 v[72:73], v[72:73], 0, 64
	v_lshl_add_u64 v[76:77], v[76:77], 0, 64
	v_lshl_add_u64 v[76:77], v[76:77], 0, 64
	v_lshl_add_u64 v[80:81], v[80:81], 0, 64
	v_lshl_add_u64 v[80:81], v[80:81], 0, 64
	v_mfma_f32_32x32x16_bf16 v[50:65], v[162:165], v[182:185], v[50:65]
	v_mfma_f32_32x32x16_bf16 v[34:49], v[162:165], v[186:189], v[34:49]
	v_mfma_f32_32x32x16_bf16 v[18:33], v[166:169], v[182:185], v[18:33]
	v_mfma_f32_32x32x16_bf16 v[2:17], v[166:169], v[186:189], v[2:17]
	v_mfma_f32_32x32x16_bf16 v[50:65], v[190:193], v[198:201], v[50:65]
	v_mfma_f32_32x32x16_bf16 v[34:49], v[190:193], v[202:205], v[34:49]
	v_mfma_f32_32x32x16_bf16 v[18:33], v[194:197], v[198:201], v[18:33]
	v_mfma_f32_32x32x16_bf16 v[2:17], v[194:197], v[202:205], v[2:17]
	ds_read_b128 v[162:165], v91
	ds_read_b128 v[166:169], v92 offset:32768
	ds_read_b128 v[182:185], v91 offset:4096
	ds_read_b128 v[186:189], v92 offset:36864
	ds_read_b128 v[190:193], v93
	ds_read_b128 v[194:197], v90 offset:32768
	ds_read_b128 v[198:201], v93 offset:4096
	ds_read_b128 v[202:205], v90 offset:36864
	s_waitcnt lgkmcnt(6)
	v_mfma_f32_32x32x16_bf16 v[50:65], v[162:165], v[166:169], v[50:65]
	s_waitcnt lgkmcnt(4)
	v_mfma_f32_32x32x16_bf16 v[34:49], v[162:165], v[186:189], v[34:49]
	v_mfma_f32_32x32x16_bf16 v[18:33], v[182:185], v[166:169], v[18:33]
	v_mfma_f32_32x32x16_bf16 v[2:17], v[182:185], v[186:189], v[2:17]
	ds_read_b128 v[162:165], v89
	ds_read_b128 v[166:169], v89 offset:4096
	ds_read_b128 v[182:185], v88 offset:32768
	ds_read_b128 v[186:189], v88 offset:36864
	s_waitcnt lgkmcnt(6)
	v_mfma_f32_32x32x16_bf16 v[50:65], v[190:193], v[194:197], v[50:65]
	s_waitcnt lgkmcnt(4)
	v_mfma_f32_32x32x16_bf16 v[34:49], v[190:193], v[202:205], v[34:49]
	v_mfma_f32_32x32x16_bf16 v[18:33], v[198:201], v[194:197], v[18:33]
	v_mfma_f32_32x32x16_bf16 v[2:17], v[198:201], v[202:205], v[2:17]
	ds_read_b128 v[190:193], v87
	ds_read_b128 v[194:197], v87 offset:4096
	ds_read_b128 v[198:201], v86 offset:32768
	ds_read_b128 v[202:205], v86 offset:36864
	s_waitcnt vmcnt(0)
	s_waitcnt lgkmcnt(0)
	s_barrier
	s_add_u32 m0, s32, 0x0
	s_nop 0
	global_load_lds_dwordx4 v[66:67], off
	s_add_u32 m0, s32, 0x1000
	s_nop 0
	global_load_lds_dwordx4 v[70:71], off
	s_add_u32 m0, s32, 0x2000
	s_nop 0
	global_load_lds_dwordx4 v[74:75], off
	s_add_u32 m0, s32, 0x3000
	s_nop 0
	global_load_lds_dwordx4 v[78:79], off
	s_add_u32 m0, s32, 0x8000
	s_nop 0
	global_load_lds_dwordx4 v[68:69], off
	s_add_u32 m0, s32, 0x9000
	s_nop 0
	global_load_lds_dwordx4 v[72:73], off
	s_add_u32 m0, s32, 0xa000
	s_nop 0
	global_load_lds_dwordx4 v[76:77], off
	s_add_u32 m0, s32, 0xb000
	s_nop 0
	global_load_lds_dwordx4 v[80:81], off
	v_lshl_add_u64 v[66:67], v[66:67], 0, 64
	v_lshl_add_u64 v[66:67], v[66:67], 0, 64
	v_lshl_add_u64 v[70:71], v[70:71], 0, 64
	v_lshl_add_u64 v[70:71], v[70:71], 0, 64
	v_lshl_add_u64 v[74:75], v[74:75], 0, 64
	v_lshl_add_u64 v[74:75], v[74:75], 0, 64
	v_lshl_add_u64 v[78:79], v[78:79], 0, 64
	v_lshl_add_u64 v[78:79], v[78:79], 0, 64
	v_lshl_add_u64 v[68:69], v[68:69], 0, 64
	v_lshl_add_u64 v[68:69], v[68:69], 0, 64
	v_lshl_add_u64 v[72:73], v[72:73], 0, 64
	v_lshl_add_u64 v[72:73], v[72:73], 0, 64
	v_lshl_add_u64 v[76:77], v[76:77], 0, 64
	v_lshl_add_u64 v[76:77], v[76:77], 0, 64
	v_lshl_add_u64 v[80:81], v[80:81], 0, 64
	v_lshl_add_u64 v[80:81], v[80:81], 0, 64
	v_mfma_f32_32x32x16_bf16 v[50:65], v[162:165], v[182:185], v[50:65]
	v_mfma_f32_32x32x16_bf16 v[34:49], v[162:165], v[186:189], v[34:49]
	v_mfma_f32_32x32x16_bf16 v[18:33], v[166:169], v[182:185], v[18:33]
	v_mfma_f32_32x32x16_bf16 v[2:17], v[166:169], v[186:189], v[2:17]
	v_mfma_f32_32x32x16_bf16 v[50:65], v[190:193], v[198:201], v[50:65]
	v_mfma_f32_32x32x16_bf16 v[34:49], v[190:193], v[202:205], v[34:49]
	v_mfma_f32_32x32x16_bf16 v[18:33], v[194:197], v[198:201], v[18:33]
	v_mfma_f32_32x32x16_bf16 v[2:17], v[194:197], v[202:205], v[2:17]
	ds_read_b128 v[162:165], v91 offset:16384
	ds_read_b128 v[166:169], v92 offset:49152
	ds_read_b128 v[182:185], v91 offset:20480
	ds_read_b128 v[186:189], v92 offset:53248
	ds_read_b128 v[190:193], v93 offset:16384
	ds_read_b128 v[194:197], v90 offset:49152
	ds_read_b128 v[198:201], v93 offset:20480
	ds_read_b128 v[202:205], v90 offset:53248
	s_waitcnt lgkmcnt(6)
	v_mfma_f32_32x32x16_bf16 v[50:65], v[162:165], v[166:169], v[50:65]
	s_waitcnt lgkmcnt(4)
	v_mfma_f32_32x32x16_bf16 v[34:49], v[162:165], v[186:189], v[34:49]
	v_mfma_f32_32x32x16_bf16 v[18:33], v[182:185], v[166:169], v[18:33]
	v_mfma_f32_32x32x16_bf16 v[2:17], v[182:185], v[186:189], v[2:17]
	ds_read_b128 v[162:165], v89 offset:16384
	ds_read_b128 v[166:169], v89 offset:20480
	ds_read_b128 v[182:185], v88 offset:49152
	ds_read_b128 v[186:189], v88 offset:53248
	s_waitcnt lgkmcnt(6)
	v_mfma_f32_32x32x16_bf16 v[50:65], v[190:193], v[194:197], v[50:65]
	s_waitcnt lgkmcnt(4)
	v_mfma_f32_32x32x16_bf16 v[34:49], v[190:193], v[202:205], v[34:49]
	v_mfma_f32_32x32x16_bf16 v[18:33], v[198:201], v[194:197], v[18:33]
	v_mfma_f32_32x32x16_bf16 v[2:17], v[198:201], v[202:205], v[2:17]
	ds_read_b128 v[190:193], v87 offset:16384
	ds_read_b128 v[194:197], v87 offset:20480
	ds_read_b128 v[198:201], v86 offset:49152
	ds_read_b128 v[202:205], v86 offset:53248
	s_waitcnt vmcnt(0)
	s_waitcnt lgkmcnt(0)
	s_barrier
	s_add_u32 m0, s32, 0x4000
	s_nop 0
	global_load_lds_dwordx4 v[66:67], off
	s_add_u32 m0, s32, 0x5000
	s_nop 0
	global_load_lds_dwordx4 v[70:71], off
	s_add_u32 m0, s32, 0x6000
	s_nop 0
	global_load_lds_dwordx4 v[74:75], off
	s_add_u32 m0, s32, 0x7000
	s_nop 0
	global_load_lds_dwordx4 v[78:79], off
	s_add_u32 m0, s32, 0xc000
	s_nop 0
	global_load_lds_dwordx4 v[68:69], off
	s_add_u32 m0, s32, 0xd000
	s_nop 0
	global_load_lds_dwordx4 v[72:73], off
	s_add_u32 m0, s32, 0xe000
	s_nop 0
	global_load_lds_dwordx4 v[76:77], off
	s_add_u32 m0, s32, 0xf000
	s_nop 0
	global_load_lds_dwordx4 v[80:81], off
	v_lshl_add_u64 v[66:67], v[66:67], 0, 64
	v_lshl_add_u64 v[66:67], v[66:67], 0, 64
	v_lshl_add_u64 v[70:71], v[70:71], 0, 64
	v_lshl_add_u64 v[70:71], v[70:71], 0, 64
	v_lshl_add_u64 v[74:75], v[74:75], 0, 64
	v_lshl_add_u64 v[74:75], v[74:75], 0, 64
	v_lshl_add_u64 v[78:79], v[78:79], 0, 64
	v_lshl_add_u64 v[78:79], v[78:79], 0, 64
	v_lshl_add_u64 v[68:69], v[68:69], 0, 64
	v_lshl_add_u64 v[68:69], v[68:69], 0, 64
	v_lshl_add_u64 v[72:73], v[72:73], 0, 64
	v_lshl_add_u64 v[72:73], v[72:73], 0, 64
	v_lshl_add_u64 v[76:77], v[76:77], 0, 64
	v_lshl_add_u64 v[76:77], v[76:77], 0, 64
	v_lshl_add_u64 v[80:81], v[80:81], 0, 64
	v_lshl_add_u64 v[80:81], v[80:81], 0, 64
	v_mfma_f32_32x32x16_bf16 v[50:65], v[162:165], v[182:185], v[50:65]
	v_mfma_f32_32x32x16_bf16 v[34:49], v[162:165], v[186:189], v[34:49]
	v_mfma_f32_32x32x16_bf16 v[18:33], v[166:169], v[182:185], v[18:33]
	v_mfma_f32_32x32x16_bf16 v[2:17], v[166:169], v[186:189], v[2:17]
	v_mfma_f32_32x32x16_bf16 v[50:65], v[190:193], v[198:201], v[50:65]
	v_mfma_f32_32x32x16_bf16 v[34:49], v[190:193], v[202:205], v[34:49]
	v_mfma_f32_32x32x16_bf16 v[18:33], v[194:197], v[198:201], v[18:33]
	v_mfma_f32_32x32x16_bf16 v[2:17], v[194:197], v[202:205], v[2:17]
	ds_read_b128 v[162:165], v91
	ds_read_b128 v[166:169], v92 offset:32768
	ds_read_b128 v[182:185], v91 offset:4096
	ds_read_b128 v[186:189], v92 offset:36864
	ds_read_b128 v[190:193], v93
	ds_read_b128 v[194:197], v90 offset:32768
	ds_read_b128 v[198:201], v93 offset:4096
	ds_read_b128 v[202:205], v90 offset:36864
	s_waitcnt lgkmcnt(6)
	v_mfma_f32_32x32x16_bf16 v[50:65], v[162:165], v[166:169], v[50:65]
	s_waitcnt lgkmcnt(4)
	v_mfma_f32_32x32x16_bf16 v[34:49], v[162:165], v[186:189], v[34:49]
	v_mfma_f32_32x32x16_bf16 v[18:33], v[182:185], v[166:169], v[18:33]
	v_mfma_f32_32x32x16_bf16 v[2:17], v[182:185], v[186:189], v[2:17]
	ds_read_b128 v[162:165], v89
	ds_read_b128 v[166:169], v89 offset:4096
	ds_read_b128 v[182:185], v88 offset:32768
	ds_read_b128 v[186:189], v88 offset:36864
	s_waitcnt lgkmcnt(6)
	v_mfma_f32_32x32x16_bf16 v[50:65], v[190:193], v[194:197], v[50:65]
	s_waitcnt lgkmcnt(4)
	v_mfma_f32_32x32x16_bf16 v[34:49], v[190:193], v[202:205], v[34:49]
	v_mfma_f32_32x32x16_bf16 v[18:33], v[198:201], v[194:197], v[18:33]
	v_mfma_f32_32x32x16_bf16 v[2:17], v[198:201], v[202:205], v[2:17]
	ds_read_b128 v[190:193], v87
	ds_read_b128 v[194:197], v87 offset:4096
	ds_read_b128 v[198:201], v86 offset:32768
	ds_read_b128 v[202:205], v86 offset:36864
	s_waitcnt vmcnt(0)
	s_waitcnt lgkmcnt(0)
	s_barrier
	s_add_u32 m0, s32, 0x0
	s_nop 0
	global_load_lds_dwordx4 v[66:67], off
	s_add_u32 m0, s32, 0x1000
	s_nop 0
	global_load_lds_dwordx4 v[70:71], off
	s_add_u32 m0, s32, 0x2000
	s_nop 0
	global_load_lds_dwordx4 v[74:75], off
	s_add_u32 m0, s32, 0x3000
	s_nop 0
	global_load_lds_dwordx4 v[78:79], off
	s_add_u32 m0, s32, 0x8000
	s_nop 0
	global_load_lds_dwordx4 v[68:69], off
	s_add_u32 m0, s32, 0x9000
	s_nop 0
	global_load_lds_dwordx4 v[72:73], off
	s_add_u32 m0, s32, 0xa000
	s_nop 0
	global_load_lds_dwordx4 v[76:77], off
	s_add_u32 m0, s32, 0xb000
	s_nop 0
	global_load_lds_dwordx4 v[80:81], off
	v_lshl_add_u64 v[66:67], v[66:67], 0, 64
	v_lshl_add_u64 v[66:67], v[66:67], 0, 64
	v_lshl_add_u64 v[70:71], v[70:71], 0, 64
	v_lshl_add_u64 v[70:71], v[70:71], 0, 64
	v_lshl_add_u64 v[74:75], v[74:75], 0, 64
	v_lshl_add_u64 v[74:75], v[74:75], 0, 64
	v_lshl_add_u64 v[78:79], v[78:79], 0, 64
	v_lshl_add_u64 v[78:79], v[78:79], 0, 64
	v_lshl_add_u64 v[68:69], v[68:69], 0, 64
	v_lshl_add_u64 v[68:69], v[68:69], 0, 64
	v_lshl_add_u64 v[72:73], v[72:73], 0, 64
	v_lshl_add_u64 v[72:73], v[72:73], 0, 64
	v_lshl_add_u64 v[76:77], v[76:77], 0, 64
	v_lshl_add_u64 v[76:77], v[76:77], 0, 64
	v_lshl_add_u64 v[80:81], v[80:81], 0, 64
	v_lshl_add_u64 v[80:81], v[80:81], 0, 64
	v_mfma_f32_32x32x16_bf16 v[50:65], v[162:165], v[182:185], v[50:65]
	v_mfma_f32_32x32x16_bf16 v[34:49], v[162:165], v[186:189], v[34:49]
	v_mfma_f32_32x32x16_bf16 v[18:33], v[166:169], v[182:185], v[18:33]
	v_mfma_f32_32x32x16_bf16 v[2:17], v[166:169], v[186:189], v[2:17]
	v_mfma_f32_32x32x16_bf16 v[50:65], v[190:193], v[198:201], v[50:65]
	v_mfma_f32_32x32x16_bf16 v[34:49], v[190:193], v[202:205], v[34:49]
	v_mfma_f32_32x32x16_bf16 v[18:33], v[194:197], v[198:201], v[18:33]
	v_mfma_f32_32x32x16_bf16 v[2:17], v[194:197], v[202:205], v[2:17]
	ds_read_b128 v[162:165], v91 offset:16384
	ds_read_b128 v[166:169], v92 offset:49152
	ds_read_b128 v[182:185], v91 offset:20480
	ds_read_b128 v[186:189], v92 offset:53248
	ds_read_b128 v[190:193], v93 offset:16384
	ds_read_b128 v[194:197], v90 offset:49152
	ds_read_b128 v[198:201], v93 offset:20480
	ds_read_b128 v[202:205], v90 offset:53248
	s_waitcnt lgkmcnt(6)
	v_mfma_f32_32x32x16_bf16 v[50:65], v[162:165], v[166:169], v[50:65]
	s_waitcnt lgkmcnt(4)
	v_mfma_f32_32x32x16_bf16 v[34:49], v[162:165], v[186:189], v[34:49]
	v_mfma_f32_32x32x16_bf16 v[18:33], v[182:185], v[166:169], v[18:33]
	v_mfma_f32_32x32x16_bf16 v[2:17], v[182:185], v[186:189], v[2:17]
	ds_read_b128 v[162:165], v89 offset:16384
	ds_read_b128 v[166:169], v89 offset:20480
	ds_read_b128 v[182:185], v88 offset:49152
	ds_read_b128 v[186:189], v88 offset:53248
	s_waitcnt lgkmcnt(6)
	v_mfma_f32_32x32x16_bf16 v[50:65], v[190:193], v[194:197], v[50:65]
	s_waitcnt lgkmcnt(4)
	v_mfma_f32_32x32x16_bf16 v[34:49], v[190:193], v[202:205], v[34:49]
	v_mfma_f32_32x32x16_bf16 v[18:33], v[198:201], v[194:197], v[18:33]
	v_mfma_f32_32x32x16_bf16 v[2:17], v[198:201], v[202:205], v[2:17]
	ds_read_b128 v[190:193], v87 offset:16384
	ds_read_b128 v[194:197], v87 offset:20480
	ds_read_b128 v[198:201], v86 offset:49152
	ds_read_b128 v[202:205], v86 offset:53248
	s_waitcnt vmcnt(0)
	s_waitcnt lgkmcnt(0)
	s_barrier
	s_add_u32 m0, s32, 0x4000
	s_nop 0
	global_load_lds_dwordx4 v[66:67], off
	s_add_u32 m0, s32, 0x5000
	s_nop 0
	global_load_lds_dwordx4 v[70:71], off
	s_add_u32 m0, s32, 0x6000
	s_nop 0
	global_load_lds_dwordx4 v[74:75], off
	s_add_u32 m0, s32, 0x7000
	s_nop 0
	global_load_lds_dwordx4 v[78:79], off
	s_add_u32 m0, s32, 0xc000
	s_nop 0
	global_load_lds_dwordx4 v[68:69], off
	s_add_u32 m0, s32, 0xd000
	s_nop 0
	global_load_lds_dwordx4 v[72:73], off
	s_add_u32 m0, s32, 0xe000
	s_nop 0
	global_load_lds_dwordx4 v[76:77], off
	s_add_u32 m0, s32, 0xf000
	s_nop 0
	global_load_lds_dwordx4 v[80:81], off
	v_lshl_add_u64 v[66:67], v[66:67], 0, 64
	v_lshl_add_u64 v[66:67], v[66:67], 0, 64
	v_lshl_add_u64 v[70:71], v[70:71], 0, 64
	v_lshl_add_u64 v[70:71], v[70:71], 0, 64
	v_lshl_add_u64 v[74:75], v[74:75], 0, 64
	v_lshl_add_u64 v[74:75], v[74:75], 0, 64
	v_lshl_add_u64 v[78:79], v[78:79], 0, 64
	v_lshl_add_u64 v[78:79], v[78:79], 0, 64
	v_lshl_add_u64 v[68:69], v[68:69], 0, 64
	v_lshl_add_u64 v[68:69], v[68:69], 0, 64
	v_lshl_add_u64 v[72:73], v[72:73], 0, 64
	v_lshl_add_u64 v[72:73], v[72:73], 0, 64
	v_lshl_add_u64 v[76:77], v[76:77], 0, 64
	v_lshl_add_u64 v[76:77], v[76:77], 0, 64
	v_lshl_add_u64 v[80:81], v[80:81], 0, 64
	v_lshl_add_u64 v[80:81], v[80:81], 0, 64
	v_mfma_f32_32x32x16_bf16 v[50:65], v[162:165], v[182:185], v[50:65]
	v_mfma_f32_32x32x16_bf16 v[34:49], v[162:165], v[186:189], v[34:49]
	v_mfma_f32_32x32x16_bf16 v[18:33], v[166:169], v[182:185], v[18:33]
	v_mfma_f32_32x32x16_bf16 v[2:17], v[166:169], v[186:189], v[2:17]
	v_mfma_f32_32x32x16_bf16 v[50:65], v[190:193], v[198:201], v[50:65]
	v_mfma_f32_32x32x16_bf16 v[34:49], v[190:193], v[202:205], v[34:49]
	v_mfma_f32_32x32x16_bf16 v[18:33], v[194:197], v[198:201], v[18:33]
	v_mfma_f32_32x32x16_bf16 v[2:17], v[194:197], v[202:205], v[2:17]
	ds_read_b128 v[162:165], v91
	ds_read_b128 v[166:169], v92 offset:32768
	ds_read_b128 v[182:185], v91 offset:4096
	ds_read_b128 v[186:189], v92 offset:36864
	ds_read_b128 v[190:193], v93
	ds_read_b128 v[194:197], v90 offset:32768
	ds_read_b128 v[198:201], v93 offset:4096
	ds_read_b128 v[202:205], v90 offset:36864
	s_waitcnt lgkmcnt(6)
	v_mfma_f32_32x32x16_bf16 v[50:65], v[162:165], v[166:169], v[50:65]
	s_waitcnt lgkmcnt(4)
	v_mfma_f32_32x32x16_bf16 v[34:49], v[162:165], v[186:189], v[34:49]
	v_mfma_f32_32x32x16_bf16 v[18:33], v[182:185], v[166:169], v[18:33]
	v_mfma_f32_32x32x16_bf16 v[2:17], v[182:185], v[186:189], v[2:17]
	ds_read_b128 v[162:165], v89
	ds_read_b128 v[166:169], v89 offset:4096
	ds_read_b128 v[182:185], v88 offset:32768
	ds_read_b128 v[186:189], v88 offset:36864
	s_waitcnt lgkmcnt(6)
	v_mfma_f32_32x32x16_bf16 v[50:65], v[190:193], v[194:197], v[50:65]
	s_waitcnt lgkmcnt(4)
	v_mfma_f32_32x32x16_bf16 v[34:49], v[190:193], v[202:205], v[34:49]
	v_mfma_f32_32x32x16_bf16 v[18:33], v[198:201], v[194:197], v[18:33]
	v_mfma_f32_32x32x16_bf16 v[2:17], v[198:201], v[202:205], v[2:17]
	ds_read_b128 v[190:193], v87
	ds_read_b128 v[194:197], v87 offset:4096
	ds_read_b128 v[198:201], v86 offset:32768
	ds_read_b128 v[202:205], v86 offset:36864
	s_waitcnt vmcnt(0)
	s_waitcnt lgkmcnt(0)
	s_barrier
	s_add_u32 m0, s32, 0x0
	s_nop 0
	global_load_lds_dwordx4 v[66:67], off
	s_add_u32 m0, s32, 0x1000
	s_nop 0
	global_load_lds_dwordx4 v[70:71], off
	s_add_u32 m0, s32, 0x2000
	s_nop 0
	global_load_lds_dwordx4 v[74:75], off
	s_add_u32 m0, s32, 0x3000
	s_nop 0
	global_load_lds_dwordx4 v[78:79], off
	s_add_u32 m0, s32, 0x8000
	s_nop 0
	global_load_lds_dwordx4 v[68:69], off
	s_add_u32 m0, s32, 0x9000
	s_nop 0
	global_load_lds_dwordx4 v[72:73], off
	s_add_u32 m0, s32, 0xa000
	s_nop 0
	global_load_lds_dwordx4 v[76:77], off
	s_add_u32 m0, s32, 0xb000
	s_nop 0
	global_load_lds_dwordx4 v[80:81], off
	v_lshl_add_u64 v[66:67], v[66:67], 0, 64
	v_lshl_add_u64 v[66:67], v[66:67], 0, 64
	v_lshl_add_u64 v[70:71], v[70:71], 0, 64
	v_lshl_add_u64 v[70:71], v[70:71], 0, 64
	v_lshl_add_u64 v[74:75], v[74:75], 0, 64
	v_lshl_add_u64 v[74:75], v[74:75], 0, 64
	v_lshl_add_u64 v[78:79], v[78:79], 0, 64
	v_lshl_add_u64 v[78:79], v[78:79], 0, 64
	v_lshl_add_u64 v[68:69], v[68:69], 0, 64
	v_lshl_add_u64 v[68:69], v[68:69], 0, 64
	v_lshl_add_u64 v[72:73], v[72:73], 0, 64
	v_lshl_add_u64 v[72:73], v[72:73], 0, 64
	v_lshl_add_u64 v[76:77], v[76:77], 0, 64
	v_lshl_add_u64 v[76:77], v[76:77], 0, 64
	v_lshl_add_u64 v[80:81], v[80:81], 0, 64
	v_lshl_add_u64 v[80:81], v[80:81], 0, 64
	s_nop 0
	s_nop 0
	s_nop 0
	s_nop 0
	s_nop 0
	s_nop 0
	s_nop 0
	v_mfma_f32_32x32x16_bf16 v[50:65], v[162:165], v[182:185], v[50:65]
	v_mfma_f32_32x32x16_bf16 v[34:49], v[162:165], v[186:189], v[34:49]
	v_mfma_f32_32x32x16_bf16 v[18:33], v[166:169], v[182:185], v[18:33]
	v_mfma_f32_32x32x16_bf16 v[2:17], v[166:169], v[186:189], v[2:17]
	ds_read_b128 v[110:113], v91 offset:16384
	ds_read_b128 v[114:117], v91 offset:20480
	ds_read_b128 v[118:121], v92 offset:49152
	ds_read_b128 v[122:125], v92 offset:53248
	ds_read_b128 v[162:165], v93 offset:16384
	ds_read_b128 v[166:169], v93 offset:20480
	ds_read_b128 v[182:185], v90 offset:49152
	ds_read_b128 v[186:189], v90 offset:53248
	v_mfma_f32_32x32x16_bf16 v[50:65], v[190:193], v[198:201], v[50:65]
	v_mfma_f32_32x32x16_bf16 v[34:49], v[190:193], v[202:205], v[34:49]
	v_mfma_f32_32x32x16_bf16 v[18:33], v[194:197], v[198:201], v[18:33]
	v_mfma_f32_32x32x16_bf16 v[2:17], v[194:197], v[202:205], v[2:17]
	s_waitcnt lgkmcnt(5)
	v_mfma_f32_32x32x16_bf16 v[50:65], v[110:113], v[118:121], v[50:65]
	s_waitcnt lgkmcnt(4)
	v_mfma_f32_32x32x16_bf16 v[34:49], v[110:113], v[122:125], v[34:49]
	v_mfma_f32_32x32x16_bf16 v[18:33], v[114:117], v[118:121], v[18:33]
	v_mfma_f32_32x32x16_bf16 v[2:17], v[114:117], v[122:125], v[2:17]
	ds_read_b128 v[110:113], v89 offset:16384
	ds_read_b128 v[114:117], v89 offset:20480
	ds_read_b128 v[118:121], v88 offset:49152
	ds_read_b128 v[122:125], v88 offset:53248
	s_waitcnt lgkmcnt(5)
	v_mfma_f32_32x32x16_bf16 v[50:65], v[162:165], v[182:185], v[50:65]
	s_waitcnt lgkmcnt(4)
	v_mfma_f32_32x32x16_bf16 v[34:49], v[162:165], v[186:189], v[34:49]
	v_mfma_f32_32x32x16_bf16 v[18:33], v[166:169], v[182:185], v[18:33]
	v_mfma_f32_32x32x16_bf16 v[2:17], v[166:169], v[186:189], v[2:17]
	ds_read_b128 v[162:165], v87 offset:16384
	ds_read_b128 v[166:169], v87 offset:20480
	ds_read_b128 v[182:185], v86 offset:49152
	ds_read_b128 v[186:189], v86 offset:53248
	s_waitcnt lgkmcnt(5)
	v_mfma_f32_32x32x16_bf16 v[50:65], v[110:113], v[118:121], v[50:65]
	s_waitcnt vmcnt(0)
	s_waitcnt lgkmcnt(0)
	s_barrier
	s_add_u32 m0, s32, 0x4000
	s_nop 0
	global_load_lds_dwordx4 v[66:67], off
	s_add_u32 m0, s32, 0x5000
	s_nop 0
	global_load_lds_dwordx4 v[70:71], off
	s_add_u32 m0, s32, 0x6000
	s_nop 0
	global_load_lds_dwordx4 v[74:75], off
	s_add_u32 m0, s32, 0x7000
	s_nop 0
	global_load_lds_dwordx4 v[78:79], off
	s_add_u32 m0, s32, 0xc000
	s_nop 0
	global_load_lds_dwordx4 v[68:69], off
	s_add_u32 m0, s32, 0xd000
	s_nop 0
	global_load_lds_dwordx4 v[72:73], off
	s_add_u32 m0, s32, 0xe000
	s_nop 0
	global_load_lds_dwordx4 v[76:77], off
	s_add_u32 m0, s32, 0xf000
	s_nop 0
	global_load_lds_dwordx4 v[80:81], off
	v_lshl_add_u64 v[66:67], v[66:67], 0, 64
	v_lshl_add_u64 v[66:67], v[66:67], 0, 64
	v_lshl_add_u64 v[70:71], v[70:71], 0, 64
	v_lshl_add_u64 v[70:71], v[70:71], 0, 64
	v_lshl_add_u64 v[74:75], v[74:75], 0, 64
	v_lshl_add_u64 v[74:75], v[74:75], 0, 64
	v_lshl_add_u64 v[78:79], v[78:79], 0, 64
	v_lshl_add_u64 v[78:79], v[78:79], 0, 64
	v_lshl_add_u64 v[68:69], v[68:69], 0, 64
	v_lshl_add_u64 v[68:69], v[68:69], 0, 64
	v_lshl_add_u64 v[72:73], v[72:73], 0, 64
	v_lshl_add_u64 v[72:73], v[72:73], 0, 64
	v_lshl_add_u64 v[76:77], v[76:77], 0, 64
	v_lshl_add_u64 v[76:77], v[76:77], 0, 64
	v_lshl_add_u64 v[80:81], v[80:81], 0, 64
	v_lshl_add_u64 v[80:81], v[80:81], 0, 64
	v_mfma_f32_32x32x16_bf16 v[34:49], v[110:113], v[122:125], v[34:49]
	v_mfma_f32_32x32x16_bf16 v[18:33], v[114:117], v[118:121], v[18:33]
	v_mfma_f32_32x32x16_bf16 v[2:17], v[114:117], v[122:125], v[2:17]
	ds_read_b128 v[110:113], v91
	ds_read_b128 v[114:117], v91 offset:4096
	ds_read_b128 v[118:121], v92 offset:32768
	ds_read_b128 v[122:125], v92 offset:36864
	ds_read_b128 v[126:129], v93
	ds_read_b128 v[134:137], v93 offset:4096
	ds_read_b128 v[138:141], v90 offset:32768
	ds_read_b128 v[142:145], v90 offset:36864
	v_mfma_f32_32x32x16_bf16 v[50:65], v[162:165], v[182:185], v[50:65]
	v_mfma_f32_32x32x16_bf16 v[34:49], v[162:165], v[186:189], v[34:49]
	v_mfma_f32_32x32x16_bf16 v[18:33], v[166:169], v[182:185], v[18:33]
	v_mfma_f32_32x32x16_bf16 v[2:17], v[166:169], v[186:189], v[2:17]
	s_waitcnt lgkmcnt(5)
	v_mfma_f32_32x32x16_bf16 v[50:65], v[110:113], v[118:121], v[50:65]
	s_waitcnt lgkmcnt(4)
	v_mfma_f32_32x32x16_bf16 v[34:49], v[110:113], v[122:125], v[34:49]
	v_mfma_f32_32x32x16_bf16 v[18:33], v[114:117], v[118:121], v[18:33]
	v_mfma_f32_32x32x16_bf16 v[2:17], v[114:117], v[122:125], v[2:17]
	ds_read_b128 v[110:113], v89
	ds_read_b128 v[114:117], v89 offset:4096
	ds_read_b128 v[118:121], v88 offset:32768
	ds_read_b128 v[122:125], v88 offset:36864
	s_waitcnt lgkmcnt(5)
	v_mfma_f32_32x32x16_bf16 v[50:65], v[126:129], v[138:141], v[50:65]
	s_waitcnt lgkmcnt(4)
	v_mfma_f32_32x32x16_bf16 v[34:49], v[126:129], v[142:145], v[34:49]
	v_mfma_f32_32x32x16_bf16 v[18:33], v[134:137], v[138:141], v[18:33]
	v_mfma_f32_32x32x16_bf16 v[2:17], v[134:137], v[142:145], v[2:17]
	ds_read_b128 v[126:129], v87
	ds_read_b128 v[134:137], v87 offset:4096
	ds_read_b128 v[138:141], v86 offset:32768
	ds_read_b128 v[142:145], v86 offset:36864
	s_waitcnt vmcnt(0)
	s_waitcnt lgkmcnt(0)
	s_barrier
	ds_read_b128 v[66:69], v91 offset:16384
	ds_read_b128 v[70:73], v91 offset:20480
	ds_read_b128 v[74:77], v92 offset:49152
	ds_read_b128 v[78:81], v92 offset:53248
	ds_read_b128 v[94:97], v93 offset:16384
	ds_read_b128 v[98:101], v93 offset:20480
	ds_read_b128 v[102:105], v90 offset:49152
	ds_read_b128 v[90:93], v90 offset:53248
	v_mfma_f32_32x32x16_bf16 v[50:65], v[110:113], v[118:121], v[50:65]
	v_mfma_f32_32x32x16_bf16 v[34:49], v[110:113], v[122:125], v[34:49]
	v_mfma_f32_32x32x16_bf16 v[18:33], v[114:117], v[118:121], v[18:33]
	v_mfma_f32_32x32x16_bf16 v[2:17], v[114:117], v[122:125], v[2:17]
	v_mfma_f32_32x32x16_bf16 v[50:65], v[126:129], v[138:141], v[50:65]
	v_mfma_f32_32x32x16_bf16 v[34:49], v[126:129], v[142:145], v[34:49]
	v_mfma_f32_32x32x16_bf16 v[18:33], v[134:137], v[138:141], v[18:33]
	v_mfma_f32_32x32x16_bf16 v[2:17], v[134:137], v[142:145], v[2:17]
	s_waitcnt lgkmcnt(5)
	v_mfma_f32_32x32x16_bf16 v[50:65], v[66:69], v[74:77], v[50:65]
	s_waitcnt lgkmcnt(4)
	v_mfma_f32_32x32x16_bf16 v[34:49], v[66:69], v[78:81], v[34:49]
	v_mfma_f32_32x32x16_bf16 v[18:33], v[70:73], v[74:77], v[18:33]
	v_mfma_f32_32x32x16_bf16 v[2:17], v[70:73], v[78:81], v[2:17]
	ds_read_b128 v[66:69], v89 offset:16384
	ds_read_b128 v[70:73], v89 offset:20480
	ds_read_b128 v[74:77], v88 offset:49152
	ds_read_b128 v[78:81], v88 offset:53248
	s_waitcnt lgkmcnt(5)
	v_mfma_f32_32x32x16_bf16 v[50:65], v[94:97], v[102:105], v[50:65]
	s_waitcnt lgkmcnt(4)
	v_mfma_f32_32x32x16_bf16 v[34:49], v[94:97], v[90:93], v[34:49]
	v_mfma_f32_32x32x16_bf16 v[18:33], v[98:101], v[102:105], v[18:33]
	v_mfma_f32_32x32x16_bf16 v[2:17], v[98:101], v[90:93], v[2:17]
	ds_read_b128 v[88:91], v87 offset:16384
	ds_read_b128 v[92:95], v87 offset:20480
	ds_read_b128 v[96:99], v86 offset:49152
	ds_read_b128 v[100:103], v86 offset:53248
	s_waitcnt lgkmcnt(5)
	v_mfma_f32_32x32x16_bf16 v[50:65], v[66:69], v[74:77], v[50:65]
	v_lshlrev_b32_e32 v0, 6, v85
	v_lshlrev_b32_e32 v84, 6, v84
	v_subrev_u32_e32 v0, s6, v0
	v_add_u32_e32 v0, s4, v0
	v_ashrrev_i32_e32 v0, 6, v0
	v_lshlrev_b32_e32 v85, 2, v83
	s_waitcnt lgkmcnt(0)
	v_mfma_f32_32x32x16_bf16 v[50:65], v[88:91], v[96:99], v[50:65]
	s_barrier
	v_or_b32_e32 v83, 2, v84
	v_or_b32_e32 v86, 3, v84
	v_or_b32_e32 v87, 8, v85
	s_add_i32 s5, s5, s66
	s_add_i32 s4, s4, s3
	v_mfma_f32_32x32x16_bf16 v[34:49], v[66:69], v[78:81], v[34:49]
	v_lshl_add_u32 v66, s34, 7, v84
	v_ashrrev_i32_e32 v66, 1, v66
	v_and_b32_e32 v66, 0xffffffc0, v66
	v_add_u32_e32 v66, v66, v0
	v_ashrrev_i32_e32 v67, 31, v66
	v_lshlrev_b64 v[66:67], 14, v[66:67]
	v_lshl_add_u64 v[66:67], s[50:51], 0, v[66:67]
	v_lshlrev_b32_e32 v0, 1, v82
	v_lshl_add_u64 v[66:67], v[66:67], 0, v[0:1]
	v_max_f32_e32 v0, v50, v50
	v_max_f32_e32 v0, 0, v0
	v_or_b32_e32 v68, v85, v84
	v_mul_f32_e32 v0, v0, v0
	v_cvt_pk_bf16_f32 v50, v0, s0
	v_lshlrev_b32_e32 v0, 7, v68
	v_and_b32_e32 v0, 0x2200, v0
	v_lshl_add_u64 v[68:69], v[66:67], 0, v[0:1]
	v_or_b32_e32 v82, 1, v84
	global_store_short v[68:69], v50, off
	v_or_b32_e32 v0, v85, v82
	v_max_f32_e32 v50, v51, v51
	v_max_f32_e32 v50, 0, v50
	v_lshlrev_b32_e32 v0, 7, v0
	v_mul_f32_e32 v50, v50, v50
	v_and_b32_e32 v0, 0x2280, v0
	v_mfma_f32_32x32x16_bf16 v[18:33], v[70:73], v[74:77], v[18:33]
	v_max_f32_e32 v52, v52, v52
	v_max_f32_e32 v52, 0, v52
	v_mul_f32_e32 v52, v52, v52
	v_cvt_pk_bf16_f32 v52, v52, s0
	v_max_f32_e32 v54, v54, v54
	v_max_f32_e32 v54, 0, v54
	v_mul_f32_e32 v54, v54, v54
	v_mfma_f32_32x32x16_bf16 v[2:17], v[70:73], v[78:81], v[2:17]
	v_cvt_pk_bf16_f32 v70, v50, s0
	v_lshl_add_u64 v[50:51], v[66:67], 0, v[0:1]
	v_or_b32_e32 v0, v85, v83
	v_lshlrev_b32_e32 v0, 7, v0
	v_and_b32_e32 v0, 0x2300, v0
	global_store_short v[50:51], v70, off
	v_lshl_add_u64 v[70:71], v[66:67], 0, v[0:1]
	global_store_short v[70:71], v52, off
	v_or_b32_e32 v0, v85, v86
	v_max_f32_e32 v52, v53, v53
	v_max_f32_e32 v52, 0, v52
	v_lshlrev_b32_e32 v0, 7, v0
	v_mul_f32_e32 v52, v52, v52
	v_and_b32_e32 v0, 0x2380, v0
	v_cvt_pk_bf16_f32 v72, v52, s0
	v_lshl_add_u64 v[52:53], v[66:67], 0, v[0:1]
	v_or_b32_e32 v0, v87, v84
	v_lshlrev_b32_e32 v0, 7, v0
	v_and_b32_e32 v0, 0x2600, v0
	global_store_short v[52:53], v72, off
	v_cvt_pk_bf16_f32 v54, v54, s0
	v_lshl_add_u64 v[72:73], v[66:67], 0, v[0:1]
	global_store_short v[72:73], v54, off
	v_or_b32_e32 v0, v87, v82
	v_max_f32_e32 v54, v55, v55
	v_max_f32_e32 v54, 0, v54
	v_lshlrev_b32_e32 v0, 7, v0
	v_mul_f32_e32 v54, v54, v54
	v_and_b32_e32 v0, 0x2680, v0
	v_cvt_pk_bf16_f32 v74, v54, s0
	v_lshl_add_u64 v[54:55], v[66:67], 0, v[0:1]
	v_or_b32_e32 v0, v87, v83
	v_max_f32_e32 v56, v56, v56
	v_max_f32_e32 v56, 0, v56
	v_lshlrev_b32_e32 v0, 7, v0
	v_mul_f32_e32 v56, v56, v56
	v_and_b32_e32 v0, 0x2700, v0
	global_store_short v[54:55], v74, off
	v_cvt_pk_bf16_f32 v56, v56, s0
	v_lshl_add_u64 v[74:75], v[66:67], 0, v[0:1]
	global_store_short v[74:75], v56, off
	v_or_b32_e32 v0, v87, v86
	v_max_f32_e32 v56, v57, v57
	v_max_f32_e32 v56, 0, v56
	v_lshlrev_b32_e32 v0, 7, v0
	v_mfma_f32_32x32x16_bf16 v[34:49], v[88:91], v[100:103], v[34:49]
	v_mul_f32_e32 v56, v56, v56
	v_and_b32_e32 v0, 0x2780, v0
	v_or_b32_e32 v88, 16, v85
	v_cvt_pk_bf16_f32 v76, v56, s0
	v_lshl_add_u64 v[56:57], v[66:67], 0, v[0:1]
	v_or_b32_e32 v0, v88, v84
	v_max_f32_e32 v58, v58, v58
	v_max_f32_e32 v58, 0, v58
	v_lshlrev_b32_e32 v0, 7, v0
	v_mul_f32_e32 v58, v58, v58
	v_and_b32_e32 v0, 0x2a00, v0
	global_store_short v[56:57], v76, off
	v_cvt_pk_bf16_f32 v58, v58, s0
	v_lshl_add_u64 v[76:77], v[66:67], 0, v[0:1]
	global_store_short v[76:77], v58, off
	v_or_b32_e32 v0, v88, v82
	v_max_f32_e32 v58, v59, v59
	v_max_f32_e32 v58, 0, v58
	v_lshlrev_b32_e32 v0, 7, v0
	v_mul_f32_e32 v58, v58, v58
	v_and_b32_e32 v0, 0x2a80, v0
	v_cvt_pk_bf16_f32 v78, v58, s0
	v_lshl_add_u64 v[58:59], v[66:67], 0, v[0:1]
	v_or_b32_e32 v0, v88, v83
	v_max_f32_e32 v60, v60, v60
	v_max_f32_e32 v60, 0, v60
	v_lshlrev_b32_e32 v0, 7, v0
	v_mul_f32_e32 v60, v60, v60
	v_and_b32_e32 v0, 0x2b00, v0
	global_store_short v[58:59], v78, off
	v_cvt_pk_bf16_f32 v60, v60, s0
	v_lshl_add_u64 v[78:79], v[66:67], 0, v[0:1]
	global_store_short v[78:79], v60, off
	v_or_b32_e32 v0, v88, v86
	v_max_f32_e32 v60, v61, v61
	v_max_f32_e32 v60, 0, v60
	v_lshlrev_b32_e32 v0, 7, v0
	v_mul_f32_e32 v60, v60, v60
	v_and_b32_e32 v0, 0x2b80, v0
	v_or_b32_e32 v89, 24, v85
	v_cvt_pk_bf16_f32 v80, v60, s0
	v_lshl_add_u64 v[60:61], v[66:67], 0, v[0:1]
	v_or_b32_e32 v0, v89, v84
	v_max_f32_e32 v62, v62, v62
	v_max_f32_e32 v62, 0, v62
	v_lshlrev_b32_e32 v0, 7, v0
	v_mul_f32_e32 v62, v62, v62
	v_and_b32_e32 v0, 0x2e00, v0
	global_store_short v[60:61], v80, off
	v_cvt_pk_bf16_f32 v62, v62, s0
	v_lshl_add_u64 v[80:81], v[66:67], 0, v[0:1]
	global_store_short v[80:81], v62, off
	v_or_b32_e32 v0, v89, v82
	v_max_f32_e32 v62, v63, v63
	v_max_f32_e32 v62, 0, v62
	v_lshlrev_b32_e32 v0, 7, v0
	v_mul_f32_e32 v62, v62, v62
	v_and_b32_e32 v0, 0x2e80, v0
	v_cvt_pk_bf16_f32 v82, v62, s0
	v_lshl_add_u64 v[62:63], v[66:67], 0, v[0:1]
	v_or_b32_e32 v0, v89, v83
	v_max_f32_e32 v64, v64, v64
	v_max_f32_e32 v64, 0, v64
	v_lshlrev_b32_e32 v0, 7, v0
	v_mul_f32_e32 v64, v64, v64
	v_and_b32_e32 v0, 0x2f00, v0
	global_store_short v[62:63], v82, off
	v_cvt_pk_bf16_f32 v64, v64, s0
	v_lshl_add_u64 v[82:83], v[66:67], 0, v[0:1]
	global_store_short v[82:83], v64, off
	v_or_b32_e32 v0, v89, v86
	v_max_f32_e32 v64, v65, v65
	v_max_f32_e32 v64, 0, v64
	v_lshlrev_b32_e32 v0, 7, v0
	v_mul_f32_e32 v64, v64, v64
	v_and_b32_e32 v0, 0x2f80, v0
	v_cvt_pk_bf16_f32 v86, v64, s0
	v_lshl_add_u64 v[64:65], v[66:67], 0, v[0:1]
	v_max_f32_e32 v0, v34, v34
	v_max_f32_e32 v0, 0, v0
	v_mul_f32_e32 v0, v0, v0
	v_cvt_pk_bf16_f32 v0, v0, s0
	global_store_short v[64:65], v86, off
	global_store_short v[68:69], v0, off offset:64
	v_max_f32_e32 v0, v35, v35
	v_max_f32_e32 v0, 0, v0
	v_mul_f32_e32 v0, v0, v0
	v_cvt_pk_bf16_f32 v0, v0, s0
	global_store_short v[50:51], v0, off offset:64
	v_max_f32_e32 v0, v36, v36
	v_max_f32_e32 v0, 0, v0
	v_mul_f32_e32 v0, v0, v0
	v_cvt_pk_bf16_f32 v0, v0, s0
	global_store_short v[70:71], v0, off offset:64
	v_max_f32_e32 v0, v37, v37
	v_max_f32_e32 v0, 0, v0
	v_mul_f32_e32 v0, v0, v0
	v_cvt_pk_bf16_f32 v0, v0, s0
	global_store_short v[52:53], v0, off offset:64
	v_max_f32_e32 v0, v38, v38
	v_max_f32_e32 v0, 0, v0
	v_mul_f32_e32 v0, v0, v0
	v_cvt_pk_bf16_f32 v0, v0, s0
	global_store_short v[72:73], v0, off offset:64
	v_max_f32_e32 v0, v39, v39
	v_max_f32_e32 v0, 0, v0
	v_mul_f32_e32 v0, v0, v0
	v_cvt_pk_bf16_f32 v0, v0, s0
	global_store_short v[54:55], v0, off offset:64
	v_max_f32_e32 v0, v40, v40
	v_max_f32_e32 v0, 0, v0
	v_mul_f32_e32 v0, v0, v0
	v_cvt_pk_bf16_f32 v0, v0, s0
	global_store_short v[74:75], v0, off offset:64
	v_max_f32_e32 v0, v41, v41
	v_max_f32_e32 v0, 0, v0
	v_mul_f32_e32 v0, v0, v0
	v_cvt_pk_bf16_f32 v0, v0, s0
	global_store_short v[56:57], v0, off offset:64
	v_max_f32_e32 v0, v42, v42
	v_max_f32_e32 v0, 0, v0
	v_mul_f32_e32 v0, v0, v0
	v_cvt_pk_bf16_f32 v0, v0, s0
	global_store_short v[76:77], v0, off offset:64
	v_max_f32_e32 v0, v43, v43
	v_max_f32_e32 v0, 0, v0
	v_mul_f32_e32 v0, v0, v0
	v_cvt_pk_bf16_f32 v0, v0, s0
	global_store_short v[58:59], v0, off offset:64
	v_max_f32_e32 v0, v44, v44
	v_max_f32_e32 v0, 0, v0
	v_mul_f32_e32 v0, v0, v0
	v_cvt_pk_bf16_f32 v0, v0, s0
	global_store_short v[78:79], v0, off offset:64
	v_max_f32_e32 v0, v45, v45
	v_max_f32_e32 v0, 0, v0
	v_mul_f32_e32 v0, v0, v0
	v_cvt_pk_bf16_f32 v0, v0, s0
	global_store_short v[60:61], v0, off offset:64
	v_max_f32_e32 v0, v46, v46
	v_max_f32_e32 v0, 0, v0
	v_mul_f32_e32 v0, v0, v0
	v_cvt_pk_bf16_f32 v0, v0, s0
	global_store_short v[80:81], v0, off offset:64
	v_max_f32_e32 v0, v47, v47
	v_max_f32_e32 v0, 0, v0
	v_mul_f32_e32 v0, v0, v0
	v_cvt_pk_bf16_f32 v0, v0, s0
	v_mfma_f32_32x32x16_bf16 v[18:33], v[92:95], v[96:99], v[18:33]
	global_store_short v[62:63], v0, off offset:64
	v_max_f32_e32 v0, v48, v48
	v_max_f32_e32 v0, 0, v0
	v_mul_f32_e32 v0, v0, v0
	v_cvt_pk_bf16_f32 v0, v0, s0
	global_store_short v[82:83], v0, off offset:64
	v_max_f32_e32 v0, v49, v49
	v_max_f32_e32 v0, 0, v0
	v_mul_f32_e32 v0, v0, v0
	v_cvt_pk_bf16_f32 v0, v0, s0
	v_or_b32_e32 v46, 32, v84
	global_store_short v[64:65], v0, off offset:64
	v_or_b32_e32 v0, v85, v46
	v_max_f32_e32 v18, v18, v18
	v_max_f32_e32 v18, 0, v18
	v_lshlrev_b32_e32 v0, 7, v0
	v_mul_f32_e32 v18, v18, v18
	v_and_b32_e32 v0, 0x3200, v0
	v_cvt_pk_bf16_f32 v18, v18, s0
	v_lshl_add_u64 v[34:35], v[66:67], 0, v[0:1]
	v_or_b32_e32 v48, 33, v84
	global_store_short v[34:35], v18, off
	v_or_b32_e32 v0, v85, v48
	v_max_f32_e32 v18, v19, v19
	v_max_f32_e32 v18, 0, v18
	v_lshlrev_b32_e32 v0, 7, v0
	v_mul_f32_e32 v18, v18, v18
	v_and_b32_e32 v0, 0x3280, v0
	v_or_b32_e32 v49, 34, v84
	v_cvt_pk_bf16_f32 v36, v18, s0
	v_lshl_add_u64 v[18:19], v[66:67], 0, v[0:1]
	v_or_b32_e32 v0, v85, v49
	v_max_f32_e32 v20, v20, v20
	v_max_f32_e32 v20, 0, v20
	v_lshlrev_b32_e32 v0, 7, v0
	v_mul_f32_e32 v20, v20, v20
	v_and_b32_e32 v0, 0x3300, v0
	global_store_short v[18:19], v36, off
	v_cvt_pk_bf16_f32 v20, v20, s0
	v_lshl_add_u64 v[36:37], v[66:67], 0, v[0:1]
	v_or_b32_e32 v50, 35, v84
	global_store_short v[36:37], v20, off
	v_or_b32_e32 v0, v85, v50
	v_max_f32_e32 v20, v21, v21
	v_max_f32_e32 v20, 0, v20
	v_lshlrev_b32_e32 v0, 7, v0
	v_mul_f32_e32 v20, v20, v20
	v_and_b32_e32 v0, 0x3380, v0
	v_cvt_pk_bf16_f32 v38, v20, s0
	v_lshl_add_u64 v[20:21], v[66:67], 0, v[0:1]
	v_or_b32_e32 v0, v87, v46
	v_max_f32_e32 v22, v22, v22
	v_max_f32_e32 v22, 0, v22
	v_lshlrev_b32_e32 v0, 7, v0
	v_mul_f32_e32 v22, v22, v22
	v_and_b32_e32 v0, 0x3600, v0
	global_store_short v[20:21], v38, off
	v_cvt_pk_bf16_f32 v22, v22, s0
	v_lshl_add_u64 v[38:39], v[66:67], 0, v[0:1]
	global_store_short v[38:39], v22, off
	v_or_b32_e32 v0, v87, v48
	v_max_f32_e32 v22, v23, v23
	v_max_f32_e32 v22, 0, v22
	v_lshlrev_b32_e32 v0, 7, v0
	v_mul_f32_e32 v22, v22, v22
	v_and_b32_e32 v0, 0x3680, v0
	v_cvt_pk_bf16_f32 v40, v22, s0
	v_lshl_add_u64 v[22:23], v[66:67], 0, v[0:1]
	v_or_b32_e32 v0, v87, v49
	v_max_f32_e32 v24, v24, v24
	v_max_f32_e32 v24, 0, v24
	v_lshlrev_b32_e32 v0, 7, v0
	v_mul_f32_e32 v24, v24, v24
	v_and_b32_e32 v0, 0x3700, v0
	global_store_short v[22:23], v40, off
	v_cvt_pk_bf16_f32 v24, v24, s0
	v_lshl_add_u64 v[40:41], v[66:67], 0, v[0:1]
	global_store_short v[40:41], v24, off
	v_or_b32_e32 v0, v87, v50
	v_max_f32_e32 v24, v25, v25
	v_max_f32_e32 v24, 0, v24
	v_lshlrev_b32_e32 v0, 7, v0
	v_mul_f32_e32 v24, v24, v24
	v_and_b32_e32 v0, 0x3780, v0
	v_cvt_pk_bf16_f32 v42, v24, s0
	v_lshl_add_u64 v[24:25], v[66:67], 0, v[0:1]
	v_or_b32_e32 v0, v88, v46
	v_max_f32_e32 v26, v26, v26
	v_max_f32_e32 v26, 0, v26
	v_lshlrev_b32_e32 v0, 7, v0
	v_mul_f32_e32 v26, v26, v26
	v_and_b32_e32 v0, 0x3a00, v0
	global_store_short v[24:25], v42, off
	v_cvt_pk_bf16_f32 v26, v26, s0
	v_lshl_add_u64 v[42:43], v[66:67], 0, v[0:1]
	global_store_short v[42:43], v26, off
	v_or_b32_e32 v0, v88, v48
	v_max_f32_e32 v26, v27, v27
	v_max_f32_e32 v26, 0, v26
	v_lshlrev_b32_e32 v0, 7, v0
	v_mul_f32_e32 v26, v26, v26
	v_and_b32_e32 v0, 0x3a80, v0
	v_cvt_pk_bf16_f32 v44, v26, s0
	v_lshl_add_u64 v[26:27], v[66:67], 0, v[0:1]
	v_or_b32_e32 v0, v88, v49
	v_max_f32_e32 v28, v28, v28
	v_max_f32_e32 v28, 0, v28
	v_lshlrev_b32_e32 v0, 7, v0
	v_mul_f32_e32 v28, v28, v28
	v_and_b32_e32 v0, 0x3b00, v0
	global_store_short v[26:27], v44, off
	v_cvt_pk_bf16_f32 v28, v28, s0
	v_lshl_add_u64 v[44:45], v[66:67], 0, v[0:1]
	global_store_short v[44:45], v28, off
	v_or_b32_e32 v0, v88, v50
	v_max_f32_e32 v28, v29, v29
	v_max_f32_e32 v28, 0, v28
	v_lshlrev_b32_e32 v0, 7, v0
	v_mul_f32_e32 v28, v28, v28
	v_and_b32_e32 v0, 0x3b80, v0
	v_cvt_pk_bf16_f32 v47, v28, s0
	v_lshl_add_u64 v[28:29], v[66:67], 0, v[0:1]
	v_or_b32_e32 v0, v89, v46
	v_max_f32_e32 v30, v30, v30
	v_max_f32_e32 v30, 0, v30
	v_lshlrev_b32_e32 v0, 7, v0
	v_mul_f32_e32 v30, v30, v30
	v_and_b32_e32 v0, 0x3e00, v0
	global_store_short v[28:29], v47, off
	v_cvt_pk_bf16_f32 v30, v30, s0
	v_lshl_add_u64 v[46:47], v[66:67], 0, v[0:1]
	global_store_short v[46:47], v30, off
	v_or_b32_e32 v0, v89, v48
	v_max_f32_e32 v30, v31, v31
	v_max_f32_e32 v30, 0, v30
	v_lshlrev_b32_e32 v0, 7, v0
	v_mfma_f32_32x32x16_bf16 v[2:17], v[92:95], v[100:103], v[2:17]
	v_mul_f32_e32 v30, v30, v30
	v_and_b32_e32 v0, 0x3e80, v0
	v_cvt_pk_bf16_f32 v48, v30, s0
	v_lshl_add_u64 v[30:31], v[66:67], 0, v[0:1]
	v_or_b32_e32 v0, v89, v49
	v_max_f32_e32 v32, v32, v32
	v_max_f32_e32 v32, 0, v32
	v_lshlrev_b32_e32 v0, 7, v0
	v_mul_f32_e32 v32, v32, v32
	v_and_b32_e32 v0, 0x3f00, v0
	global_store_short v[30:31], v48, off
	v_cvt_pk_bf16_f32 v32, v32, s0
	v_lshl_add_u64 v[48:49], v[66:67], 0, v[0:1]
	global_store_short v[48:49], v32, off
	v_or_b32_e32 v0, v89, v50
	v_max_f32_e32 v32, v33, v33
	v_max_f32_e32 v32, 0, v32
	v_lshlrev_b32_e32 v0, 7, v0
	v_mul_f32_e32 v32, v32, v32
	v_and_b32_e32 v0, 0x3f80, v0
	v_cvt_pk_bf16_f32 v50, v32, s0
	v_lshl_add_u64 v[32:33], v[66:67], 0, v[0:1]
	v_max_f32_e32 v0, v2, v2
	v_max_f32_e32 v0, 0, v0
	v_mul_f32_e32 v0, v0, v0
	v_cvt_pk_bf16_f32 v0, v0, s0
	global_store_short v[32:33], v50, off
	global_store_short v[34:35], v0, off offset:64
	v_max_f32_e32 v0, v3, v3
	v_max_f32_e32 v0, 0, v0
	v_mul_f32_e32 v0, v0, v0
	v_cvt_pk_bf16_f32 v0, v0, s0
	global_store_short v[18:19], v0, off offset:64
	v_max_f32_e32 v0, v4, v4
	v_max_f32_e32 v0, 0, v0
	v_mul_f32_e32 v0, v0, v0
	v_cvt_pk_bf16_f32 v0, v0, s0
	global_store_short v[36:37], v0, off offset:64
	v_max_f32_e32 v0, v5, v5
	v_max_f32_e32 v0, 0, v0
	v_mul_f32_e32 v0, v0, v0
	v_cvt_pk_bf16_f32 v0, v0, s0
	global_store_short v[20:21], v0, off offset:64
	v_max_f32_e32 v0, v6, v6
	v_max_f32_e32 v0, 0, v0
	v_mul_f32_e32 v0, v0, v0
	v_cvt_pk_bf16_f32 v0, v0, s0
	global_store_short v[38:39], v0, off offset:64
	v_max_f32_e32 v0, v7, v7
	v_max_f32_e32 v0, 0, v0
	v_mul_f32_e32 v0, v0, v0
	v_cvt_pk_bf16_f32 v0, v0, s0
	global_store_short v[22:23], v0, off offset:64
	v_max_f32_e32 v0, v8, v8
	v_max_f32_e32 v0, 0, v0
	v_mul_f32_e32 v0, v0, v0
	v_cvt_pk_bf16_f32 v0, v0, s0
	global_store_short v[40:41], v0, off offset:64
	v_max_f32_e32 v0, v9, v9
	v_max_f32_e32 v0, 0, v0
	v_mul_f32_e32 v0, v0, v0
	v_cvt_pk_bf16_f32 v0, v0, s0
	global_store_short v[24:25], v0, off offset:64
	v_max_f32_e32 v0, v10, v10
	v_max_f32_e32 v0, 0, v0
	v_mul_f32_e32 v0, v0, v0
	v_cvt_pk_bf16_f32 v0, v0, s0
	global_store_short v[42:43], v0, off offset:64
	v_max_f32_e32 v0, v11, v11
	v_max_f32_e32 v0, 0, v0
	v_mul_f32_e32 v0, v0, v0
	v_cvt_pk_bf16_f32 v0, v0, s0
	global_store_short v[26:27], v0, off offset:64
	v_max_f32_e32 v0, v12, v12
	v_max_f32_e32 v0, 0, v0
	v_mul_f32_e32 v0, v0, v0
	v_cvt_pk_bf16_f32 v0, v0, s0
	global_store_short v[44:45], v0, off offset:64
	v_max_f32_e32 v0, v13, v13
	v_max_f32_e32 v0, 0, v0
	v_mul_f32_e32 v0, v0, v0
	v_cvt_pk_bf16_f32 v0, v0, s0
	global_store_short v[28:29], v0, off offset:64
	v_max_f32_e32 v0, v14, v14
	v_max_f32_e32 v0, 0, v0
	v_mul_f32_e32 v0, v0, v0
	v_cvt_pk_bf16_f32 v0, v0, s0
	global_store_short v[46:47], v0, off offset:64
	v_max_f32_e32 v0, v15, v15
	v_max_f32_e32 v0, 0, v0
	v_mul_f32_e32 v0, v0, v0
	v_cvt_pk_bf16_f32 v0, v0, s0
	global_store_short v[30:31], v0, off offset:64
	v_max_f32_e32 v0, v16, v16
	v_max_f32_e32 v0, 0, v0
	v_mul_f32_e32 v0, v0, v0
	v_cvt_pk_bf16_f32 v0, v0, s0
	global_store_short v[48:49], v0, off offset:64
	v_max_f32_e32 v0, v17, v17
	v_max_f32_e32 v0, 0, v0
	v_mul_f32_e32 v0, v0, v0
	v_cvt_pk_bf16_f32 v0, v0, s0
	s_cmp_lt_i32 s5, s2
	global_store_short v[32:33], v0, off offset:64
	s_cbranch_scc1 .LBB0_1298
	s_mov_b32 s10, 0x8000
	s_mov_b32 s34, 0xa000
	s_mov_b32 s35, 0x2b000
	s_mov_b64 s[42:43], s[8:9]

	.amdhsa_kernel _Z11mega_kernel6Params
		.amdhsa_group_segment_fixed_size 65560
		.amdhsa_private_segment_fixed_size 0
		.amdhsa_kernarg_size 696
		.amdhsa_user_sgpr_count 2
		.amdhsa_user_sgpr_dispatch_ptr 0
		.amdhsa_user_sgpr_queue_ptr 0
		.amdhsa_user_sgpr_kernarg_segment_ptr 1
		.amdhsa_user_sgpr_dispatch_id 0
		.amdhsa_user_sgpr_kernarg_preload_length 0
		.amdhsa_user_sgpr_kernarg_preload_offset 0
		.amdhsa_user_sgpr_private_segment_size 0
		.amdhsa_uses_dynamic_stack 0
		.amdhsa_enable_private_segment 0
		.amdhsa_system_sgpr_workgroup_id_x 1
		.amdhsa_system_sgpr_workgroup_id_y 0
		.amdhsa_system_sgpr_workgroup_id_z 0
		.amdhsa_system_sgpr_workgroup_info 0
		.amdhsa_system_vgpr_workitem_id 2
		.amdhsa_next_free_vgpr 228
		.amdhsa_next_free_sgpr 100
		.amdhsa_accum_offset 228
		.amdhsa_reserve_vcc 1
		.amdhsa_float_round_mode_32 0
		.amdhsa_float_round_mode_16_64 0
		.amdhsa_float_denorm_mode_32 3
		.amdhsa_float_denorm_mode_16_64 3
		.amdhsa_dx10_clamp 1
		.amdhsa_ieee_mode 1
		.amdhsa_fp16_overflow 0
		.amdhsa_tg_split 0
		.amdhsa_exception_fp_ieee_invalid_op 0
		.amdhsa_exception_fp_denorm_src 0
		.amdhsa_exception_fp_ieee_div_zero 0
		.amdhsa_exception_fp_ieee_overflow 0
		.amdhsa_exception_fp_ieee_underflow 0
		.amdhsa_exception_fp_ieee_inexact 0
		.amdhsa_exception_int_div_zero 0
	.end_amdhsa_kernel

amdhsa.kernels:
  - .agpr_count:     0
    .args:
      - .offset:         0
        .size:           440
        .value_kind:     by_value
      - .offset:         440
        .size:           4
        .value_kind:     hidden_block_count_x
      - .offset:         444
        .size:           4
        .value_kind:     hidden_block_count_y
      - .offset:         448
        .size:           4
        .value_kind:     hidden_block_count_z
      - .offset:         452
        .size:           2
        .value_kind:     hidden_group_size_x
      - .offset:         454
        .size:           2
        .value_kind:     hidden_group_size_y
      - .offset:         456
        .size:           2
        .value_kind:     hidden_group_size_z
      - .offset:         458
        .size:           2
        .value_kind:     hidden_remainder_x
      - .offset:         460
        .size:           2
        .value_kind:     hidden_remainder_y
      - .offset:         462
        .size:           2
        .value_kind:     hidden_remainder_z
      - .offset:         480
        .size:           8
        .value_kind:     hidden_global_offset_x
      - .offset:         488
        .size:           8
        .value_kind:     hidden_global_offset_y
      - .offset:         496
        .size:           8
        .value_kind:     hidden_global_offset_z
      - .offset:         504
        .size:           2
        .value_kind:     hidden_grid_dims
      - .offset:         528
        .size:           8
        .value_kind:     hidden_multigrid_sync_arg
    .group_segment_fixed_size: 65560
    .kernarg_segment_align: 8
    .kernarg_segment_size: 696
    .language:       OpenCL C
    .language_version:
      - 2
      - 0
    .max_flat_workgroup_size: 256
    .name:           _Z11mega_kernel6Params
    .private_segment_fixed_size: 0
    .sgpr_count:     106
    .sgpr_spill_count: 289
    .symbol:         _Z11mega_kernel6Params.kd
    .uniform_work_group_size: 1
    .uses_dynamic_stack: false
    .vgpr_count:     228
    .vgpr_spill_count: 0
    .wavefront_size: 64
